# baseline (speedup 1.0000x reference)
; DI int tid_() { int t = threadIdx.x; asm volatile("" : "+v"(t)); return t; }
; DI int bid_() { int b = blockIdx.x; asm volatile("" : "+s"(b)); return b; }
; DI void phase_final_norm(float* x, const float* g, int rows) {
;   const int wid = tid_() >> 6, lane = tid_() & 63;
;   for (int row = bid_() * 8 + wid; row < rows; row += gridDim.x * 8) {
;     float* xr = x + (size_t)row * 1024;
;     float4 v[4]; float ss = 0.f;
; #pragma unroll
;     for (int i = 0; i < 4; ++i) { float4 t = *reinterpret_cast<const float4*>(xr + i * 256 + lane * 4); v[i] = t; ss += t.x * t.x + t.y * t.y + t.z * t.z + t.w * t.w; }
;     ss = wave_sum_l(ss, lane);
;     const float r = rsqrtf(ss * (1.f / 1024.f) + EPS);
; #pragma unroll
;     for (int i = 0; i < 4; ++i) { const float4 gg = *reinterpret_cast<const float4*>(g + i * 256 + lane * 4);
;       float4 o = make_float4(v[i].x * r * gg.x, v[i].y * r * gg.y, v[i].z * r * gg.z, v[i].w * r * gg.w);
;       *reinterpret_cast<float4*>(xr + i * 256 + lane * 4) = o; }
;   }
; }
.LBB0_32:
	v_ashrrev_i32_e32 v1, 31, v0
	v_lshlrev_b64 v[8:9], 12, v[0:1]
	v_lshl_add_u64 v[28:29], v[4:5], 0, v[8:9]
	global_load_dwordx4 v[8:11], v[28:29], off
	global_load_dwordx4 v[12:15], v[28:29], off offset:1024
	global_load_dwordx4 v[16:19], v[28:29], off offset:2048
	global_load_dwordx4 v[20:23], v[28:29], off offset:3072
	v_add_u32_e32 v0, s99, v0
	s_mov_b32 s2, 0xbfff
	s_waitcnt vmcnt(3)
	v_mov_b32_e32 v32, v9
	s_waitcnt vmcnt(2)
	v_mov_b32_e32 v33, v13
	v_mov_b32_e32 v30, v8
	v_mov_b32_e32 v31, v12
	s_waitcnt vmcnt(1)
	v_mov_b32_e32 v40, v17
	s_waitcnt vmcnt(0)
	v_mov_b32_e32 v41, v21
	v_pk_mul_f32 v[32:33], v[32:33], v[32:33]
	v_mov_b32_e32 v34, v10
	v_mov_b32_e32 v35, v14
	v_mov_b32_e32 v38, v16
	v_mov_b32_e32 v39, v20
	v_pk_mul_f32 v[40:41], v[40:41], v[40:41]
	v_pk_fma_f32 v[30:31], v[30:31], v[30:31], v[32:33]
	v_mov_b32_e32 v36, v11
	v_mov_b32_e32 v37, v15
	v_mov_b32_e32 v42, v18
	v_mov_b32_e32 v43, v22
	v_pk_fma_f32 v[32:33], v[38:39], v[38:39], v[40:41]
	v_pk_fma_f32 v[30:31], v[34:35], v[34:35], v[30:31]
	v_mov_b32_e32 v44, v19
	v_mov_b32_e32 v45, v23
	v_pk_fma_f32 v[32:33], v[42:43], v[42:43], v[32:33]
	v_pk_fma_f32 v[30:31], v[36:37], v[36:37], v[30:31]
	v_pk_fma_f32 v[32:33], v[44:45], v[44:45], v[32:33]
	v_add_f32_e32 v1, v30, v31
	v_add_f32_e32 v1, v1, v32
	v_add_f32_e32 v1, v1, v33
	s_nop 1
	v_add_f32_dpp v1, v1, v1 quad_perm:[1,0,3,2] row_mask:0xf bank_mask:0xf bound_ctrl:1
	s_nop 1
	v_add_f32_dpp v1, v1, v1 quad_perm:[2,3,0,1] row_mask:0xf bank_mask:0xf bound_ctrl:1
	s_nop 1
	v_add_f32_dpp v1, v1, v1 row_half_mirror row_mask:0xf bank_mask:0xf bound_ctrl:1
	s_nop 1
	v_add_f32_dpp v1, v1, v1 row_mirror row_mask:0xf bank_mask:0xf bound_ctrl:1
	ds_bpermute_b32 v30, v6, v1
	s_waitcnt lgkmcnt(0)
	v_add_f32_e32 v1, v1, v30
	ds_bpermute_b32 v30, v7, v1
	s_waitcnt lgkmcnt(0)
	v_add_f32_e32 v1, v1, v30
	v_fmamk_f32 v1, v1, 0x3a800000, v233
	v_mul_f32_e32 v30, 0x4b800000, v1
	v_cmp_gt_f32_e32 vcc, s94, v1
	s_nop 1
	v_cndmask_b32_e32 v1, v1, v30, vcc
	v_rsq_f32_e32 v1, v1
	s_nop 0
	v_mul_f32_e32 v30, 0x45800000, v1
	v_cndmask_b32_e32 v30, v1, v30, vcc
	v_pk_mul_f32 v[8:9], v[8:9], v[30:31] op_sel_hi:[1,0]
	v_pk_mul_f32 v[10:11], v[10:11], v[30:31] op_sel_hi:[1,0]
	v_pk_mul_f32 v[8:9], v[48:49], v[8:9]
	v_pk_mul_f32 v[10:11], v[50:51], v[10:11]
	global_store_dwordx4 v[28:29], v[8:11], off sc1
	v_pk_mul_f32 v[12:13], v[12:13], v[30:31] op_sel_hi:[1,0]
	v_pk_mul_f32 v[14:15], v[14:15], v[30:31] op_sel_hi:[1,0]
	v_cmp_lt_i32_e32 vcc, s2, v0
	s_or_b64 s[36:37], vcc, s[36:37]
	v_pk_mul_f32 v[12:13], v[52:53], v[12:13]
	v_pk_mul_f32 v[14:15], v[54:55], v[14:15]
	global_store_dwordx4 v[28:29], v[12:15], off offset:1024 sc1
	v_pk_mul_f32 v[16:17], v[16:17], v[30:31] op_sel_hi:[1,0]
	v_pk_mul_f32 v[18:19], v[18:19], v[30:31] op_sel_hi:[1,0]
	v_pk_mul_f32 v[16:17], v[16:17], v[56:57]
	v_pk_mul_f32 v[18:19], v[18:19], v[58:59]
	global_store_dwordx4 v[28:29], v[16:19], off offset:2048 sc1
	v_pk_mul_f32 v[20:21], v[20:21], v[30:31] op_sel_hi:[1,0]
	v_pk_mul_f32 v[22:23], v[22:23], v[30:31] op_sel_hi:[1,0]
	v_pk_mul_f32 v[20:21], v[20:21], v[60:61]
	v_pk_mul_f32 v[22:23], v[22:23], v[62:63]
	global_store_dwordx4 v[28:29], v[20:23], off offset:3072 sc1
	s_andn2_b64 exec, exec, s[36:37]
	s_cbranch_execnz .LBB0_32

; DI bf16x8 pack8(const float* a) { u32x4 w = {cvtpk(a[0], a[1]), cvtpk(a[2], a[3]), cvtpk(a[4], a[5]), cvtpk(a[6], a[7])}; return *reinterpret_cast<bf16x8*>(&w); }
; DI int tid_() { int t = threadIdx.x; asm volatile("" : "+v"(t)); return t; }
; DI int bid_() { int b = blockIdx.x; asm volatile("" : "+s"(b)); return b; }
; DI void phase_norm(const float* x, const float* g, u16* out) {
;   const int wid = tid_() >> 6, lane = tid_() & 63;
;   for (int row = bid_() * 8 + wid; row < TG; row += gridDim.x * 8) {
;     const float* xr = x + (size_t)row * 1024;
;     float4 v[4]; float ss = 0.f;
; #pragma unroll
;     for (int i = 0; i < 2; ++i) for (int h = 0; h < 2; ++h) { float4 t = *reinterpret_cast<const float4*>(xr + i * 512 + lane * 8 + h * 4); v[2 * i + h] = t;
;       ss += t.x * t.x + t.y * t.y + t.z * t.z + t.w * t.w; }
;     ss = wave_sum_l(ss, lane);
;     const float r = rsqrtf(ss * (1.f / 1024.f) + EPS);
; #pragma unroll
;     for (int i = 0; i < 2; ++i) { const float4 g0 = *reinterpret_cast<const float4*>(g + i * 512 + lane * 8), g1 = *reinterpret_cast<const float4*>(g + i * 512 + lane * 8 + 4);
;       float a[8] = {v[2 * i].x * r * g0.x, v[2 * i].y * r * g0.y, v[2 * i].z * r * g0.z, v[2 * i].w * r * g0.w,
;                     v[2 * i + 1].x * r * g1.x, v[2 * i + 1].y * r * g1.y, v[2 * i + 1].z * r * g1.z, v[2 * i + 1].w * r * g1.w};
;       *reinterpret_cast<bf16x8*>(out + (size_t)row * 1024 + i * 512 + lane * 8) = pack8(a); }
;   }
; }
.LBB0_46:
	v_ashrrev_i32_e32 v21, 31, v20
	v_lshlrev_b64 v[0:1], 12, v[20:21]
	v_lshl_add_u64 v[12:13], v[22:23], 0, v[0:1]
	global_load_dwordx4 v[4:7], v[12:13], off offset:16
	global_load_dwordx4 v[8:11], v[12:13], off
	s_waitcnt vmcnt(1)
	v_pk_mul_f32 v[16:17], v[4:5], v[4:5]
	s_waitcnt vmcnt(0)
	v_pk_mul_f32 v[14:15], v[8:9], v[8:9]
	v_pk_mul_f32 v[0:1], v[10:11], v[10:11]
	v_pk_mul_f32 v[2:3], v[6:7], v[6:7]
	v_mov_b32_e32 v18, v14
	v_mov_b32_e32 v19, v16
	v_mov_b32_e32 v16, v15
	v_pk_add_f32 v[14:15], v[18:19], v[16:17]
	v_mov_b32_e32 v16, v0
	v_mov_b32_e32 v17, v2
	v_pk_add_f32 v[14:15], v[14:15], v[16:17]
	v_mov_b32_e32 v2, v1
	v_pk_add_f32 v[16:17], v[14:15], v[2:3]
	global_load_dwordx4 v[0:3], v[12:13], off offset:2064
	s_nop 0
	global_load_dwordx4 v[12:15], v[12:13], off offset:2048
	v_add_f32_e32 v16, v16, v17
	s_waitcnt vmcnt(1)
	v_pk_mul_f32 v[34:35], v[0:1], v[0:1]
	s_waitcnt vmcnt(0)
	v_pk_mul_f32 v[32:33], v[12:13], v[12:13]
	v_pk_mul_f32 v[18:19], v[14:15], v[14:15]
	v_pk_mul_f32 v[28:29], v[2:3], v[2:3]
	v_mov_b32_e32 v36, v32
	v_mov_b32_e32 v37, v34
	v_mov_b32_e32 v34, v33
	v_pk_add_f32 v[32:33], v[36:37], v[34:35]
	v_mov_b32_e32 v34, v18
	v_mov_b32_e32 v35, v28
	v_pk_add_f32 v[32:33], v[32:33], v[34:35]
	v_mov_b32_e32 v28, v19
	v_pk_add_f32 v[18:19], v[32:33], v[28:29]
	s_nop 0
	v_add_f32_e32 v16, v16, v18
	v_add_f32_e32 v16, v16, v19
	s_nop 1
	v_add_f32_dpp v16, v16, v16 quad_perm:[1,0,3,2] row_mask:0xf bank_mask:0xf bound_ctrl:1
	s_nop 1
	v_add_f32_dpp v16, v16, v16 quad_perm:[2,3,0,1] row_mask:0xf bank_mask:0xf bound_ctrl:1
	s_nop 1
	v_add_f32_dpp v16, v16, v16 row_half_mirror row_mask:0xf bank_mask:0xf bound_ctrl:1
	s_nop 1
	v_add_f32_dpp v16, v16, v16 row_mirror row_mask:0xf bank_mask:0xf bound_ctrl:1
	ds_bpermute_b32 v17, v30, v16
	s_waitcnt lgkmcnt(0)
	v_add_f32_e32 v16, v16, v17
	ds_bpermute_b32 v17, v31, v16
	s_waitcnt lgkmcnt(0)
	v_add_f32_e32 v16, v16, v17
	v_fmamk_f32 v16, v16, 0x3a800000, v233
	v_cmp_gt_f32_e32 vcc, s94, v16
	v_mul_f32_e32 v17, 0x4b800000, v16
	s_nop 0
	v_cndmask_b32_e32 v16, v16, v17, vcc
	v_rsq_f32_e32 v16, v16
	s_nop 0
	v_mul_f32_e32 v17, 0x45800000, v16
	v_cndmask_b32_e32 v36, v16, v17, vcc
	v_lshlrev_b64 v[16:17], 11, v[20:21]
	v_lshl_add_u64 v[28:29], v[26:27], 0, v[16:17]
	global_load_dwordx4 v[16:19], v[24:25], off offset:16
	global_load_dwordx4 v[32:35], v[24:25], off
	v_mul_f32_e32 v4, v4, v36
	v_mul_f32_e32 v8, v8, v36
	v_mul_f32_e32 v9, v9, v36
	v_mul_f32_e32 v10, v10, v36
	v_mul_f32_e32 v11, v11, v36
	v_mul_f32_e32 v0, v0, v36
	v_mul_f32_e32 v12, v12, v36
	v_add_u32_e32 v20, s99, v20
	v_cmp_lt_i32_e32 vcc, s78, v20
	s_or_b64 s[40:41], vcc, s[40:41]
	s_waitcnt vmcnt(1)
	v_mul_f32_e32 v16, v16, v4
	v_mul_f32_e32 v4, v5, v36
	v_mul_f32_e32 v17, v17, v4
	v_mul_f32_e32 v4, v6, v36
	v_mul_f32_e32 v18, v18, v4
	v_mul_f32_e32 v4, v7, v36
	v_mul_f32_e32 v7, v19, v4
	s_waitcnt vmcnt(0)
	v_mul_f32_e32 v8, v32, v8
	v_mul_f32_e32 v9, v33, v9
	v_mul_f32_e32 v10, v34, v10
	v_mul_f32_e32 v11, v35, v11
	v_cvt_pk_bf16_f32 v4, v8, v9
	v_cvt_pk_bf16_f32 v5, v10, v11
	v_cvt_pk_bf16_f32 v6, v16, v17
	v_cvt_pk_bf16_f32 v7, v18, v7
	global_store_dwordx4 v[28:29], v[4:7], off sc1
	global_load_dwordx4 v[4:7], v[24:25], off offset:2064
	s_nop 0
	global_load_dwordx4 v[8:11], v[24:25], off offset:2048
	s_waitcnt vmcnt(1)
	v_mul_f32_e32 v4, v0, v4
	v_mul_f32_e32 v0, v1, v36
	s_waitcnt vmcnt(0)
	v_mul_f32_e32 v8, v12, v8
	v_mul_f32_e32 v12, v13, v36
	v_mul_f32_e32 v5, v0, v5
	v_mul_f32_e32 v0, v2, v36
	v_mul_f32_e32 v9, v12, v9
	v_mul_f32_e32 v12, v14, v36
	v_mul_f32_e32 v6, v0, v6
	v_mul_f32_e32 v0, v3, v36
	v_mul_f32_e32 v10, v12, v10
	v_mul_f32_e32 v12, v15, v36
	v_mul_f32_e32 v3, v0, v7
	v_mul_f32_e32 v11, v12, v11
	v_cvt_pk_bf16_f32 v0, v8, v9
	v_cvt_pk_bf16_f32 v1, v10, v11
	v_cvt_pk_bf16_f32 v2, v4, v5
	v_cvt_pk_bf16_f32 v3, v6, v3
	global_store_dwordx4 v[28:29], v[0:3], off offset:1024 sc1
	s_andn2_b64 exec, exec, s[40:41]
	s_cbranch_execnz .LBB0_46

; DI uint2 pack4(float a, float b, float c, float d) { return make_uint2(cvtpk(a, b), cvtpk(c, d)); }
; template <int MODE>
; DI void hgrn_item2(const u16* PROJ, int tokbase, int dir, int h, int layer, const float* hgrn_lb, float* Sg, float* Pg,
;                    u16* OH, const float* norm_g, char* lds) {
;     ...
;     if (MODE == 1) {
;       const int t = tb2 * 32 + r32, p_ = c * 64 + t; const int tok = tokbase + (dir ? 511 - p_ : p_);
;       u16* op = OH + (size_t)tok * 1024 + h * 128 + vb * 32 + 4 * hi;
;       if (dir == 0) {
; #pragma unroll
;         for (int q4 = 0; q4 < 4; ++q4) *reinterpret_cast<uint2*>(op + 8 * q4) = pack4(oa[4 * q4], oa[4 * q4 + 1], oa[4 * q4 + 2], oa[4 * q4 + 3]);
;         __syncthreads();
;       } else {
;         float ss = 0.f;
; #pragma unroll
;         for (int q4 = 0; q4 < 4; ++q4) { const uint2 t8 = pf_t[q4];
;           oa[4 * q4] += __uint_as_float(t8.x << 16); oa[4 * q4 + 1] += __uint_as_float(t8.x & 0xffff0000u);
;           oa[4 * q4 + 2] += __uint_as_float(t8.y << 16); oa[4 * q4 + 3] += __uint_as_float(t8.y & 0xffff0000u);
;           ss += oa[4 * q4] * oa[4 * q4] + oa[4 * q4 + 1] * oa[4 * q4 + 1] + oa[4 * q4 + 2] * oa[4 * q4 + 2] + oa[4 * q4 + 3] * oa[4 * q4 + 3]; }
;         ss += __int_as_float(__builtin_amdgcn_ds_bpermute((lane ^ 32) << 2, __float_as_int(ss)));
;         if (hi == 0) reinterpret_cast<float*>(lds + HL_SS)[vb * 64 + t] = ss;
;         __syncthreads();
;         const float* ssp = reinterpret_cast<const float*>(lds + HL_SS) + t;
;         const float rn = rsqrtf((ssp[0] + ssp[64] + ssp[128] + ssp[192]) * (1.f / 128.f) + EPS);
; #pragma unroll
;         for (int q4 = 0; q4 < 4; ++q4) { const int cv = h * 128 + vb * 32 + 4 * hi + 8 * q4;
;           const uint2 hg = pf_g[q4]; const float4 ng = *reinterpret_cast<const float4*>(norm_g + cv);
;           const float h0 = __uint_as_float(hg.x << 16), h1 = __uint_as_float(hg.x & 0xffff0000u), h2 = __uint_as_float(hg.y << 16), h3 = __uint_as_float(hg.y & 0xffff0000u);
;           *reinterpret_cast<uint2*>(op + 8 * q4) = pack4(oa[4 * q4] * rn * ng.x * (h0 * sigm(h0)), oa[4 * q4 + 1] * rn * ng.y * (h1 * sigm(h1)),
;                                                          oa[4 * q4 + 2] * rn * ng.z * (h2 * sigm(h2)), oa[4 * q4 + 3] * rn * ng.w * (h3 * sigm(h3))); }
;       }
.LBB0_78:
	s_or_b64 exec, exec, s[6:7]
	s_waitcnt lgkmcnt(0)
	s_barrier
	ds_read2st64_b32 v[190:191], v131 offset1:1
	s_waitcnt vmcnt(3)
	v_lshlrev_b32_e32 v194, 16, v114
	v_and_b32_e32 v195, 0xffff0000, v114
	v_lshlrev_b32_e32 v196, 16, v115
	v_and_b32_e32 v197, 0xffff0000, v115
	s_waitcnt lgkmcnt(0)
	v_add_f32_e32 v175, v190, v191
	ds_read2st64_b32 v[190:191], v131 offset0:2 offset1:3
	s_mov_b64 s[6:7], 0
	s_waitcnt lgkmcnt(0)
	v_add_f32_e32 v175, v175, v190
	v_add_f32_e32 v175, v175, v191
	v_fmamk_f32 v175, v175, 0x3c000000, v233
	v_cmp_gt_f32_e32 vcc, s91, v175
	v_mul_f32_e32 v190, 0x4b800000, v175
	s_nop 0
	v_cndmask_b32_e32 v175, v175, v190, vcc
	v_rsq_f32_e32 v175, v175
	s_nop 0
	v_mul_f32_e32 v190, 0x45800000, v175
	v_cndmask_b32_e32 v175, v175, v190, vcc
	v_mul_f32_e32 v189, v189, v175
	v_mul_f32_e32 v188, v188, v175
	v_mul_f32_e32 v187, v187, v175
	v_mul_f32_e32 v186, v186, v175
	v_mul_f32_e32 v185, v185, v175
	v_mul_f32_e32 v184, v184, v175
	v_mul_f32_e32 v183, v183, v175
	v_mul_f32_e32 v182, v182, v175
	v_mul_f32_e32 v181, v181, v175
	v_mul_f32_e32 v180, v180, v175
	v_mul_f32_e32 v179, v179, v175
	v_mul_f32_e32 v178, v178, v175
	v_mul_f32_e32 v177, v177, v175
	v_mul_f32_e32 v176, v176, v175
	v_mul_f32_e32 v174, v174, v175
	v_mul_f32_e32 v173, v173, v175
	s_waitcnt vmcnt(0)
	v_mul_f32_e32 v189, v198, v189
	v_mul_f32_e32 v190, 0xbfb8aa3b, v194
	v_exp_f32_e32 v190, v190
	v_mul_f32_e32 v188, v199, v188
	v_mul_f32_e32 v187, v200, v187
	v_mul_f32_e32 v186, v201, v186
	v_add_f32_e32 v190, 1.0, v190
	v_rcp_f32_e32 v190, v190
	v_and_b32_e32 v191, 0xffff0000, v112
	v_lshlrev_b32_e32 v192, 16, v113
	v_and_b32_e32 v193, 0xffff0000, v113
	v_mul_f32_e32 v190, v190, v194
	v_mul_f32_e32 v189, v190, v189
	v_mul_f32_e32 v190, 0xbfb8aa3b, v195
	v_exp_f32_e32 v190, v190
	s_nop 0
	v_add_f32_e32 v190, 1.0, v190
	v_rcp_f32_e32 v190, v190
	s_nop 0
	v_mul_f32_e32 v190, v190, v195
	v_mul_f32_e32 v188, v190, v188
	v_mul_f32_e32 v190, 0xbfb8aa3b, v196
	v_exp_f32_e32 v190, v190
	s_nop 0
	v_add_f32_e32 v190, 1.0, v190
	v_rcp_f32_e32 v190, v190
	s_nop 0
	v_mul_f32_e32 v190, v190, v196
	v_mul_f32_e32 v187, v190, v187
	v_mul_f32_e32 v190, 0xbfb8aa3b, v197
	v_exp_f32_e32 v190, v190
	s_nop 0
	v_add_f32_e32 v190, 1.0, v190
	v_rcp_f32_e32 v190, v190
	s_nop 0
	v_mul_f32_e32 v190, v190, v197
	v_mul_f32_e32 v190, v190, v186
	v_cvt_pk_bf16_f32 v186, v189, v188
	v_cvt_pk_bf16_f32 v187, v187, v190
	global_store_dwordx2 v[116:117], v[186:187], off sc1
	v_lshlrev_b32_e32 v190, 16, v112
	v_mul_f32_e32 v185, v185, v202
	v_mul_f32_e32 v186, 0xbfb8aa3b, v190
	v_exp_f32_e32 v186, v186
	v_mul_f32_e32 v184, v184, v203
	v_mul_f32_e32 v183, v183, v204
	v_mul_f32_e32 v182, v182, v205
	v_add_f32_e32 v186, 1.0, v186
	v_rcp_f32_e32 v186, v186
	v_and_b32_e32 v187, 0xffff0000, v110
	v_lshlrev_b32_e32 v188, 16, v111
	v_and_b32_e32 v189, 0xffff0000, v111
	v_mul_f32_e32 v186, v186, v190
	v_mul_f32_e32 v185, v186, v185
	v_mul_f32_e32 v186, 0xbfb8aa3b, v191
	v_exp_f32_e32 v186, v186
	s_nop 0
	v_add_f32_e32 v186, 1.0, v186
	v_rcp_f32_e32 v186, v186
	s_nop 0
	v_mul_f32_e32 v186, v186, v191
	v_mul_f32_e32 v184, v186, v184
	v_mul_f32_e32 v186, 0xbfb8aa3b, v192
	v_exp_f32_e32 v186, v186
	s_nop 0
	v_add_f32_e32 v186, 1.0, v186
	v_rcp_f32_e32 v186, v186
	s_nop 0
	v_mul_f32_e32 v186, v186, v192
	v_mul_f32_e32 v183, v186, v183
	v_mul_f32_e32 v186, 0xbfb8aa3b, v193
	v_exp_f32_e32 v186, v186
	s_nop 0
	v_add_f32_e32 v186, 1.0, v186
	v_rcp_f32_e32 v186, v186
	s_nop 0
	v_mul_f32_e32 v186, v186, v193
	v_mul_f32_e32 v186, v186, v182
	v_cvt_pk_bf16_f32 v182, v185, v184
	v_cvt_pk_bf16_f32 v183, v183, v186
	global_store_dwordx2 v[116:117], v[182:183], off offset:16 sc1
	v_lshlrev_b32_e32 v186, 16, v110
	v_mul_f32_e32 v181, v181, v206
	v_mul_f32_e32 v182, 0xbfb8aa3b, v186
	v_exp_f32_e32 v182, v182
	v_mul_f32_e32 v180, v180, v207
	v_mul_f32_e32 v179, v179, v208
	v_mul_f32_e32 v178, v178, v209
	v_add_f32_e32 v182, 1.0, v182
	v_rcp_f32_e32 v182, v182
	v_and_b32_e32 v183, 0xffff0000, v108
	v_lshlrev_b32_e32 v184, 16, v109
	v_and_b32_e32 v185, 0xffff0000, v109
	v_mul_f32_e32 v182, v182, v186
	v_mul_f32_e32 v181, v182, v181
	v_mul_f32_e32 v182, 0xbfb8aa3b, v187
	v_exp_f32_e32 v182, v182
	s_nop 0
	v_add_f32_e32 v182, 1.0, v182
	v_rcp_f32_e32 v182, v182
	s_nop 0
	v_mul_f32_e32 v182, v182, v187
	v_mul_f32_e32 v180, v182, v180
	v_mul_f32_e32 v182, 0xbfb8aa3b, v188
	v_exp_f32_e32 v182, v182
	s_nop 0
	v_add_f32_e32 v182, 1.0, v182
	v_rcp_f32_e32 v182, v182
	s_nop 0
	v_mul_f32_e32 v182, v182, v188
	v_mul_f32_e32 v179, v182, v179
	v_mul_f32_e32 v182, 0xbfb8aa3b, v189
	v_exp_f32_e32 v182, v182
	s_nop 0
	v_add_f32_e32 v182, 1.0, v182
	v_rcp_f32_e32 v182, v182
	s_nop 0
	v_mul_f32_e32 v182, v182, v189
	v_mul_f32_e32 v182, v182, v178
	v_cvt_pk_bf16_f32 v178, v181, v180
	v_cvt_pk_bf16_f32 v179, v179, v182
	global_store_dwordx2 v[116:117], v[178:179], off offset:32 sc1
	v_lshlrev_b32_e32 v182, 16, v108
	v_mul_f32_e32 v177, v177, v210
	v_mul_f32_e32 v178, 0xbfb8aa3b, v182
	v_exp_f32_e32 v178, v178
	v_mul_f32_e32 v176, v176, v211
	v_mul_f32_e32 v174, v174, v212
	v_mul_f32_e32 v173, v173, v213
	v_add_f32_e32 v178, 1.0, v178
	v_rcp_f32_e32 v178, v178
	s_nop 0
	v_mul_f32_e32 v178, v178, v182
	v_mul_f32_e32 v177, v178, v177
	v_mul_f32_e32 v178, 0xbfb8aa3b, v183
	v_exp_f32_e32 v178, v178
	s_nop 0
	v_add_f32_e32 v178, 1.0, v178
	v_rcp_f32_e32 v178, v178
	s_nop 0
	v_mul_f32_e32 v178, v178, v183
	v_mul_f32_e32 v176, v178, v176
	v_mul_f32_e32 v178, 0xbfb8aa3b, v184
	v_exp_f32_e32 v178, v178
	s_nop 0
	v_add_f32_e32 v178, 1.0, v178
	v_rcp_f32_e32 v178, v178
	s_nop 0
	v_mul_f32_e32 v178, v178, v184
	v_mul_f32_e32 v178, v178, v174
	v_mul_f32_e32 v174, 0xbfb8aa3b, v185
	v_exp_f32_e32 v174, v174
	s_nop 0
	v_add_f32_e32 v174, 1.0, v174
	v_rcp_f32_e32 v174, v174
	s_nop 0
	v_mul_f32_e32 v174, v174, v185
	v_mul_f32_e32 v173, v174, v173
	v_cvt_pk_bf16_f32 v174, v177, v176
	v_cvt_pk_bf16_f32 v175, v178, v173
	global_store_dwordx2 v[116:117], v[174:175], off offset:48 sc1
.LBB0_79:
	s_and_b64 vcc, exec, s[6:7]
	s_cbranch_vccz .LBB0_66
	v_cvt_pk_bf16_f32 v32, v32, v33
	v_cvt_pk_bf16_f32 v33, v34, v35
	s_nop 8
	global_store_dwordx2 v[116:117], v[32:33], off sc1
	v_cvt_pk_bf16_f32 v32, v36, v37
	v_cvt_pk_bf16_f32 v33, v38, v39
	global_store_dwordx2 v[116:117], v[32:33], off offset:16 sc1
	v_cvt_pk_bf16_f32 v32, v40, v41
	v_cvt_pk_bf16_f32 v33, v42, v43
	global_store_dwordx2 v[116:117], v[32:33], off offset:32 sc1
	v_cvt_pk_bf16_f32 v32, v44, v45
	v_cvt_pk_bf16_f32 v33, v46, v47
	global_store_dwordx2 v[116:117], v[32:33], off offset:48 sc1
	s_waitcnt lgkmcnt(0)
	s_barrier
	s_branch .LBB0_66

; DI void phase_hg2(const Params& p, int L) {
;     ...
;     for (int j0 = 0; j0 < nsc; j0 += 8) {
;       float tmp[8], pv[8];
; #pragma unroll
;       for (int u = 0; u < 8; ++u) { tmp[u] = sp[u * s_st]; pv[u] = pp[u * s_pv]; }
; #pragma unroll
;       for (int u = 0; u < 8; ++u) { sp[u * s_st] = carry; carry = pv[u] * carry + tmp[u]; }
;       sp += 8 * s_st; pp += 8 * s_pv;
;     }
.LBB0_90:
	v_lshl_add_u64 v[28:29], s[26:27], 0, v[2:3]
	v_lshl_add_u64 v[30:31], s[26:27], 0, v[6:7]
	global_load_dword v27, v[30:31], off
	global_load_dword v46, v[28:29], off
	v_lshl_add_u64 v[32:33], s[26:27], 0, v[22:23]
	v_lshl_add_u64 v[28:29], v[28:29], 0, v[0:1]
	global_load_dword v47, v[32:33], off
	global_load_dword v48, v[28:29], off
	v_lshl_add_u64 v[34:35], s[26:27], 0, v[10:11]
	v_lshl_add_u64 v[28:29], v[28:29], 0, v[0:1]
	global_load_dword v49, v[34:35], off
	global_load_dword v50, v[28:29], off
	v_lshl_add_u64 v[36:37], s[26:27], 0, v[12:13]
	v_lshl_add_u64 v[28:29], v[28:29], 0, v[0:1]
	global_load_dword v51, v[36:37], off
	global_load_dword v52, v[28:29], off
	v_lshl_add_u64 v[38:39], s[26:27], 0, v[14:15]
	v_lshl_add_u64 v[28:29], v[28:29], 0, v[0:1]
	global_load_dword v53, v[38:39], off
	global_load_dword v54, v[28:29], off
	v_lshl_add_u64 v[40:41], s[26:27], 0, v[16:17]
	v_lshl_add_u64 v[28:29], v[28:29], 0, v[0:1]
	global_load_dword v55, v[40:41], off
	global_load_dword v56, v[28:29], off
	v_lshl_add_u64 v[42:43], s[26:27], 0, v[18:19]
	v_lshl_add_u64 v[28:29], v[28:29], 0, v[0:1]
	global_load_dword v57, v[42:43], off
	global_load_dword v58, v[28:29], off
	v_lshl_add_u64 v[44:45], s[26:27], 0, v[20:21]
	v_lshl_add_u64 v[28:29], v[28:29], 0, v[0:1]
	global_load_dword v59, v[44:45], off
	s_add_i32 s40, s40, 8
	global_load_dword v28, v[28:29], off
	v_lshl_add_u64 v[2:3], v[2:3], 0, v[4:5]
	global_store_dword v[30:31], v26, off sc1
	v_lshl_add_u64 v[6:7], v[6:7], 0, v[8:9]
	v_lshl_add_u64 v[10:11], v[10:11], 0, v[8:9]
	v_lshl_add_u64 v[12:13], v[12:13], 0, v[8:9]
	v_lshl_add_u64 v[14:15], v[14:15], 0, v[8:9]
	v_lshl_add_u64 v[16:17], v[16:17], 0, v[8:9]
	v_lshl_add_u64 v[18:19], v[18:19], 0, v[8:9]
	v_lshl_add_u64 v[20:21], v[20:21], 0, v[8:9]
	v_lshl_add_u64 v[22:23], v[22:23], 0, v[8:9]
	s_cmp_lt_u32 s40, s7
	s_waitcnt vmcnt(15)
	v_fmac_f32_e32 v27, v26, v46
	global_store_dword v[32:33], v27, off sc1
	s_waitcnt vmcnt(14)
	v_fmac_f32_e32 v47, v27, v48
	global_store_dword v[34:35], v47, off sc1
	s_waitcnt vmcnt(13)
	v_fmac_f32_e32 v49, v47, v50
	global_store_dword v[36:37], v49, off sc1
	s_waitcnt vmcnt(12)
	v_fmac_f32_e32 v51, v49, v52
	global_store_dword v[38:39], v51, off sc1
	s_waitcnt vmcnt(11)
	v_fmac_f32_e32 v53, v51, v54
	global_store_dword v[40:41], v53, off sc1
	s_waitcnt vmcnt(10)
	v_fmac_f32_e32 v55, v53, v56
	global_store_dword v[42:43], v55, off sc1
	s_waitcnt vmcnt(9)
	v_fmac_f32_e32 v57, v55, v58
	global_store_dword v[44:45], v57, off sc1
	s_waitcnt vmcnt(8)
	v_fmac_f32_e32 v59, v57, v28
	v_mov_b32_e32 v26, v59
	s_cbranch_scc1 .LBB0_90
	v_add_u32_e32 v24, s58, v24
	v_cmp_le_i32_e32 vcc, s6, v24
	s_or_b64 s[38:39], vcc, s[38:39]
	v_add_u16_e32 v25, s58, v25
	s_andn2_b64 exec, exec, s[38:39]
	s_cbranch_execnz .LBB0_89

; DI int crow(int r, int hi) { return (r & 3) + 8 * (r >> 2) + 4 * hi; }
; template <int MODE>
; DI void hgrn_item2(const u16* PROJ, int tokbase, int dir, int h, int layer, const float* hgrn_lb, float* Sg, float* Pg,
;                    u16* OH, const float* norm_g, char* lds) {
;     ...
;   if (MODE == 0) {
; #pragma unroll
;     for (int e = 0; e < 2; ++e) {
; #pragma unroll
;       for (int i = 0; i < 16; ++i) Sg[(kb * 32 + crow(i, hi)) * 128 + (vbs + e) * 32 + r32] = S[e][i]; }
;     if (part == 0) Pg[bk] = __builtin_amdgcn_exp2f(logP);
;   }
.LBB0_112:
	s_lshl_b64 s[38:39], s[50:51], 16
	v_readlane_b32 s2, v253, 18
	s_waitcnt vmcnt(3)
	v_lshl_or_b32 v32, v57, 9, v60
	s_add_u32 s38, s2, s38
	v_readlane_b32 s2, v253, 19
	v_or3_b32 v32, v32, v56, v65
	s_addc_u32 s39, s2, s39
	v_ashrrev_i32_e32 v33, 31, v32
	v_lshl_add_u64 v[32:33], v[32:33], 2, s[38:39]
	s_movk_i32 s2, 0x1000
	global_store_dword v[32:33], v16, off sc1
	global_store_dword v[32:33], v17, off offset:512 sc1
	global_store_dword v[32:33], v18, off offset:1024 sc1
	global_store_dword v[32:33], v19, off offset:1536 sc1
	v_add_co_u32_e32 v16, vcc, s2, v32
	s_movk_i32 s2, 0x2000
	s_nop 0
	v_addc_co_u32_e32 v17, vcc, 0, v33, vcc
	v_add_co_u32_e32 v18, vcc, s2, v32
	s_movk_i32 s2, 0x3000
	s_nop 0
	v_addc_co_u32_e32 v19, vcc, 0, v33, vcc
	global_store_dword v[18:19], v20, off offset:-4096 sc1
	global_store_dword v[16:17], v21, off offset:512 sc1
	global_store_dword v[16:17], v22, off offset:1024 sc1
	global_store_dword v[16:17], v23, off offset:1536 sc1
	global_store_dword v[18:19], v24, off sc1
	global_store_dword v[18:19], v25, off offset:512 sc1
	global_store_dword v[18:19], v26, off offset:1024 sc1
	global_store_dword v[18:19], v27, off offset:1536 sc1
	v_add_co_u32_e32 v20, vcc, s2, v32
	s_nop 1
	v_addc_co_u32_e32 v21, vcc, 0, v33, vcc
	global_store_dword v[20:21], v28, off sc1
	global_store_dword v[20:21], v29, off offset:512 sc1
	global_store_dword v[20:21], v30, off offset:1024 sc1
	global_store_dword v[20:21], v31, off offset:1536 sc1
	global_store_dword v[32:33], v0, off offset:128 sc1
	global_store_dword v[32:33], v1, off offset:640 sc1
	global_store_dword v[32:33], v2, off offset:1152 sc1
	global_store_dword v[32:33], v3, off offset:1664 sc1
	global_store_dword v[16:17], v4, off offset:128 sc1
	global_store_dword v[16:17], v5, off offset:640 sc1
	global_store_dword v[16:17], v6, off offset:1152 sc1
	global_store_dword v[16:17], v7, off offset:1664 sc1
	global_store_dword v[18:19], v8, off offset:128 sc1
	global_store_dword v[18:19], v9, off offset:640 sc1
	global_store_dword v[18:19], v10, off offset:1152 sc1
	global_store_dword v[18:19], v11, off offset:1664 sc1
	global_store_dword v[20:21], v12, off offset:128 sc1
	global_store_dword v[20:21], v13, off offset:640 sc1
	global_store_dword v[20:21], v14, off offset:1152 sc1
	global_store_dword v[20:21], v15, off offset:1664 sc1
	s_and_saveexec_b64 s[38:39], s[36:37]
	s_cbranch_execz .LBB0_101
	v_exp_f32_e32 v0, v59
	s_lshl_b64 s[36:37], s[50:51], 9
	v_readlane_b32 s2, v253, 22
	s_add_u32 s36, s2, s36
	v_readlane_b32 s2, v253, 23
	s_addc_u32 s37, s2, s37
	global_store_dword v55, v0, s[36:37] sc1
	s_branch .LBB0_101

; DI u16 f2bf(float x) { unsigned u = __float_as_uint(x); u += 0x7fffu + ((u >> 16) & 1u); return (u16)(u >> 16); }
; DI int crow(int r, int hi) { return (r & 3) + 8 * (r >> 2) + 4 * hi; }
; DI void attn_item_dma(const u16* Qb, const u16* Kh, const u16* Vh, const u16* Rh, u16* Ob, int seq, const float* rope, int pos0, char* lds) {
;     ...
;   if (hi == 0) li_l[r32] = l_reg; asm volatile("s_waitcnt lgkmcnt(0)" ::: "memory");
;   float rli[16];
; #pragma unroll
;   for (int r = 0; r < 16; ++r) rli[r] = __builtin_amdgcn_rcpf(li_l[crow(r, hi)]);
;   u16* Ow = Ob + (size_t)(wid * 32) * LDO;
; #pragma unroll
;   for (int r = 0; r < 16; ++r) { const int orow = crow(r, hi);
; #pragma unroll
;     for (int d0 = 0; d0 < 4; ++d0) Ow[(size_t)orow * LDO + d0 * 32 + r32] = f2bf(o[d0][r] * rli[r]); }
.LBB0_120:
	s_or_b64 exec, exec, s[38:39]
	s_waitcnt lgkmcnt(0)
	v_add_u32_e32 v72, v147, v96
	ds_read_b128 v[64:67], v72
	ds_read_b128 v[68:71], v72 offset:32
	s_lshl_b64 s[6:7], s[40:41], 11
	v_readlane_b32 s12, v255, 19
	v_readlane_b32 s13, v255, 20
	s_waitcnt lgkmcnt(0)
	v_rcp_f32_e32 v73, v64
	v_rcp_f32_e32 v74, v65
	v_rcp_f32_e32 v75, v66
	v_rcp_f32_e32 v76, v67
	ds_read_b128 v[64:67], v72 offset:64
	s_add_u32 s2, s12, s6
	s_addc_u32 s7, s13, s7
	s_lshl_b32 s6, s60, 8
	s_add_u32 s6, s2, s6
	v_ashrrev_i32_e32 v147, 31, v146
	s_addc_u32 s7, s7, 0
	v_rcp_f32_e32 v77, v68
	v_rcp_f32_e32 v78, v69
	v_rcp_f32_e32 v79, v70
	v_rcp_f32_e32 v80, v71
	ds_read_b128 v[68:71], v72 offset:96
	s_waitcnt lgkmcnt(0)
	v_rcp_f32_e32 v72, v64
	v_rcp_f32_e32 v81, v65
	v_lshlrev_b64 v[64:65], 11, v[146:147]
	v_lshl_add_u64 v[64:65], s[6:7], 0, v[64:65]
	v_lshlrev_b32_e32 v96, 1, v170
	v_rcp_f32_e32 v82, v66
	v_rcp_f32_e32 v83, v67
	v_lshlrev_b32_e32 v66, 13, v171
	v_lshl_add_u64 v[64:65], v[64:65], 0, v[96:97]
	v_mov_b32_e32 v67, v97
	v_mul_f32_e32 v0, v0, v73
	v_lshl_add_u64 v[64:65], v[64:65], 0, v[66:67]
	v_bfe_u32 v66, v0, 16, 1
	v_add3_u32 v0, v0, v66, s10
	global_store_short_d16_hi v[64:65], v0, off sc1
	v_mul_f32_e32 v0, v48, v73
	v_bfe_u32 v48, v0, 16, 1
	v_add3_u32 v0, v0, v48, s10
	global_store_short_d16_hi v[64:65], v0, off offset:64 sc1
	v_mul_f32_e32 v0, v32, v73
	v_bfe_u32 v32, v0, 16, 1
	v_add3_u32 v0, v0, v32, s10
	global_store_short_d16_hi v[64:65], v0, off offset:128 sc1
	v_mul_f32_e32 v0, v16, v73
	v_bfe_u32 v16, v0, 16, 1
	v_add3_u32 v0, v0, v16, s10
	global_store_short_d16_hi v[64:65], v0, off offset:192 sc1
	v_mul_f32_e32 v0, v1, v74
	v_bfe_u32 v1, v0, 16, 1
	v_add3_u32 v0, v0, v1, s10
	global_store_short_d16_hi v[64:65], v0, off offset:2048 sc1
	v_mul_f32_e32 v0, v49, v74
	v_bfe_u32 v1, v0, 16, 1
	v_add3_u32 v0, v0, v1, s10
	global_store_short_d16_hi v[64:65], v0, off offset:2112 sc1
	v_mul_f32_e32 v0, v33, v74
	v_bfe_u32 v1, v0, 16, 1
	v_add3_u32 v0, v0, v1, s10
	global_store_short_d16_hi v[64:65], v0, off offset:2176 sc1
	v_mul_f32_e32 v0, v17, v74
	v_bfe_u32 v1, v0, 16, 1
	v_add3_u32 v0, v0, v1, s10
	global_store_short_d16_hi v[64:65], v0, off offset:2240 sc1
	v_mul_f32_e32 v0, v2, v75
	v_bfe_u32 v1, v0, 16, 1
	s_movk_i32 s2, 0x1000
	v_add3_u32 v2, v0, v1, s10
	v_add_co_u32_e32 v0, vcc, s2, v64
	s_movk_i32 s2, 0x5000
	s_nop 0
	v_addc_co_u32_e32 v1, vcc, 0, v65, vcc
	global_store_short_d16_hi v[0:1], v2, off sc1
	v_mul_f32_e32 v2, v50, v75
	v_bfe_u32 v16, v2, 16, 1
	v_add3_u32 v2, v2, v16, s10
	global_store_short_d16_hi v[0:1], v2, off offset:64 sc1
	v_mul_f32_e32 v2, v34, v75
	v_bfe_u32 v16, v2, 16, 1
	v_add3_u32 v2, v2, v16, s10
	global_store_short_d16_hi v[0:1], v2, off offset:128 sc1
	v_mul_f32_e32 v2, v18, v75
	v_bfe_u32 v16, v2, 16, 1
	v_add3_u32 v2, v2, v16, s10
	global_store_short_d16_hi v[0:1], v2, off offset:192 sc1
	v_mul_f32_e32 v2, v3, v76
	v_bfe_u32 v3, v2, 16, 1
	v_add3_u32 v2, v2, v3, s10
	global_store_short_d16_hi v[0:1], v2, off offset:2048 sc1
	v_mul_f32_e32 v2, v51, v76
	v_bfe_u32 v3, v2, 16, 1
	v_add3_u32 v2, v2, v3, s10
	global_store_short_d16_hi v[0:1], v2, off offset:2112 sc1
	v_mul_f32_e32 v2, v35, v76
	v_bfe_u32 v3, v2, 16, 1
	v_add3_u32 v2, v2, v3, s10
	global_store_short_d16_hi v[0:1], v2, off offset:2176 sc1
	v_mul_f32_e32 v2, v19, v76
	v_bfe_u32 v3, v2, 16, 1
	v_add3_u32 v2, v2, v3, s10
	global_store_short_d16_hi v[0:1], v2, off offset:2240 sc1
	v_mul_f32_e32 v0, v4, v77
	v_bfe_u32 v1, v0, 16, 1
	v_add3_u32 v4, v0, v1, s10
	v_add_co_u32_e32 v0, vcc, s77, v64
	v_rcp_f32_e32 v68, v68
	s_nop 0
	v_addc_co_u32_e32 v1, vcc, 0, v65, vcc
	v_add_co_u32_e32 v2, vcc, s2, v64
	s_mov_b32 s2, 0x8000
	s_nop 0
	v_addc_co_u32_e32 v3, vcc, 0, v65, vcc
	global_store_short_d16_hi v[2:3], v4, off offset:-4096 sc1
	v_mul_f32_e32 v4, v52, v77
	v_bfe_u32 v16, v4, 16, 1
	v_add3_u32 v4, v4, v16, s10
	global_store_short_d16_hi v[0:1], v4, off offset:64 sc1
	v_mul_f32_e32 v4, v36, v77
	v_bfe_u32 v16, v4, 16, 1
	v_add3_u32 v4, v4, v16, s10
	global_store_short_d16_hi v[0:1], v4, off offset:128 sc1
	v_mul_f32_e32 v4, v20, v77
	v_bfe_u32 v16, v4, 16, 1
	v_add3_u32 v4, v4, v16, s10
	global_store_short_d16_hi v[0:1], v4, off offset:192 sc1
	v_mul_f32_e32 v4, v5, v78
	v_bfe_u32 v5, v4, 16, 1
	v_add3_u32 v4, v4, v5, s10
	global_store_short_d16_hi v[0:1], v4, off offset:2048 sc1
	v_mul_f32_e32 v4, v53, v78
	v_bfe_u32 v5, v4, 16, 1
	v_add3_u32 v4, v4, v5, s10
	global_store_short_d16_hi v[0:1], v4, off offset:2112 sc1
	v_mul_f32_e32 v4, v37, v78
	v_bfe_u32 v5, v4, 16, 1
	v_add3_u32 v4, v4, v5, s10
	global_store_short_d16_hi v[0:1], v4, off offset:2176 sc1
	v_mul_f32_e32 v4, v21, v78
	v_bfe_u32 v5, v4, 16, 1
	v_add3_u32 v4, v4, v5, s10
	global_store_short_d16_hi v[0:1], v4, off offset:2240 sc1
	v_mul_f32_e32 v0, v6, v79
	v_bfe_u32 v1, v0, 16, 1
	v_add3_u32 v0, v0, v1, s10
	global_store_short_d16_hi v[2:3], v0, off sc1
	v_mul_f32_e32 v0, v54, v79
	v_bfe_u32 v1, v0, 16, 1
	v_add3_u32 v0, v0, v1, s10
	global_store_short_d16_hi v[2:3], v0, off offset:64 sc1
	v_mul_f32_e32 v0, v38, v79
	v_bfe_u32 v1, v0, 16, 1
	v_add3_u32 v0, v0, v1, s10
	global_store_short_d16_hi v[2:3], v0, off offset:128 sc1
	v_mul_f32_e32 v0, v22, v79
	v_bfe_u32 v1, v0, 16, 1
	v_add3_u32 v0, v0, v1, s10
	global_store_short_d16_hi v[2:3], v0, off offset:192 sc1
	v_mul_f32_e32 v0, v7, v80
	v_bfe_u32 v1, v0, 16, 1
	v_add3_u32 v0, v0, v1, s10
	global_store_short_d16_hi v[2:3], v0, off offset:2048 sc1
; DI u16 f2bf(float x) { unsigned u = __float_as_uint(x); u += 0x7fffu + ((u >> 16) & 1u); return (u16)(u >> 16); }
; DI int crow(int r, int hi) { return (r & 3) + 8 * (r >> 2) + 4 * hi; }
; DI int bid_() { int b = blockIdx.x; asm volatile("" : "+s"(b)); return b; }
; DI void attn_item_dma(const u16* Qb, const u16* Kh, const u16* Vh, const u16* Rh, u16* Ob, int seq, const float* rope, int pos0, char* lds) {
;     ...
;   if (hi == 0) li_l[r32] = l_reg; asm volatile("s_waitcnt lgkmcnt(0)" ::: "memory");
;   float rli[16];
; #pragma unroll
;   for (int r = 0; r < 16; ++r) rli[r] = __builtin_amdgcn_rcpf(li_l[crow(r, hi)]);
;   u16* Ow = Ob + (size_t)(wid * 32) * LDO;
; #pragma unroll
;   for (int r = 0; r < 16; ++r) { const int orow = crow(r, hi);
; #pragma unroll
;     for (int d0 = 0; d0 < 4; ++d0) Ow[(size_t)orow * LDO + d0 * 32 + r32] = f2bf(o[d0][r] * rli[r]); }
; DI void phase_attn(const u16* Q, const u16* KV, const u16* KR, u16* OM, int L, const float* rope, char* lds) {
;     ...
;   for (int it = bid_(); it < 512; it += gridDim.x) {
;     const int h = it & 7, rest = it >> 3;
;     const int seq = rest / nqb, qb = rest % nqb;
;     const size_t tok0 = (size_t)seq * L;
;     ...
;     attn_item_dma(
;     ...
;     attn_item(
;     ...
;               Q + (tok0 + qb * 256) * 1536 + h * 192, KV + tok0 * 2048 + h * 256, KV + tok0 * 2048 + h * 256 + 128, KR + tok0 * 64,
;               OM + (tok0 + qb * 256) * 1024 + h * 128, L, rope, qb * 256, lds);
;   }
	v_mul_f32_e32 v0, v55, v80
	v_bfe_u32 v1, v0, 16, 1
	v_add3_u32 v0, v0, v1, s10
	global_store_short_d16_hi v[2:3], v0, off offset:2112 sc1
	v_mul_f32_e32 v0, v39, v80
	v_bfe_u32 v1, v0, 16, 1
	v_add3_u32 v0, v0, v1, s10
	global_store_short_d16_hi v[2:3], v0, off offset:2176 sc1
	v_mul_f32_e32 v0, v23, v80
	v_bfe_u32 v1, v0, 16, 1
	v_add3_u32 v0, v0, v1, s10
	global_store_short_d16_hi v[2:3], v0, off offset:2240 sc1
	v_mul_f32_e32 v0, v8, v72
	v_bfe_u32 v1, v0, 16, 1
	v_add3_u32 v4, v0, v1, s10
	v_add_co_u32_e32 v0, vcc, s2, v64
	s_mov_b32 s2, 0x9000
	s_nop 0
	v_addc_co_u32_e32 v1, vcc, 0, v65, vcc
	v_add_co_u32_e32 v2, vcc, s2, v64
	s_mov_b32 s2, 0xd000
	s_nop 0
	v_addc_co_u32_e32 v3, vcc, 0, v65, vcc
	global_store_short_d16_hi v[2:3], v4, off offset:-4096 sc1
	v_mul_f32_e32 v4, v56, v72
	v_bfe_u32 v5, v4, 16, 1
	v_add3_u32 v4, v4, v5, s10
	global_store_short_d16_hi v[0:1], v4, off offset:64 sc1
	v_mul_f32_e32 v4, v40, v72
	v_bfe_u32 v5, v4, 16, 1
	v_add3_u32 v4, v4, v5, s10
	global_store_short_d16_hi v[0:1], v4, off offset:128 sc1
	v_mul_f32_e32 v4, v24, v72
	v_bfe_u32 v5, v4, 16, 1
	v_add3_u32 v4, v4, v5, s10
	global_store_short_d16_hi v[0:1], v4, off offset:192 sc1
	v_mul_f32_e32 v4, v9, v81
	v_bfe_u32 v5, v4, 16, 1
	v_add3_u32 v4, v4, v5, s10
	global_store_short_d16_hi v[0:1], v4, off offset:2048 sc1
	v_mul_f32_e32 v4, v57, v81
	v_bfe_u32 v5, v4, 16, 1
	v_add3_u32 v4, v4, v5, s10
	global_store_short_d16_hi v[0:1], v4, off offset:2112 sc1
	v_mul_f32_e32 v4, v41, v81
	v_bfe_u32 v5, v4, 16, 1
	v_add3_u32 v4, v4, v5, s10
	global_store_short_d16_hi v[0:1], v4, off offset:2176 sc1
	v_mul_f32_e32 v4, v25, v81
	v_bfe_u32 v5, v4, 16, 1
	v_add3_u32 v4, v4, v5, s10
	global_store_short_d16_hi v[0:1], v4, off offset:2240 sc1
	v_mul_f32_e32 v0, v10, v82
	v_bfe_u32 v1, v0, 16, 1
	v_add3_u32 v0, v0, v1, s10
	global_store_short_d16_hi v[2:3], v0, off sc1
	v_mul_f32_e32 v0, v58, v82
	v_bfe_u32 v1, v0, 16, 1
	v_add3_u32 v0, v0, v1, s10
	global_store_short_d16_hi v[2:3], v0, off offset:64 sc1
	v_mul_f32_e32 v0, v42, v82
	v_bfe_u32 v1, v0, 16, 1
	v_add3_u32 v0, v0, v1, s10
	global_store_short_d16_hi v[2:3], v0, off offset:128 sc1
	v_mul_f32_e32 v0, v26, v82
	v_bfe_u32 v1, v0, 16, 1
	v_add3_u32 v0, v0, v1, s10
	global_store_short_d16_hi v[2:3], v0, off offset:192 sc1
	v_mul_f32_e32 v0, v11, v83
	v_bfe_u32 v1, v0, 16, 1
	v_add3_u32 v0, v0, v1, s10
	global_store_short_d16_hi v[2:3], v0, off offset:2048 sc1
	v_mul_f32_e32 v0, v59, v83
	v_bfe_u32 v1, v0, 16, 1
	v_add3_u32 v0, v0, v1, s10
	global_store_short_d16_hi v[2:3], v0, off offset:2112 sc1
	v_mul_f32_e32 v0, v43, v83
	v_bfe_u32 v1, v0, 16, 1
	v_add3_u32 v0, v0, v1, s10
	global_store_short_d16_hi v[2:3], v0, off offset:2176 sc1
	v_mul_f32_e32 v0, v27, v83
	v_bfe_u32 v1, v0, 16, 1
	v_add3_u32 v0, v0, v1, s10
	global_store_short_d16_hi v[2:3], v0, off offset:2240 sc1
	v_mul_f32_e32 v0, v12, v68
	v_bfe_u32 v1, v0, 16, 1
	v_add3_u32 v4, v0, v1, s10
	v_add_co_u32_e32 v0, vcc, s76, v64
	v_rcp_f32_e32 v69, v69
	s_nop 0
	v_addc_co_u32_e32 v1, vcc, 0, v65, vcc
	v_add_co_u32_e32 v2, vcc, s2, v64
	v_rcp_f32_e32 v70, v70
	s_nop 0
	v_addc_co_u32_e32 v3, vcc, 0, v65, vcc
	global_store_short_d16_hi v[2:3], v4, off offset:-4096 sc1
	v_mul_f32_e32 v4, v60, v68
	v_bfe_u32 v5, v4, 16, 1
	v_add3_u32 v4, v4, v5, s10
	global_store_short_d16_hi v[0:1], v4, off offset:64 sc1
	v_mul_f32_e32 v4, v44, v68
	v_bfe_u32 v5, v4, 16, 1
	v_add3_u32 v4, v4, v5, s10
	global_store_short_d16_hi v[0:1], v4, off offset:128 sc1
	v_mul_f32_e32 v4, v28, v68
	v_bfe_u32 v5, v4, 16, 1
	v_add3_u32 v4, v4, v5, s10
	global_store_short_d16_hi v[0:1], v4, off offset:192 sc1
	v_mul_f32_e32 v4, v13, v69
	v_bfe_u32 v5, v4, 16, 1
	v_add3_u32 v4, v4, v5, s10
	global_store_short_d16_hi v[0:1], v4, off offset:2048 sc1
	v_mul_f32_e32 v4, v61, v69
	v_bfe_u32 v5, v4, 16, 1
	v_add3_u32 v4, v4, v5, s10
	global_store_short_d16_hi v[0:1], v4, off offset:2112 sc1
	v_mul_f32_e32 v4, v45, v69
	v_bfe_u32 v5, v4, 16, 1
	v_add3_u32 v4, v4, v5, s10
	global_store_short_d16_hi v[0:1], v4, off offset:2176 sc1
	v_mul_f32_e32 v4, v29, v69
	v_bfe_u32 v5, v4, 16, 1
	v_add3_u32 v4, v4, v5, s10
	global_store_short_d16_hi v[0:1], v4, off offset:2240 sc1
	v_mul_f32_e32 v0, v14, v70
	v_bfe_u32 v1, v0, 16, 1
	v_add3_u32 v0, v0, v1, s10
	global_store_short_d16_hi v[2:3], v0, off sc1
	v_mul_f32_e32 v0, v62, v70
	v_bfe_u32 v1, v0, 16, 1
	v_add3_u32 v0, v0, v1, s10
	global_store_short_d16_hi v[2:3], v0, off offset:64 sc1
	v_mul_f32_e32 v0, v46, v70
	v_bfe_u32 v1, v0, 16, 1
	v_rcp_f32_e32 v71, v71
	v_add3_u32 v0, v0, v1, s10
	global_store_short_d16_hi v[2:3], v0, off offset:128 sc1
	v_mul_f32_e32 v0, v30, v70
	v_bfe_u32 v1, v0, 16, 1
	v_add3_u32 v0, v0, v1, s10
	global_store_short_d16_hi v[2:3], v0, off offset:192 sc1
	v_mul_f32_e32 v0, v15, v71
	v_bfe_u32 v1, v0, 16, 1
	v_add3_u32 v0, v0, v1, s10
	global_store_short_d16_hi v[2:3], v0, off offset:2048 sc1
	v_mul_f32_e32 v0, v63, v71
	v_bfe_u32 v1, v0, 16, 1
	v_add3_u32 v0, v0, v1, s10
	global_store_short_d16_hi v[2:3], v0, off offset:2112 sc1
	v_mul_f32_e32 v0, v47, v71
	v_bfe_u32 v1, v0, 16, 1
	v_add3_u32 v0, v0, v1, s10
	global_store_short_d16_hi v[2:3], v0, off offset:2176 sc1
	v_mul_f32_e32 v0, v31, v71
	v_bfe_u32 v1, v0, 16, 1
	s_add_i32 s59, s59, s30
	s_add_i32 s50, s50, s30
	v_add3_u32 v0, v0, v1, s10
	s_cmpk_gt_i32 s59, 0x1ff
	global_store_short_d16_hi v[2:3], v0, off offset:2240 sc1
	s_cbranch_scc1 .LBB0_142

; DI float bf2f(short b) { return __uint_as_float(((unsigned)(unsigned short)b) << 16); }
; DI unsigned cvtpk(float lo, float hi) { unsigned r; asm volatile("v_cvt_pk_bf16_f32 %0, %1, %2" : "=v"(r) : "v"(lo), "v"(hi)); return r; }
; DI u16 f2bf(float x) { unsigned u = __float_as_uint(x); u += 0x7fffu + ((u >> 16) & 1u); return (u16)(u >> 16); }
; DI void phase_mqkv_norm(u16* PROJ, const float* qg, const float* kvg, const float* rope, u16* KR, int L) {
;     ...
;     for (int b = 0; b < 4; ++b) { const int tok = tok0 + b * stride;
;       if (tok < TG) { u16* row = PROJ + (size_t)tok * INP;
;         { float a[6]; float ss = 0.f;
; #pragma unroll
;           for (int i = 0; i < 3; ++i) { const unsigned u = uq[b][i]; a[2 * i] = __uint_as_float(u << 16); a[2 * i + 1] = __uint_as_float(u & 0xffff0000u);
;             ss += a[2 * i] * a[2 * i] + a[2 * i + 1] * a[2 * i + 1]; }
;           ss = wave_sum_l(ss, lane); const float r = rsqrtf(ss * (1.f / 384.f) + EPS);
; #pragma unroll
;           for (int i = 0; i < 3; ++i) *reinterpret_cast<unsigned*>(row + C_MQ + i * 128 + lane * 2) = cvtpk(a[2 * i] * r * qgv[2 * i], a[2 * i + 1] * r * qgv[2 * i + 1]); }
;         { float a[4]; float ss = 0.f;
; #pragma unroll
;           for (int i = 0; i < 2; ++i) { const unsigned u = uk[b][i]; a[2 * i] = __uint_as_float(u << 16); a[2 * i + 1] = __uint_as_float(u & 0xffff0000u);
;             ss += a[2 * i] * a[2 * i] + a[2 * i + 1] * a[2 * i + 1]; }
;           ss = wave_sum_l(ss, lane); const float r = rsqrtf(ss * (1.f / 256.f) + EPS);
; #pragma unroll
;           for (int i = 0; i < 2; ++i) *reinterpret_cast<unsigned*>(row + C_MKV + i * 128 + lane * 2) = cvtpk(a[2 * i] * r * kgv[2 * i], a[2 * i + 1] * r * kgv[2 * i + 1]); }
;         if (lane < 32) { const float x1 = bf2f((short)r1[b]), x2 = bf2f((short)r2[b]);
;           KR[(size_t)tok * 64 + lane] = f2bf(x1 * c1[b] - x2 * s1[b]); KR[(size_t)tok * 64 + 32 + lane] = f2bf(x1 * s1[b] + x2 * c1[b]); } } }
.LBB0_159:
	s_or_b64 exec, exec, s[50:51]
	s_waitcnt vmcnt(6)
	v_lshlrev_b32_e32 v53, 16, v65
	v_lshlrev_b32_e32 v52, 16, v64
	v_lshlrev_b32_e32 v67, 16, v63
	v_and_b32_e32 v66, 0xffff0000, v63
	v_and_b32_e32 v65, 0xffff0000, v65
	v_and_b32_e32 v64, 0xffff0000, v64
	v_pk_mul_f32 v[68:69], v[66:67], v[66:67]
	v_pk_mul_f32 v[70:71], v[52:53], v[52:53]
	v_add_f32_e32 v63, v68, v69
	v_pk_fma_f32 v[70:71], v[64:65], v[64:65], v[70:71]
	s_waitcnt vmcnt(4)
	v_lshlrev_b32_e32 v69, 16, v62
	v_add_f32_e32 v63, v70, v63
	v_add_f32_e32 v63, v63, v71
	s_nop 1
	v_add_f32_dpp v63, v63, v63 quad_perm:[1,0,3,2] row_mask:0xf bank_mask:0xf bound_ctrl:1
	s_nop 1
	v_add_f32_dpp v63, v63, v63 quad_perm:[2,3,0,1] row_mask:0xf bank_mask:0xf bound_ctrl:1
	s_nop 1
	v_add_f32_dpp v63, v63, v63 row_half_mirror row_mask:0xf bank_mask:0xf bound_ctrl:1
	s_nop 1
	v_add_f32_dpp v63, v63, v63 row_mirror row_mask:0xf bank_mask:0xf bound_ctrl:1
	ds_bpermute_b32 v68, v39, v63
	s_waitcnt lgkmcnt(0)
	v_add_f32_e32 v63, v63, v68
	ds_bpermute_b32 v68, v41, v63
	s_waitcnt lgkmcnt(0)
	v_add_f32_e32 v63, v63, v68
	v_fmamk_f32 v63, v63, 0x3b2aaaab, v233
	v_mul_f32_e32 v68, 0x4b800000, v63
	v_cmp_gt_f32_e32 vcc, s94, v63
	s_nop 1
	v_cndmask_b32_e32 v63, v63, v68, vcc
	v_rsq_f32_e32 v63, v63
	s_nop 0
	v_mul_f32_e32 v68, 0x45800000, v63
	v_cndmask_b32_e32 v72, v63, v68, vcc
	v_mul_f32_e32 v52, v72, v52
	v_mul_f32_e32 v63, v72, v64
	v_mul_f32_e32 v52, v8, v52
	v_mul_f32_e32 v63, v9, v63
	v_lshlrev_b32_e32 v68, 16, v49
	v_cvt_pk_bf16_f32 v52, v52, v63
	v_and_b32_e32 v63, 0xffff0000, v62
	v_and_b32_e32 v62, 0xffff0000, v49
	v_pk_mul_f32 v[70:71], v[68:69], v[68:69]
	global_store_dword v[50:51], v52, off offset:-768 sc1
	v_pk_fma_f32 v[70:71], v[62:63], v[62:63], v[70:71]
	v_mul_f32_e32 v64, v72, v67
	v_add_f32_e32 v49, v70, v71
	v_mul_f32_e32 v64, v10, v64
	v_mul_f32_e32 v66, v72, v66
	v_add_f32_dpp v49, v49, v49 quad_perm:[1,0,3,2] row_mask:0xf bank_mask:0xf bound_ctrl:1
	v_mul_f32_e32 v66, v11, v66
	v_cvt_pk_bf16_f32 v64, v64, v66
	global_store_dword v[50:51], v64, off offset:-512 sc1
	v_add_f32_dpp v49, v49, v49 quad_perm:[2,3,0,1] row_mask:0xf bank_mask:0xf bound_ctrl:1
	v_mul_f32_e32 v64, v72, v65
	v_mul_f32_e32 v53, v72, v53
	v_add_f32_dpp v49, v49, v49 row_half_mirror row_mask:0xf bank_mask:0xf bound_ctrl:1
	v_mul_f32_e32 v53, v12, v53
	s_nop 0
	v_add_f32_dpp v49, v49, v49 row_mirror row_mask:0xf bank_mask:0xf bound_ctrl:1
	ds_bpermute_b32 v52, v39, v49
	s_waitcnt lgkmcnt(0)
	v_add_f32_e32 v49, v49, v52
	ds_bpermute_b32 v52, v41, v49
	s_waitcnt lgkmcnt(0)
	v_add_f32_e32 v49, v49, v52
	v_fmamk_f32 v49, v49, 0x3b800000, v233
	v_mul_f32_e32 v52, 0x4b800000, v49
	v_cmp_gt_f32_e32 vcc, s94, v49
	s_nop 1
	v_cndmask_b32_e32 v49, v49, v52, vcc
	v_rsq_f32_e32 v49, v49
	v_mul_f32_e32 v52, v13, v64
	v_cvt_pk_bf16_f32 v52, v53, v52
	global_store_dword v[50:51], v52, off offset:-256 sc1
	v_mul_f32_e32 v52, 0x45800000, v49
	v_cndmask_b32_e32 v49, v49, v52, vcc
	v_mul_f32_e32 v52, v49, v68
	v_mul_f32_e32 v52, v14, v52
	v_mul_f32_e32 v53, v49, v62
	v_mul_f32_e32 v53, v15, v53
	v_cvt_pk_bf16_f32 v52, v52, v53
	global_store_dword v[50:51], v52, off sc1
	v_mul_f32_e32 v52, v49, v69
	v_mul_f32_e32 v49, v49, v63
	v_mul_f32_e32 v49, v17, v49
	v_mul_f32_e32 v52, v16, v52
	v_cvt_pk_bf16_f32 v49, v52, v49
	global_store_dword v[50:51], v49, off offset:256 sc1
	s_and_saveexec_b64 s[50:51], s[36:37]
	s_cbranch_execz .LBB0_161
	s_waitcnt vmcnt(7)
	v_lshlrev_b32_e32 v47, 16, v47
	v_lshlrev_b32_e32 v45, 16, v45
	s_waitcnt vmcnt(5)
	v_mul_f32_e32 v49, v4, v47
	v_fma_f32 v49, v0, v45, -v49
	v_bfe_u32 v50, v49, 16, 1
	v_mul_f32_e32 v0, v0, v47
	v_add3_u32 v49, v49, v50, s10
	v_lshl_add_u64 v[50:51], v[26:27], 0, s[64:65]
	v_fmac_f32_e32 v0, v4, v45
	v_add_co_u32_e32 v50, vcc, 0x1fb40000, v50
	v_bfe_u32 v4, v0, 16, 1
	s_nop 0
	v_addc_co_u32_e32 v51, vcc, 0, v51, vcc
	v_add3_u32 v0, v0, v4, s10
	global_store_short_d16_hi v[50:51], v49, off sc1
	global_store_short_d16_hi v[50:51], v0, off offset:64 sc1
.LBB0_161:
	s_or_b64 exec, exec, s[50:51]
	s_and_saveexec_b64 s[50:51], s[42:43]
	s_cbranch_execz .LBB0_164
	v_and_b32_e32 v50, 0xffff0000, v55
	v_lshlrev_b32_e32 v51, 16, v55
	v_lshlrev_b32_e32 v63, 16, v37
	s_waitcnt vmcnt(6)
	v_lshlrev_b32_e32 v62, 16, v42
	v_pk_mul_f32 v[52:53], v[50:51], v[50:51]
	v_and_b32_e32 v65, 0xffff0000, v37
	v_and_b32_e32 v64, 0xffff0000, v42
	v_pk_mul_f32 v[66:67], v[62:63], v[62:63]
	v_add_f32_e32 v0, v52, v53
	v_pk_fma_f32 v[66:67], v[64:65], v[64:65], v[66:67]
	v_lshlrev_b32_e32 v69, 16, v35
	v_add_f32_e32 v0, v67, v0
	v_add_f32_e32 v0, v66, v0
	v_lshlrev_b32_e32 v68, 16, v38
	v_and_b32_e32 v71, 0xffff0000, v35
	v_add_f32_dpp v0, v0, v0 quad_perm:[1,0,3,2] row_mask:0xf bank_mask:0xf bound_ctrl:1
	v_and_b32_e32 v70, 0xffff0000, v38
	v_pk_mul_f32 v[72:73], v[68:69], v[68:69]
	v_add_f32_dpp v0, v0, v0 quad_perm:[2,3,0,1] row_mask:0xf bank_mask:0xf bound_ctrl:1
	v_pk_fma_f32 v[72:73], v[70:71], v[70:71], v[72:73]
	v_mov_b64_e32 v[52:53], s[8:9]
	v_add_f32_dpp v0, v0, v0 row_half_mirror row_mask:0xf bank_mask:0xf bound_ctrl:1
	v_mad_i64_i32 v[52:53], s[12:13], v48, s33, v[52:53]
	s_nop 0
	v_add_f32_dpp v0, v0, v0 row_mirror row_mask:0xf bank_mask:0xf bound_ctrl:1
	s_waitcnt vmcnt(5)
	ds_bpermute_b32 v4, v39, v0
	v_lshl_add_u64 v[52:53], v[52:53], 0, v[96:97]
	s_movk_i32 s2, 0x2000
	v_lshl_add_u64 v[66:67], v[52:53], 0, s[60:61]
	s_waitcnt lgkmcnt(0)
	v_add_f32_e32 v0, v0, v4
	ds_bpermute_b32 v4, v41, v0
	s_waitcnt lgkmcnt(0)
; DI float bf2f(short b) { return __uint_as_float(((unsigned)(unsigned short)b) << 16); }
; DI unsigned cvtpk(float lo, float hi) { unsigned r; asm volatile("v_cvt_pk_bf16_f32 %0, %1, %2" : "=v"(r) : "v"(lo), "v"(hi)); return r; }
; DI u16 f2bf(float x) { unsigned u = __float_as_uint(x); u += 0x7fffu + ((u >> 16) & 1u); return (u16)(u >> 16); }
; DI void phase_mqkv_norm(u16* PROJ, const float* qg, const float* kvg, const float* rope, u16* KR, int L) {
;     ...
;     for (int b = 0; b < 4; ++b) { const int tok = tok0 + b * stride;
;       if (tok < TG) { u16* row = PROJ + (size_t)tok * INP;
;         { float a[6]; float ss = 0.f;
; #pragma unroll
;           for (int i = 0; i < 3; ++i) { const unsigned u = uq[b][i]; a[2 * i] = __uint_as_float(u << 16); a[2 * i + 1] = __uint_as_float(u & 0xffff0000u);
;             ss += a[2 * i] * a[2 * i] + a[2 * i + 1] * a[2 * i + 1]; }
;           ss = wave_sum_l(ss, lane); const float r = rsqrtf(ss * (1.f / 384.f) + EPS);
; #pragma unroll
;           for (int i = 0; i < 3; ++i) *reinterpret_cast<unsigned*>(row + C_MQ + i * 128 + lane * 2) = cvtpk(a[2 * i] * r * qgv[2 * i], a[2 * i + 1] * r * qgv[2 * i + 1]); }
;         { float a[4]; float ss = 0.f;
; #pragma unroll
;           for (int i = 0; i < 2; ++i) { const unsigned u = uk[b][i]; a[2 * i] = __uint_as_float(u << 16); a[2 * i + 1] = __uint_as_float(u & 0xffff0000u);
;             ss += a[2 * i] * a[2 * i] + a[2 * i + 1] * a[2 * i + 1]; }
;           ss = wave_sum_l(ss, lane); const float r = rsqrtf(ss * (1.f / 256.f) + EPS);
; #pragma unroll
;           for (int i = 0; i < 2; ++i) *reinterpret_cast<unsigned*>(row + C_MKV + i * 128 + lane * 2) = cvtpk(a[2 * i] * r * kgv[2 * i], a[2 * i + 1] * r * kgv[2 * i + 1]); }
;         if (lane < 32) { const float x1 = bf2f((short)r1[b]), x2 = bf2f((short)r2[b]);
;           KR[(size_t)tok * 64 + lane] = f2bf(x1 * c1[b] - x2 * s1[b]); KR[(size_t)tok * 64 + 32 + lane] = f2bf(x1 * s1[b] + x2 * c1[b]); } } }
	v_add_f32_e32 v0, v0, v4
	v_fmamk_f32 v0, v0, 0x3b2aaaab, v233
	v_mul_f32_e32 v4, 0x4b800000, v0
	v_cmp_gt_f32_e32 vcc, s94, v0
	s_nop 1
	v_cndmask_b32_e32 v0, v0, v4, vcc
	v_rsq_f32_e32 v0, v0
	s_nop 0
	v_mul_f32_e32 v4, 0x45800000, v0
	v_cndmask_b32_e32 v0, v0, v4, vcc
	v_mul_f32_e32 v4, v0, v51
	v_mul_f32_e32 v45, v0, v50
	v_mul_f32_e32 v4, v8, v4
	v_mul_f32_e32 v45, v9, v45
	v_cvt_pk_bf16_f32 v4, v4, v45
	v_add_f32_e32 v45, v72, v73
	v_add_co_u32_e32 v50, vcc, s2, v52
	s_nop 0
	v_add_f32_dpp v45, v45, v45 quad_perm:[1,0,3,2] row_mask:0xf bank_mask:0xf bound_ctrl:1
	v_addc_co_u32_e32 v51, vcc, 0, v53, vcc
	s_nop 0
	v_add_f32_dpp v45, v45, v45 quad_perm:[2,3,0,1] row_mask:0xf bank_mask:0xf bound_ctrl:1
	global_store_dword v[50:51], v4, off offset:2048 sc1
	v_mul_f32_e32 v4, v0, v63
	v_add_f32_dpp v45, v45, v45 row_half_mirror row_mask:0xf bank_mask:0xf bound_ctrl:1
	v_mul_f32_e32 v4, v10, v4
	v_mul_f32_e32 v49, v0, v65
	v_add_f32_dpp v45, v45, v45 row_mirror row_mask:0xf bank_mask:0xf bound_ctrl:1
	ds_bpermute_b32 v47, v39, v45
	v_mul_f32_e32 v49, v11, v49
	v_cvt_pk_bf16_f32 v4, v4, v49
	global_store_dword v[66:67], v4, off offset:256 sc1
	v_mul_f32_e32 v4, v0, v62
	s_waitcnt lgkmcnt(0)
	v_add_f32_e32 v45, v45, v47
	ds_bpermute_b32 v47, v41, v45
	v_mul_f32_e32 v0, v0, v64
	v_mul_f32_e32 v0, v13, v0
	v_mul_f32_e32 v4, v12, v4
	v_cvt_pk_bf16_f32 v0, v4, v0
	s_waitcnt lgkmcnt(0)
	v_add_f32_e32 v45, v45, v47
	v_fmamk_f32 v45, v45, 0x3b800000, v233
	v_mul_f32_e32 v47, 0x4b800000, v45
	v_cmp_gt_f32_e32 vcc, s94, v45
	global_store_dword v[66:67], v0, off offset:512 sc1
	v_lshl_add_u64 v[52:53], v[52:53], 0, s[62:63]
	v_cndmask_b32_e32 v45, v45, v47, vcc
	v_rsq_f32_e32 v45, v45
	s_nop 0
	v_mul_f32_e32 v0, 0x45800000, v45
	v_cndmask_b32_e32 v0, v45, v0, vcc
	v_mul_f32_e32 v4, v0, v69
	v_mul_f32_e32 v4, v14, v4
	v_mul_f32_e32 v45, v0, v71
	v_mul_f32_e32 v45, v15, v45
	v_cvt_pk_bf16_f32 v4, v4, v45
	global_store_dword v[50:51], v4, off offset:2816 sc1
	v_mul_f32_e32 v4, v0, v68
	v_mul_f32_e32 v0, v0, v70
	v_mul_f32_e32 v0, v17, v0
	v_mul_f32_e32 v4, v16, v4
	v_cvt_pk_bf16_f32 v0, v4, v0
	global_store_dword v[52:53], v0, off offset:256 sc1
	s_and_b64 exec, exec, s[36:37]
	s_cbranch_execz .LBB0_164
	v_lshlrev_b32_e32 v4, 16, v61
	v_lshlrev_b32_e32 v0, 16, v58
	v_mul_f32_e32 v45, v5, v4
	v_mul_f32_e32 v4, v1, v4
	v_ashrrev_i32_e32 v49, 31, v48
	v_fma_f32 v45, v1, v0, -v45
	v_fmac_f32_e32 v4, v5, v0
	v_bfe_u32 v47, v45, 16, 1
	v_lshlrev_b64 v[48:49], 7, v[48:49]
	v_bfe_u32 v0, v4, 16, 1
	v_add3_u32 v45, v45, v47, s10
	v_lshl_add_u64 v[48:49], v[24:25], 0, v[48:49]
	v_add3_u32 v0, v4, v0, s10
	global_store_short_d16_hi v[48:49], v45, off sc1
	global_store_short_d16_hi v[48:49], v0, off offset:64 sc1
.LBB0_164:
	s_or_b64 exec, exec, s[50:51]
	s_and_saveexec_b64 s[42:43], s[40:41]
	s_cbranch_execz .LBB0_167
	v_and_b32_e32 v48, 0xffff0000, v54
	v_lshlrev_b32_e32 v49, 16, v54
	v_lshlrev_b32_e32 v53, 16, v33
	s_waitcnt vmcnt(6)
	v_lshlrev_b32_e32 v52, 16, v40
	v_pk_mul_f32 v[50:51], v[48:49], v[48:49]
	v_and_b32_e32 v63, 0xffff0000, v33
	v_and_b32_e32 v62, 0xffff0000, v40
	v_pk_mul_f32 v[64:65], v[52:53], v[52:53]
	v_add_f32_e32 v0, v50, v51
	v_pk_fma_f32 v[64:65], v[62:63], v[62:63], v[64:65]
	v_lshlrev_b32_e32 v67, 16, v23
	v_add_f32_e32 v0, v65, v0
	v_add_f32_e32 v0, v64, v0
	v_lshlrev_b32_e32 v66, 16, v34
	v_and_b32_e32 v69, 0xffff0000, v23
	v_add_f32_dpp v0, v0, v0 quad_perm:[1,0,3,2] row_mask:0xf bank_mask:0xf bound_ctrl:1
	v_and_b32_e32 v68, 0xffff0000, v34
	v_pk_mul_f32 v[70:71], v[66:67], v[66:67]
	v_add_f32_dpp v0, v0, v0 quad_perm:[2,3,0,1] row_mask:0xf bank_mask:0xf bound_ctrl:1
	v_pk_fma_f32 v[70:71], v[68:69], v[68:69], v[70:71]
	v_mov_b64_e32 v[50:51], s[8:9]
	v_add_f32_dpp v0, v0, v0 row_half_mirror row_mask:0xf bank_mask:0xf bound_ctrl:1
	v_mad_i64_i32 v[50:51], s[12:13], v46, s33, v[50:51]
	s_nop 0
	v_add_f32_dpp v0, v0, v0 row_mirror row_mask:0xf bank_mask:0xf bound_ctrl:1
	s_waitcnt vmcnt(5)
	ds_bpermute_b32 v4, v39, v0
	v_lshl_add_u64 v[50:51], v[50:51], 0, v[96:97]
	s_movk_i32 s2, 0x2000
	v_lshl_add_u64 v[64:65], v[50:51], 0, s[60:61]
	s_waitcnt lgkmcnt(0)
	v_add_f32_e32 v0, v0, v4
	ds_bpermute_b32 v4, v41, v0
	s_waitcnt lgkmcnt(0)
	v_add_f32_e32 v0, v0, v4
	v_fmamk_f32 v0, v0, 0x3b2aaaab, v233
	v_mul_f32_e32 v4, 0x4b800000, v0
	v_cmp_gt_f32_e32 vcc, s94, v0
	s_nop 1
	v_cndmask_b32_e32 v0, v0, v4, vcc
	v_rsq_f32_e32 v0, v0
	s_nop 0
	v_mul_f32_e32 v4, 0x45800000, v0
	v_cndmask_b32_e32 v0, v0, v4, vcc
	v_mul_f32_e32 v4, v0, v49
	v_mul_f32_e32 v45, v0, v48
	v_mul_f32_e32 v4, v8, v4
	v_mul_f32_e32 v45, v9, v45
	v_cvt_pk_bf16_f32 v4, v4, v45
	v_add_f32_e32 v45, v70, v71
	v_add_co_u32_e32 v48, vcc, s2, v50
	s_nop 0
	v_add_f32_dpp v45, v45, v45 quad_perm:[1,0,3,2] row_mask:0xf bank_mask:0xf bound_ctrl:1
	v_addc_co_u32_e32 v49, vcc, 0, v51, vcc
	s_nop 0
	v_add_f32_dpp v45, v45, v45 quad_perm:[2,3,0,1] row_mask:0xf bank_mask:0xf bound_ctrl:1
	global_store_dword v[48:49], v4, off offset:2048 sc1
	v_mul_f32_e32 v4, v0, v53
	v_add_f32_dpp v45, v45, v45 row_half_mirror row_mask:0xf bank_mask:0xf bound_ctrl:1
	v_mul_f32_e32 v4, v10, v4
	v_mul_f32_e32 v53, v0, v63
	v_add_f32_dpp v45, v45, v45 row_mirror row_mask:0xf bank_mask:0xf bound_ctrl:1
	ds_bpermute_b32 v47, v39, v45
	v_mul_f32_e32 v53, v11, v53
	v_cvt_pk_bf16_f32 v4, v4, v53
	global_store_dword v[64:65], v4, off offset:256 sc1
	v_mul_f32_e32 v4, v0, v52
	s_waitcnt lgkmcnt(0)
	v_add_f32_e32 v45, v45, v47
	ds_bpermute_b32 v47, v41, v45
	v_mul_f32_e32 v0, v0, v62
	v_mul_f32_e32 v0, v13, v0
	v_mul_f32_e32 v4, v12, v4
	v_cvt_pk_bf16_f32 v0, v4, v0
	s_waitcnt lgkmcnt(0)
	v_add_f32_e32 v45, v45, v47
	v_fmamk_f32 v45, v45, 0x3b800000, v233
	v_mul_f32_e32 v47, 0x4b800000, v45
	v_cmp_gt_f32_e32 vcc, s94, v45
	global_store_dword v[64:65], v0, off offset:512 sc1
	v_lshl_add_u64 v[50:51], v[50:51], 0, s[62:63]
	v_cndmask_b32_e32 v45, v45, v47, vcc
	v_rsq_f32_e32 v45, v45
	s_nop 0
	v_mul_f32_e32 v0, 0x45800000, v45
	v_cndmask_b32_e32 v0, v45, v0, vcc
	v_mul_f32_e32 v4, v0, v67
	v_mul_f32_e32 v4, v14, v4
	v_mul_f32_e32 v45, v0, v69
	v_mul_f32_e32 v45, v15, v45
	v_cvt_pk_bf16_f32 v4, v4, v45
	global_store_dword v[48:49], v4, off offset:2816 sc1
	v_mul_f32_e32 v4, v0, v66
	v_mul_f32_e32 v0, v0, v68
	v_mul_f32_e32 v0, v17, v0
	v_mul_f32_e32 v4, v16, v4
	v_cvt_pk_bf16_f32 v0, v4, v0
	global_store_dword v[50:51], v0, off offset:256 sc1
	s_and_b64 exec, exec, s[36:37]
	s_cbranch_execz .LBB0_167
	v_lshlrev_b32_e32 v4, 16, v60
	v_lshlrev_b32_e32 v0, 16, v57
	v_mul_f32_e32 v45, v6, v4
	v_mul_f32_e32 v4, v2, v4
	v_ashrrev_i32_e32 v47, 31, v46
	v_fma_f32 v45, v2, v0, -v45
	v_fmac_f32_e32 v4, v6, v0
	v_bfe_u32 v48, v45, 16, 1
	v_lshlrev_b64 v[46:47], 7, v[46:47]
	v_bfe_u32 v0, v4, 16, 1
	v_add3_u32 v45, v45, v48, s10
	v_lshl_add_u64 v[46:47], v[24:25], 0, v[46:47]
	v_add3_u32 v0, v4, v0, s10
	global_store_short_d16_hi v[46:47], v45, off sc1
	global_store_short_d16_hi v[46:47], v0, off offset:64 sc1
; DI float bf2f(short b) { return __uint_as_float(((unsigned)(unsigned short)b) << 16); }
; DI unsigned cvtpk(float lo, float hi) { unsigned r; asm volatile("v_cvt_pk_bf16_f32 %0, %1, %2" : "=v"(r) : "v"(lo), "v"(hi)); return r; }
; DI u16 f2bf(float x) { unsigned u = __float_as_uint(x); u += 0x7fffu + ((u >> 16) & 1u); return (u16)(u >> 16); }
; DI void phase_mqkv_norm(u16* PROJ, const float* qg, const float* kvg, const float* rope, u16* KR, int L) {
;     ...
;     for (int b = 0; b < 4; ++b) { const int tok = tok0 + b * stride;
;       if (tok < TG) { u16* row = PROJ + (size_t)tok * INP;
;         { float a[6]; float ss = 0.f;
; #pragma unroll
;           for (int i = 0; i < 3; ++i) { const unsigned u = uq[b][i]; a[2 * i] = __uint_as_float(u << 16); a[2 * i + 1] = __uint_as_float(u & 0xffff0000u);
;             ss += a[2 * i] * a[2 * i] + a[2 * i + 1] * a[2 * i + 1]; }
;           ss = wave_sum_l(ss, lane); const float r = rsqrtf(ss * (1.f / 384.f) + EPS);
; #pragma unroll
;           for (int i = 0; i < 3; ++i) *reinterpret_cast<unsigned*>(row + C_MQ + i * 128 + lane * 2) = cvtpk(a[2 * i] * r * qgv[2 * i], a[2 * i + 1] * r * qgv[2 * i + 1]); }
;         { float a[4]; float ss = 0.f;
; #pragma unroll
;           for (int i = 0; i < 2; ++i) { const unsigned u = uk[b][i]; a[2 * i] = __uint_as_float(u << 16); a[2 * i + 1] = __uint_as_float(u & 0xffff0000u);
;             ss += a[2 * i] * a[2 * i] + a[2 * i + 1] * a[2 * i + 1]; }
;           ss = wave_sum_l(ss, lane); const float r = rsqrtf(ss * (1.f / 256.f) + EPS);
; #pragma unroll
;           for (int i = 0; i < 2; ++i) *reinterpret_cast<unsigned*>(row + C_MKV + i * 128 + lane * 2) = cvtpk(a[2 * i] * r * kgv[2 * i], a[2 * i + 1] * r * kgv[2 * i + 1]); }
;         if (lane < 32) { const float x1 = bf2f((short)r1[b]), x2 = bf2f((short)r2[b]);
;           KR[(size_t)tok * 64 + lane] = f2bf(x1 * c1[b] - x2 * s1[b]); KR[(size_t)tok * 64 + 32 + lane] = f2bf(x1 * s1[b] + x2 * c1[b]); } } }
.LBB0_167:
	s_or_b64 exec, exec, s[42:43]
	s_and_saveexec_b64 s[40:41], s[38:39]
	s_cbranch_execz .LBB0_152
	v_and_b32_e32 v46, 0xffff0000, v43
	s_waitcnt vmcnt(7)
	v_lshlrev_b32_e32 v47, 16, v43
	v_lshlrev_b32_e32 v51, 16, v21
	s_waitcnt vmcnt(6)
	v_lshlrev_b32_e32 v50, 16, v36
	v_pk_mul_f32 v[48:49], v[46:47], v[46:47]
	v_and_b32_e32 v53, 0xffff0000, v21
	v_and_b32_e32 v52, 0xffff0000, v36
	v_pk_mul_f32 v[62:63], v[50:51], v[50:51]
	v_add_f32_e32 v0, v48, v49
	v_pk_fma_f32 v[62:63], v[52:53], v[52:53], v[62:63]
	v_lshlrev_b32_e32 v65, 16, v19
	v_add_f32_e32 v0, v63, v0
	v_add_f32_e32 v0, v62, v0
	v_lshlrev_b32_e32 v64, 16, v32
	v_and_b32_e32 v67, 0xffff0000, v19
	v_add_f32_dpp v0, v0, v0 quad_perm:[1,0,3,2] row_mask:0xf bank_mask:0xf bound_ctrl:1
	v_and_b32_e32 v66, 0xffff0000, v32
	v_pk_mul_f32 v[68:69], v[64:65], v[64:65]
	v_add_f32_dpp v0, v0, v0 quad_perm:[2,3,0,1] row_mask:0xf bank_mask:0xf bound_ctrl:1
	v_pk_fma_f32 v[68:69], v[66:67], v[66:67], v[68:69]
	v_mov_b64_e32 v[48:49], s[8:9]
	v_add_f32_dpp v0, v0, v0 row_half_mirror row_mask:0xf bank_mask:0xf bound_ctrl:1
	v_mad_i64_i32 v[48:49], s[12:13], v44, s33, v[48:49]
	s_nop 0
	v_add_f32_dpp v0, v0, v0 row_mirror row_mask:0xf bank_mask:0xf bound_ctrl:1
	s_waitcnt vmcnt(5)
	ds_bpermute_b32 v4, v39, v0
	v_lshl_add_u64 v[48:49], v[48:49], 0, v[96:97]
	s_movk_i32 s2, 0x2000
	v_lshl_add_u64 v[62:63], v[48:49], 0, s[60:61]
	s_waitcnt lgkmcnt(0)
	v_add_f32_e32 v0, v0, v4
	ds_bpermute_b32 v4, v41, v0
	s_waitcnt lgkmcnt(0)
	v_add_f32_e32 v0, v0, v4
	v_fmamk_f32 v0, v0, 0x3b2aaaab, v233
	v_mul_f32_e32 v4, 0x4b800000, v0
	v_cmp_gt_f32_e32 vcc, s94, v0
	s_nop 1
	v_cndmask_b32_e32 v0, v0, v4, vcc
	v_rsq_f32_e32 v0, v0
	s_nop 0
	v_mul_f32_e32 v4, 0x45800000, v0
	v_cndmask_b32_e32 v0, v0, v4, vcc
	v_mul_f32_e32 v4, v0, v47
	v_mul_f32_e32 v45, v0, v46
	v_mul_f32_e32 v4, v8, v4
	v_mul_f32_e32 v45, v9, v45
	v_cvt_pk_bf16_f32 v4, v4, v45
	v_add_f32_e32 v45, v68, v69
	v_add_co_u32_e32 v46, vcc, s2, v48
	s_nop 0
	v_add_f32_dpp v45, v45, v45 quad_perm:[1,0,3,2] row_mask:0xf bank_mask:0xf bound_ctrl:1
	v_addc_co_u32_e32 v47, vcc, 0, v49, vcc
	s_nop 0
	v_add_f32_dpp v45, v45, v45 quad_perm:[2,3,0,1] row_mask:0xf bank_mask:0xf bound_ctrl:1
	global_store_dword v[46:47], v4, off offset:2048 sc1
	v_mul_f32_e32 v4, v0, v51
	v_add_f32_dpp v45, v45, v45 row_half_mirror row_mask:0xf bank_mask:0xf bound_ctrl:1
	v_mul_f32_e32 v4, v10, v4
	v_mul_f32_e32 v53, v0, v53
	v_add_f32_dpp v45, v45, v45 row_mirror row_mask:0xf bank_mask:0xf bound_ctrl:1
	ds_bpermute_b32 v51, v39, v45
	v_mul_f32_e32 v53, v11, v53
	v_cvt_pk_bf16_f32 v4, v4, v53
	global_store_dword v[62:63], v4, off offset:256 sc1
	v_mul_f32_e32 v4, v0, v50
	s_waitcnt lgkmcnt(0)
	v_add_f32_e32 v45, v45, v51
	ds_bpermute_b32 v51, v41, v45
	v_mul_f32_e32 v0, v0, v52
	v_mul_f32_e32 v0, v13, v0
	v_mul_f32_e32 v4, v12, v4
	v_cvt_pk_bf16_f32 v0, v4, v0
	s_waitcnt lgkmcnt(0)
	v_add_f32_e32 v45, v45, v51
	v_fmamk_f32 v45, v45, 0x3b800000, v233
	v_mul_f32_e32 v50, 0x4b800000, v45
	v_cmp_gt_f32_e32 vcc, s94, v45
	global_store_dword v[62:63], v0, off offset:512 sc1
	v_lshl_add_u64 v[48:49], v[48:49], 0, s[62:63]
	v_cndmask_b32_e32 v45, v45, v50, vcc
	v_rsq_f32_e32 v45, v45
	s_nop 0
	v_mul_f32_e32 v0, 0x45800000, v45
	v_cndmask_b32_e32 v0, v45, v0, vcc
	v_mul_f32_e32 v4, v0, v65
	v_mul_f32_e32 v4, v14, v4
	v_mul_f32_e32 v45, v0, v67
	v_mul_f32_e32 v45, v15, v45
	v_cvt_pk_bf16_f32 v4, v4, v45
	global_store_dword v[46:47], v4, off offset:2816 sc1
	v_mul_f32_e32 v4, v0, v64
	v_mul_f32_e32 v0, v0, v66
	v_mul_f32_e32 v0, v17, v0
	v_mul_f32_e32 v4, v16, v4
	v_cvt_pk_bf16_f32 v0, v4, v0
	global_store_dword v[48:49], v0, off offset:256 sc1
	s_and_b64 exec, exec, s[36:37]
	s_cbranch_execz .LBB0_152
	v_lshlrev_b32_e32 v4, 16, v59
	v_lshlrev_b32_e32 v0, 16, v56
	v_mul_f32_e32 v46, v7, v4
	v_mul_f32_e32 v4, v3, v4
	v_ashrrev_i32_e32 v45, 31, v44
	v_fma_f32 v46, v3, v0, -v46
	v_fmac_f32_e32 v4, v7, v0
	v_bfe_u32 v47, v46, 16, 1
	v_lshlrev_b64 v[44:45], 7, v[44:45]
	v_bfe_u32 v0, v4, 16, 1
	v_add3_u32 v46, v46, v47, s10
	v_lshl_add_u64 v[44:45], v[24:25], 0, v[44:45]
	v_add3_u32 v0, v4, v0, s10
	global_store_short_d16_hi v[44:45], v46, off sc1
	global_store_short_d16_hi v[44:45], v0, off offset:64 sc1
	s_branch .LBB0_152

; DI bf16x8 pack8(const float* a) { u32x4 w = {cvtpk(a[0], a[1]), cvtpk(a[2], a[3]), cvtpk(a[4], a[5]), cvtpk(a[6], a[7])}; return *reinterpret_cast<bf16x8*>(&w); }
; DI int tid_() { int t = threadIdx.x; asm volatile("" : "+v"(t)); return t; }
; DI int bid_() { int b = blockIdx.x; asm volatile("" : "+s"(b)); return b; }
; DI void phase_norm(const float* x, const float* g, u16* out) {
;   const int wid = tid_() >> 6, lane = tid_() & 63;
;   for (int row = bid_() * 8 + wid; row < TG; row += gridDim.x * 8) {
;     const float* xr = x + (size_t)row * 1024;
;     float4 v[4]; float ss = 0.f;
; #pragma unroll
;     for (int i = 0; i < 2; ++i) for (int h = 0; h < 2; ++h) { float4 t = *reinterpret_cast<const float4*>(xr + i * 512 + lane * 8 + h * 4); v[2 * i + h] = t;
;       ss += t.x * t.x + t.y * t.y + t.z * t.z + t.w * t.w; }
;     ss = wave_sum_l(ss, lane);
;     const float r = rsqrtf(ss * (1.f / 1024.f) + EPS);
; #pragma unroll
;     for (int i = 0; i < 2; ++i) { const float4 g0 = *reinterpret_cast<const float4*>(g + i * 512 + lane * 8), g1 = *reinterpret_cast<const float4*>(g + i * 512 + lane * 8 + 4);
;       float a[8] = {v[2 * i].x * r * g0.x, v[2 * i].y * r * g0.y, v[2 * i].z * r * g0.z, v[2 * i].w * r * g0.w,
;                     v[2 * i + 1].x * r * g1.x, v[2 * i + 1].y * r * g1.y, v[2 * i + 1].z * r * g1.z, v[2 * i + 1].w * r * g1.w};
;       *reinterpret_cast<bf16x8*>(out + (size_t)row * 1024 + i * 512 + lane * 8) = pack8(a); }
;   }
; }
.LBB0_181:
	v_ashrrev_i32_e32 v1, 31, v0
	v_lshlrev_b64 v[10:11], 12, v[0:1]
	v_lshl_add_u64 v[22:23], v[2:3], 0, v[10:11]
	global_load_dwordx4 v[10:13], v[22:23], off
	global_load_dwordx4 v[14:17], v[22:23], off offset:16
	global_load_dwordx4 v[18:21], v[22:23], off offset:2048
	s_nop 0
	global_load_dwordx4 v[22:25], v[22:23], off offset:2064
	s_nop 0
	global_load_dwordx4 v[26:29], v[4:5], off
	global_load_dwordx4 v[30:33], v[4:5], off offset:16
	s_waitcnt vmcnt(5)
	v_pk_mul_f32 v[38:39], v[10:11], v[10:11]
	s_waitcnt vmcnt(4)
	v_pk_mul_f32 v[40:41], v[14:15], v[14:15]
	v_pk_mul_f32 v[34:35], v[12:13], v[12:13]
	v_pk_mul_f32 v[36:37], v[16:17], v[16:17]
	s_waitcnt vmcnt(3)
	v_pk_mul_f32 v[46:47], v[18:19], v[18:19]
	s_waitcnt vmcnt(2)
	v_pk_mul_f32 v[48:49], v[22:23], v[22:23]
	v_mov_b32_e32 v50, v38
	v_mov_b32_e32 v51, v40
	v_mov_b32_e32 v40, v39
	v_pk_mul_f32 v[42:43], v[20:21], v[20:21]
	v_pk_mul_f32 v[44:45], v[24:25], v[24:25]
	v_mov_b32_e32 v38, v34
	v_mov_b32_e32 v39, v36
	v_mov_b32_e32 v36, v35
	v_mov_b32_e32 v34, v46
	v_mov_b32_e32 v35, v48
	v_mov_b32_e32 v48, v47
	v_pk_add_f32 v[40:41], v[50:51], v[40:41]
	v_mov_b32_e32 v46, v42
	v_mov_b32_e32 v47, v44
	v_pk_add_f32 v[34:35], v[34:35], v[48:49]
	v_pk_add_f32 v[38:39], v[40:41], v[38:39]
	v_mov_b32_e32 v44, v43
	v_pk_add_f32 v[34:35], v[34:35], v[46:47]
	v_pk_add_f32 v[36:37], v[38:39], v[36:37]
	v_pk_add_f32 v[34:35], v[34:35], v[44:45]
	v_add_f32_e32 v36, v36, v37
	v_add_f32_e32 v34, v36, v34
	v_add_f32_e32 v34, v34, v35
	s_nop 1
	v_add_f32_dpp v34, v34, v34 quad_perm:[1,0,3,2] row_mask:0xf bank_mask:0xf bound_ctrl:1
	s_nop 1
	v_add_f32_dpp v34, v34, v34 quad_perm:[2,3,0,1] row_mask:0xf bank_mask:0xf bound_ctrl:1
	s_nop 1
	v_add_f32_dpp v34, v34, v34 row_half_mirror row_mask:0xf bank_mask:0xf bound_ctrl:1
	s_nop 1
	v_add_f32_dpp v34, v34, v34 row_mirror row_mask:0xf bank_mask:0xf bound_ctrl:1
	ds_bpermute_b32 v35, v8, v34
	s_waitcnt lgkmcnt(0)
	v_add_f32_e32 v34, v34, v35
	ds_bpermute_b32 v35, v9, v34
	s_waitcnt lgkmcnt(0)
	v_add_f32_e32 v34, v34, v35
	v_fmamk_f32 v34, v34, 0x3a800000, v233
	v_mul_f32_e32 v35, 0x4b800000, v34
	v_cmp_gt_f32_e32 vcc, s94, v34
	s_nop 1
	v_cndmask_b32_e32 v34, v34, v35, vcc
	v_rsq_f32_e32 v36, v34
	v_lshlrev_b64 v[34:35], 11, v[0:1]
	v_lshl_add_u64 v[34:35], v[6:7], 0, v[34:35]
	v_add_u32_e32 v0, s99, v0
	v_mul_f32_e32 v1, 0x45800000, v36
	v_cndmask_b32_e32 v1, v36, v1, vcc
	v_mul_f32_e32 v10, v10, v1
	v_mul_f32_e32 v11, v11, v1
	v_mul_f32_e32 v12, v12, v1
	v_mul_f32_e32 v13, v13, v1
	v_mul_f32_e32 v14, v14, v1
	v_mul_f32_e32 v15, v15, v1
	v_mul_f32_e32 v16, v16, v1
	v_mul_f32_e32 v17, v17, v1
	s_waitcnt vmcnt(1)
	v_mul_f32_e32 v10, v26, v10
	v_mul_f32_e32 v11, v27, v11
	v_mul_f32_e32 v12, v28, v12
	v_mul_f32_e32 v13, v29, v13
	s_waitcnt vmcnt(0)
	v_mul_f32_e32 v14, v30, v14
	v_mul_f32_e32 v15, v31, v15
	v_mul_f32_e32 v16, v32, v16
	v_mul_f32_e32 v17, v33, v17
	v_cvt_pk_bf16_f32 v10, v10, v11
	v_cvt_pk_bf16_f32 v11, v12, v13
	v_cvt_pk_bf16_f32 v12, v14, v15
	v_cvt_pk_bf16_f32 v13, v16, v17
	global_store_dwordx4 v[34:35], v[10:13], off sc1
	global_load_dwordx4 v[10:13], v[4:5], off offset:2048
	s_nop 0
	global_load_dwordx4 v[14:17], v[4:5], off offset:2064
	v_cmp_lt_i32_e32 vcc, s78, v0
	v_mul_f32_e32 v18, v18, v1
	v_mul_f32_e32 v19, v19, v1
	v_mul_f32_e32 v20, v20, v1
	v_mul_f32_e32 v21, v21, v1
	v_mul_f32_e32 v22, v22, v1
	v_mul_f32_e32 v23, v23, v1
	v_mul_f32_e32 v24, v24, v1
	v_mul_f32_e32 v1, v25, v1
	s_or_b64 s[12:13], vcc, s[12:13]
	s_waitcnt vmcnt(1)
	v_mul_f32_e32 v10, v18, v10
	v_mul_f32_e32 v11, v19, v11
	v_mul_f32_e32 v12, v20, v12
	v_mul_f32_e32 v13, v21, v13
	s_waitcnt vmcnt(0)
	v_mul_f32_e32 v14, v22, v14
	v_mul_f32_e32 v15, v23, v15
	v_mul_f32_e32 v16, v24, v16
	v_mul_f32_e32 v1, v1, v17
	v_cvt_pk_bf16_f32 v10, v10, v11
	v_cvt_pk_bf16_f32 v11, v12, v13
	v_cvt_pk_bf16_f32 v12, v14, v15
	v_cvt_pk_bf16_f32 v13, v16, v1
	global_store_dwordx4 v[34:35], v[10:13], off offset:1024 sc1
	s_andn2_b64 exec, exec, s[12:13]
	s_cbranch_execnz .LBB0_181

; DI uint2 pack4(float a, float b, float c, float d) { return make_uint2(cvtpk(a, b), cvtpk(c, d)); }
; #define WAIT_L(n) asm volatile("s_waitcnt lgkmcnt(" #n ")":::"memory")
; #define BAR __builtin_amdgcn_s_barrier()
; #define WAIT_L(n) asm volatile("s_waitcnt lgkmcnt(" #n ")":::"memory")
; #define BAR __builtin_amdgcn_s_barrier()
; DI void gemm8_run(const GemmJob& ja, const GemmJob& jb, char* lds) {
;     ...
;               float v0 = acc[ai][bj][m][n][0], v1 = acc[ai][bj][m][n][1], v2 = acc[ai][bj][m][n][2], v3 = acc[ai][bj][m][n][3];
;               if (r2) { v0 = fmaxf(v0, 0.f); v1 = fmaxf(v1, 0.f); v2 = fmaxf(v2, 0.f); v3 = fmaxf(v3, 0.f); v0 *= v0; v1 *= v1; v2 *= v2; v3 *= v3; }
;               *reinterpret_cast<uint2*>(cst + (wr * 64 + m * 16 + fr) * 528 + (bj * 128 + wc * 32 + n * 16 + fq * 4) * 2) = pack4(v0, v1, v2, v3); } } }
;         WAIT_L(0); BAR;
;         u16* Cb = J.C + (size_t)(brow + ai * 128) * J.ldc + bcol;
; #pragma unroll
;         for (int it = 0; it < 8; ++it) { const int idx = it * 512 + tid; const int r = idx >> 5, c16 = idx & 31;
;           *reinterpret_cast<bf16x8*>(Cb + (size_t)r * J.ldc + c16 * 8) = *reinterpret_cast<const bf16x8*>(cst + r * 528 + c16 * 16); }
;         WAIT_L(0); BAR;
.LBB0_190:
	v_cvt_pk_bf16_f32 v0, v0, v1
	v_cvt_pk_bf16_f32 v1, v2, v3
	ds_write_b64 v126, v[0:1] offset:25632
	v_mov_b32_e32 v0, s95
	v_mul_hi_u32_u24_e32 v1, s6, v0
	v_mul_u32_u24_e32 v0, s6, v0
	s_waitcnt lgkmcnt(0)
	s_barrier
	v_lshl_add_u64 v[4:5], v[0:1], 1, v[68:69]
	ds_read_b128 v[0:3], v89
	v_lshl_add_u64 v[6:7], v[78:79], 1, v[4:5]
	s_waitcnt lgkmcnt(0)
	global_store_dwordx4 v[6:7], v[0:3], off sc1
	ds_read_b128 v[0:3], v87
	v_lshl_add_u64 v[6:7], v[80:81], 1, v[4:5]
	s_waitcnt lgkmcnt(0)
	global_store_dwordx4 v[6:7], v[0:3], off sc1
	ds_read_b128 v[0:3], v85
	v_lshl_add_u64 v[6:7], v[72:73], 1, v[4:5]
	s_waitcnt lgkmcnt(0)
	global_store_dwordx4 v[6:7], v[0:3], off sc1
	ds_read_b128 v[0:3], v83
	v_lshl_add_u64 v[6:7], v[76:77], 1, v[4:5]
	s_waitcnt lgkmcnt(0)
	global_store_dwordx4 v[6:7], v[0:3], off sc1
	ds_read_b128 v[0:3], v82
	v_lshl_add_u64 v[6:7], v[64:65], 1, v[4:5]
	s_waitcnt lgkmcnt(0)
	global_store_dwordx4 v[6:7], v[0:3], off sc1
	ds_read_b128 v[0:3], v84
	v_lshl_add_u64 v[6:7], v[74:75], 1, v[4:5]
	s_waitcnt lgkmcnt(0)
	global_store_dwordx4 v[6:7], v[0:3], off sc1
	ds_read_b128 v[0:3], v86
	v_lshl_add_u64 v[6:7], v[70:71], 1, v[4:5]
	v_lshl_add_u64 v[4:5], v[66:67], 1, v[4:5]
	s_waitcnt lgkmcnt(0)
	global_store_dwordx4 v[6:7], v[0:3], off sc1
	ds_read_b128 v[0:3], v88
	s_waitcnt lgkmcnt(0)
	global_store_dwordx4 v[4:5], v[0:3], off sc1
	s_waitcnt lgkmcnt(0)
	s_barrier

; #define WAIT_L(n) asm volatile("s_waitcnt lgkmcnt(" #n ")":::"memory")
; #define BAR __builtin_amdgcn_s_barrier()
; #define WAIT_L(n) asm volatile("s_waitcnt lgkmcnt(" #n ")":::"memory")
; #define BAR __builtin_amdgcn_s_barrier()
; DI void gemm8_run(const GemmJob& ja, const GemmJob& jb, char* lds) {
;     ...
;       for (int ai = 0; ai < 2; ++ai) {
; #pragma unroll
;         for (int bj = 0; bj < 2; ++bj) {
; #pragma unroll
;           for (int m = 0; m < 4; ++m) {
; #pragma unroll
;             for (int n = 0; n < 2; ++n)
;               *reinterpret_cast<f32x4v*>(lds + (wr * 64 + m * 16 + fr) * 1040 + (bj * 128 + wc * 32 + n * 16 + fq * 4) * 4) = acc[ai][bj][m][n]; } }
;         WAIT_L(0); BAR;
;         const size_t gbase = (size_t)(brow + ai * 128) * 1024 + bcol;
; #pragma unroll
;         for (int hb = 0; hb < 2; ++hb) {
;           float4 xv[8]; f32x4v cv[8];
; #pragma unroll
;           for (int it = 0; it < 8; ++it) { const int idx = (hb * 8 + it) * 512 + tid; const int r = idx >> 6, c4 = idx & 63;
;             xv[it] = *reinterpret_cast<const float4*>(J.xin + gbase + (size_t)r * 1024 + c4 * 4);
;             cv[it] = *reinterpret_cast<const f32x4v*>(lds + r * 1040 + c4 * 16); }
; #pragma unroll
;           for (int it = 0; it < 8; ++it) { const int idx = (hb * 8 + it) * 512 + tid; const int r = idx >> 6, c4 = idx & 63;
;             float4 o_; o_.x = xv[it].x + cv[it][0]; o_.y = xv[it].y + cv[it][1]; o_.z = xv[it].z + cv[it][2]; o_.w = xv[it].w + cv[it][3];
;             *reinterpret_cast<float4*>(J.xout + gbase + (size_t)r * 1024 + c4 * 4) = o_; } }
;         WAIT_L(0); BAR;
;       }
.LBB0_216:
	v_mov_b32_e32 v157, v232
	s_lshl_b32 s80, s96, 10
	v_and_b32_e32 v96, 15, v157
	v_lshrrev_b32_e32 v130, 2, v157
	v_and_or_b32 v130, v130, s65, v96
	v_lshlrev_b32_e32 v96, 1, v157
	v_and_b32_e32 v131, 0x180, v96
	v_and_b32_e32 v96, 48, v157
	v_add_u32_e32 v132, 16, v96
	v_mul_lo_u32 v130, v130, s0
	v_add3_u32 v246, v132, v131, v130
	v_add_u32_e32 v130, 0x200, v157
	v_ashrrev_i32_e32 v182, 6, v130
	v_add_u32_e32 v130, 0x400, v157
	v_ashrrev_i32_e32 v192, 6, v130
	v_add_u32_e32 v130, 0x600, v157
	v_ashrrev_i32_e32 v194, 6, v130
	v_add_u32_e32 v130, 0x800, v157
	v_ashrrev_i32_e32 v206, 6, v130
	v_add_u32_e32 v130, 0xa00, v157
	v_ashrrev_i32_e32 v208, 6, v130
	v_add_u32_e32 v130, 0xc00, v157
	v_lshlrev_b32_e32 v96, 4, v157
	s_add_u32 s78, s12, s80
	v_ashrrev_i32_e32 v234, 6, v130
	v_add_u32_e32 v130, 0xe00, v157
	v_and_b32_e32 v96, 0x3f0, v96
	s_addc_u32 s79, s13, 0
	v_ashrrev_i32_e32 v228, 6, v130
	v_lshl_add_u64 v[180:181], s[44:45], 0, v[96:97]
	s_lshl_b64 s[78:79], s[78:79], 2
	v_ashrrev_i32_e32 v229, 31, v228
	v_lshl_add_u64 v[154:155], v[180:181], 0, s[78:79]
	v_lshlrev_b64 v[172:173], 12, v[228:229]
	ds_write_b128 v246, v[126:129]
	ds_write_b128 v246, v[122:125] offset:64
	ds_write_b128 v246, v[118:121] offset:16640
	ds_write_b128 v246, v[114:117] offset:16704
	ds_write_b128 v246, v[110:113] offset:33280
	ds_write_b128 v246, v[106:109] offset:33344
	ds_write_b128 v246, v[102:105] offset:49920
	ds_write_b128 v246, v[98:101] offset:49984
	ds_write_b128 v246, v[92:95] offset:512
	ds_write_b128 v246, v[88:91] offset:576
	ds_write_b128 v246, v[84:87] offset:17152
	ds_write_b128 v246, v[80:83] offset:17216
	ds_write_b128 v246, v[76:79] offset:33792
	ds_write_b128 v246, v[72:75] offset:33856
	ds_write_b128 v246, v[68:71] offset:50432
	ds_write_b128 v246, v[64:67] offset:50496
	v_lshl_add_u64 v[130:131], v[154:155], 0, v[172:173]
	s_waitcnt lgkmcnt(0)
	s_barrier
	v_ashrrev_i32_e32 v170, 6, v157
	global_load_dwordx4 v[130:133], v[130:131], off
	v_ashrrev_i32_e32 v171, 31, v170
	v_ashrrev_i32_e32 v183, 31, v182
	v_lshlrev_b64 v[162:163], 12, v[170:171]
	v_lshlrev_b64 v[164:165], 12, v[182:183]
	v_ashrrev_i32_e32 v193, 31, v192
	v_ashrrev_i32_e32 v235, 31, v234
	v_ashrrev_i32_e32 v209, 31, v208
	v_ashrrev_i32_e32 v207, 31, v206
	v_ashrrev_i32_e32 v195, 31, v194
	v_lshlrev_b64 v[178:179], 12, v[234:235]
	v_lshlrev_b64 v[184:185], 12, v[208:209]
	v_lshlrev_b64 v[186:187], 12, v[206:207]
	v_lshlrev_b64 v[188:189], 12, v[194:195]
	v_lshlrev_b64 v[190:191], 12, v[192:193]
	v_lshl_add_u64 v[158:159], v[154:155], 0, v[164:165]
	v_lshl_add_u64 v[166:167], v[154:155], 0, v[162:163]
	v_lshl_add_u64 v[134:135], v[154:155], 0, v[178:179]
	v_lshl_add_u64 v[138:139], v[154:155], 0, v[184:185]
	v_lshl_add_u64 v[142:143], v[154:155], 0, v[186:187]
	v_lshl_add_u64 v[146:147], v[154:155], 0, v[188:189]
	v_lshl_add_u64 v[150:151], v[154:155], 0, v[190:191]
	global_load_dwordx4 v[158:161], v[158:159], off
	v_readlane_b32 vcc_lo, v255, 21
	global_load_dwordx4 v[166:169], v[166:167], off
	v_readlane_b32 vcc_hi, v255, 22
	global_load_dwordx4 v[134:137], v[134:135], off
	v_add_u32_e32 v156, 16, v96
	global_load_dwordx4 v[138:141], v[138:139], off
	v_lshl_add_u64 v[196:197], vcc, 0, v[96:97]
	global_load_dwordx4 v[142:145], v[142:143], off
	v_lshl_add_u64 v[210:211], v[196:197], 0, s[78:79]
	global_load_dwordx4 v[146:149], v[146:147], off
	v_mad_u64_u32 v[198:199], s[78:79], v192, s0, v[156:157]
	global_load_dwordx4 v[150:153], v[150:151], off
	v_mad_u64_u32 v[192:193], s[78:79], v206, s0, v[156:157]
	v_mad_u64_u32 v[206:207], s[78:79], v228, s0, v[156:157]
	ds_read_b128 v[228:231], v206
	v_mad_u64_u32 v[202:203], s[78:79], v170, s0, v[156:157]
	v_mad_u64_u32 v[204:205], s[78:79], v182, s0, v[156:157]
	ds_read_b128 v[174:177], v202
	ds_read_b128 v[212:215], v204
	v_mad_u64_u32 v[200:201], s[78:79], v194, s0, v[156:157]
	v_mad_u64_u32 v[194:195], s[78:79], v208, s0, v[156:157]
	v_mad_u64_u32 v[208:209], s[78:79], v234, s0, v[156:157]
	ds_read_b128 v[216:219], v198
	ds_read_b128 v[220:223], v200
	ds_read_b128 v[224:227], v192
	ds_read_b128 v[248:251], v208
	v_lshl_add_u64 v[170:171], v[210:211], 0, v[162:163]
	v_add_u32_e32 v96, 0x1e00, v157
	v_lshl_add_u64 v[182:183], v[210:211], 0, v[164:165]
	v_lshl_add_u64 v[234:235], v[210:211], 0, v[190:191]
	s_bitset1_b32 s80, 17
	s_waitcnt vmcnt(0) lgkmcnt(0)
	v_pk_add_f32 v[130:131], v[130:131], v[228:229]
	v_pk_add_f32 v[132:133], v[132:133], v[230:231]
	ds_read_b128 v[228:231], v194
	v_pk_add_f32 v[158:159], v[158:159], v[212:213]
	v_pk_add_f32 v[160:161], v[160:161], v[214:215]
	v_pk_add_f32 v[166:167], v[166:167], v[174:175]
	v_pk_add_f32 v[168:169], v[168:169], v[176:177]
	v_pk_add_f32 v[134:135], v[134:135], v[248:249]
	v_pk_add_f32 v[136:137], v[136:137], v[250:251]
	s_waitcnt lgkmcnt(0)
; #define WAIT_L(n) asm volatile("s_waitcnt lgkmcnt(" #n ")":::"memory")
; #define BAR __builtin_amdgcn_s_barrier()
; #define WAIT_L(n) asm volatile("s_waitcnt lgkmcnt(" #n ")":::"memory")
; #define BAR __builtin_amdgcn_s_barrier()
; DI void gemm8_run(const GemmJob& ja, const GemmJob& jb, char* lds) {
;     ...
; #pragma unroll
;         for (int hb = 0; hb < 2; ++hb) {
;           float4 xv[8]; f32x4v cv[8];
; #pragma unroll
;           for (int it = 0; it < 8; ++it) { const int idx = (hb * 8 + it) * 512 + tid; const int r = idx >> 6, c4 = idx & 63;
;             xv[it] = *reinterpret_cast<const float4*>(J.xin + gbase + (size_t)r * 1024 + c4 * 4);
;             cv[it] = *reinterpret_cast<const f32x4v*>(lds + r * 1040 + c4 * 16); }
; #pragma unroll
;           for (int it = 0; it < 8; ++it) { const int idx = (hb * 8 + it) * 512 + tid; const int r = idx >> 6, c4 = idx & 63;
;             float4 o_; o_.x = xv[it].x + cv[it][0]; o_.y = xv[it].y + cv[it][1]; o_.z = xv[it].z + cv[it][2]; o_.w = xv[it].w + cv[it][3];
;             *reinterpret_cast<float4*>(J.xout + gbase + (size_t)r * 1024 + c4 * 4) = o_; } }
;         WAIT_L(0); BAR;
;       }
	v_pk_add_f32 v[138:139], v[138:139], v[228:229]
	v_pk_add_f32 v[140:141], v[140:141], v[230:231]
	v_lshl_add_u64 v[228:229], v[210:211], 0, v[188:189]
	v_lshl_add_u64 v[230:231], v[210:211], 0, v[186:187]
	v_pk_add_f32 v[142:143], v[142:143], v[224:225]
	v_pk_add_f32 v[144:145], v[144:145], v[226:227]
	v_lshl_add_u64 v[224:225], v[210:211], 0, v[184:185]
	v_lshl_add_u64 v[226:227], v[210:211], 0, v[178:179]
	v_pk_add_f32 v[146:147], v[146:147], v[220:221]
	v_pk_add_f32 v[148:149], v[148:149], v[222:223]
	v_lshl_add_u64 v[220:221], v[210:211], 0, v[172:173]
	v_pk_add_f32 v[150:151], v[150:151], v[216:217]
	v_pk_add_f32 v[152:153], v[152:153], v[218:219]
	global_store_dwordx4 v[170:171], v[166:169], off sc1
	global_store_dwordx4 v[182:183], v[158:161], off sc1
	global_store_dwordx4 v[234:235], v[150:153], off sc1
	global_store_dwordx4 v[228:229], v[146:149], off sc1
	global_store_dwordx4 v[230:231], v[142:145], off sc1
	global_store_dwordx4 v[224:225], v[138:141], off sc1
	global_store_dwordx4 v[226:227], v[134:137], off sc1
	global_store_dwordx4 v[220:221], v[130:133], off sc1
	v_ashrrev_i32_e32 v158, 6, v96
	v_add_u32_e32 v96, 0x1c00, v157
	v_ashrrev_i32_e32 v160, 6, v96
	v_add_u32_e32 v96, 0x1a00, v157
	v_ashrrev_i32_e32 v218, 6, v96
	v_add_u32_e32 v96, 0x1800, v157
	v_ashrrev_i32_e32 v220, 6, v96
	v_add_u32_e32 v96, 0x1600, v157
	v_ashrrev_i32_e32 v222, 6, v96
	v_add_u32_e32 v96, 0x1400, v157
	v_ashrrev_i32_e32 v224, 6, v96
	v_add_u32_e32 v96, 0x1000, v157
	v_add_u32_e32 v157, 0x1200, v157
	v_ashrrev_i32_e32 v159, 31, v158
	v_ashrrev_i32_e32 v230, 6, v157
	v_lshlrev_b64 v[166:167], 12, v[158:159]
	v_ashrrev_i32_e32 v231, 31, v230
	v_lshl_add_u64 v[130:131], v[154:155], 0, v[166:167]
	v_ashrrev_i32_e32 v161, 31, v160
	v_lshlrev_b64 v[212:213], 12, v[230:231]
	global_load_dwordx4 v[134:137], v[130:131], off
	v_lshlrev_b64 v[168:169], 12, v[160:161]
	v_lshl_add_u64 v[216:217], v[154:155], 0, v[212:213]
	global_load_dwordx4 v[248:251], v[216:217], off
	v_lshl_add_u64 v[130:131], v[154:155], 0, v[168:169]
	global_load_dwordx4 v[138:141], v[130:131], off
	v_ashrrev_i32_e32 v219, 31, v218
	v_lshlrev_b64 v[170:171], 12, v[218:219]
	v_lshl_add_u64 v[130:131], v[154:155], 0, v[170:171]
	v_ashrrev_i32_e32 v221, 31, v220
	global_load_dwordx4 v[142:145], v[130:131], off
	v_lshlrev_b64 v[174:175], 12, v[220:221]
	v_lshl_add_u64 v[130:131], v[154:155], 0, v[174:175]
	global_load_dwordx4 v[146:149], v[130:131], off
	v_ashrrev_i32_e32 v223, 31, v222
	v_lshlrev_b64 v[176:177], 12, v[222:223]
	v_lshl_add_u64 v[130:131], v[154:155], 0, v[176:177]
	v_ashrrev_i32_e32 v225, 31, v224
	global_load_dwordx4 v[150:153], v[130:131], off
	v_lshlrev_b64 v[182:183], 12, v[224:225]
	v_lshl_add_u64 v[130:131], v[154:155], 0, v[182:183]
	global_load_dwordx4 v[130:133], v[130:131], off
	v_mad_u64_u32 v[214:215], s[78:79], v158, s0, v[156:157]
	ds_read_b128 v[226:229], v214
	v_mad_u64_u32 v[216:217], s[78:79], v160, s0, v[156:157]
	ds_read_b128 v[158:161], v216
	v_mad_u64_u32 v[218:219], s[78:79], v218, s0, v[156:157]
	v_mad_u64_u32 v[220:221], s[78:79], v220, s0, v[156:157]
	v_mad_u64_u32 v[222:223], s[78:79], v222, s0, v[156:157]
	v_mad_u64_u32 v[224:225], s[78:79], v224, s0, v[156:157]
	v_ashrrev_i32_e32 v234, 6, v96
	v_ashrrev_i32_e32 v235, 31, v234
	s_waitcnt vmcnt(6) lgkmcnt(1)
	v_pk_add_f32 v[134:135], v[134:135], v[226:227]
	v_pk_add_f32 v[136:137], v[136:137], v[228:229]
	ds_read_b128 v[226:229], v218
	s_waitcnt vmcnt(4) lgkmcnt(1)
	v_pk_add_f32 v[138:139], v[138:139], v[158:159]
	v_pk_add_f32 v[140:141], v[140:141], v[160:161]
	ds_read_b128 v[158:161], v220
	s_waitcnt vmcnt(3) lgkmcnt(1)
	v_pk_add_f32 v[142:143], v[142:143], v[226:227]
	v_pk_add_f32 v[144:145], v[144:145], v[228:229]
	ds_read_b128 v[226:229], v222
	s_waitcnt vmcnt(2) lgkmcnt(1)
	v_pk_add_f32 v[146:147], v[146:147], v[158:159]
	v_pk_add_f32 v[148:149], v[148:149], v[160:161]
	ds_read_b128 v[158:161], v224
	s_waitcnt vmcnt(1) lgkmcnt(1)
	v_pk_add_f32 v[150:151], v[150:151], v[226:227]
	v_lshlrev_b64 v[226:227], 12, v[234:235]
	v_lshl_add_u64 v[154:155], v[154:155], 0, v[226:227]
	s_waitcnt vmcnt(0) lgkmcnt(0)
	v_pk_add_f32 v[130:131], v[130:131], v[158:159]
	v_pk_add_f32 v[132:133], v[132:133], v[160:161]
	global_load_dwordx4 v[158:161], v[154:155], off
	v_pk_add_f32 v[152:153], v[152:153], v[228:229]
	v_mad_u64_u32 v[228:229], s[78:79], v230, s0, v[156:157]
	ds_read_b128 v[238:241], v228
	v_mad_u64_u32 v[230:231], s[78:79], v234, s0, v[156:157]
	s_add_u32 s78, s12, s80
	s_addc_u32 s79, s13, 0
	s_waitcnt lgkmcnt(0)
	v_pk_add_f32 v[154:155], v[248:249], v[238:239]
	v_pk_add_f32 v[156:157], v[250:251], v[240:241]
	ds_read_b128 v[238:241], v230
	v_lshl_add_u64 v[234:235], v[210:211], 0, v[226:227]
	s_lshl_b64 s[78:79], s[78:79], 2
	v_lshl_add_u64 v[248:249], v[210:211], 0, v[176:177]
	v_lshl_add_u64 v[180:181], v[180:181], 0, s[78:79]
	s_waitcnt vmcnt(0) lgkmcnt(0)
	v_pk_add_f32 v[158:159], v[158:159], v[238:239]
	v_pk_add_f32 v[160:161], v[160:161], v[240:241]
	v_lshl_add_u64 v[238:239], v[210:211], 0, v[212:213]
	v_lshl_add_u64 v[240:241], v[210:211], 0, v[182:183]
	global_store_dwordx4 v[234:235], v[158:161], off sc1
	v_lshl_add_u64 v[234:235], v[210:211], 0, v[168:169]
	s_nop 0
	v_lshl_add_u64 v[158:159], v[210:211], 0, v[174:175]
	v_lshl_add_u64 v[160:161], v[210:211], 0, v[170:171]
	v_lshl_add_u64 v[210:211], v[210:211], 0, v[166:167]
	global_store_dwordx4 v[238:239], v[154:157], off sc1
	global_store_dwordx4 v[240:241], v[130:133], off sc1
	global_store_dwordx4 v[248:249], v[150:153], off sc1
	global_store_dwordx4 v[158:159], v[146:149], off sc1
	global_store_dwordx4 v[160:161], v[142:145], off sc1
	global_store_dwordx4 v[234:235], v[138:141], off sc1
	global_store_dwordx4 v[210:211], v[134:137], off sc1
	s_waitcnt lgkmcnt(0)
	s_barrier
; #define WAIT_L(n) asm volatile("s_waitcnt lgkmcnt(" #n ")":::"memory")
; #define BAR __builtin_amdgcn_s_barrier()
; #define WAIT_L(n) asm volatile("s_waitcnt lgkmcnt(" #n ")":::"memory")
; #define BAR __builtin_amdgcn_s_barrier()
; DI void gemm8_run(const GemmJob& ja, const GemmJob& jb, char* lds) {
;     ...
;       for (int ai = 0; ai < 2; ++ai) {
; #pragma unroll
;         for (int bj = 0; bj < 2; ++bj) {
; #pragma unroll
;           for (int m = 0; m < 4; ++m) {
; #pragma unroll
;             for (int n = 0; n < 2; ++n)
;               *reinterpret_cast<f32x4v*>(lds + (wr * 64 + m * 16 + fr) * 1040 + (bj * 128 + wc * 32 + n * 16 + fq * 4) * 4) = acc[ai][bj][m][n]; } }
;         WAIT_L(0); BAR;
;         const size_t gbase = (size_t)(brow + ai * 128) * 1024 + bcol;
; #pragma unroll
;         for (int hb = 0; hb < 2; ++hb) {
;           float4 xv[8]; f32x4v cv[8];
; #pragma unroll
;           for (int it = 0; it < 8; ++it) { const int idx = (hb * 8 + it) * 512 + tid; const int r = idx >> 6, c4 = idx & 63;
;             xv[it] = *reinterpret_cast<const float4*>(J.xin + gbase + (size_t)r * 1024 + c4 * 4);
;             cv[it] = *reinterpret_cast<const f32x4v*>(lds + r * 1040 + c4 * 16); }
; #pragma unroll
;           for (int it = 0; it < 8; ++it) { const int idx = (hb * 8 + it) * 512 + tid; const int r = idx >> 6, c4 = idx & 63;
;             float4 o_; o_.x = xv[it].x + cv[it][0]; o_.y = xv[it].y + cv[it][1]; o_.z = xv[it].z + cv[it][2]; o_.w = xv[it].w + cv[it][3];
;             *reinterpret_cast<float4*>(J.xout + gbase + (size_t)r * 1024 + c4 * 4) = o_; } }
;         WAIT_L(0); BAR;
	ds_write_b128 v246, v[60:63]
	ds_write_b128 v246, v[56:59] offset:64
	ds_write_b128 v246, v[52:55] offset:16640
	ds_write_b128 v246, v[48:51] offset:16704
	ds_write_b128 v246, v[44:47] offset:33280
	ds_write_b128 v246, v[40:43] offset:33344
	ds_write_b128 v246, v[36:39] offset:49920
	ds_write_b128 v246, v[32:35] offset:49984
	ds_write_b128 v246, v[28:31] offset:512
	ds_write_b128 v246, v[24:27] offset:576
	ds_write_b128 v246, v[20:23] offset:17152
	ds_write_b128 v246, v[16:19] offset:17216
	ds_write_b128 v246, v[12:15] offset:33792
	ds_write_b128 v246, v[8:11] offset:33856
	ds_write_b128 v246, v[4:7] offset:50432
	ds_write_b128 v246, v[0:3] offset:50496
	v_lshl_add_u64 v[130:131], v[180:181], 0, v[172:173]
	v_lshl_add_u64 v[134:135], v[180:181], 0, v[178:179]
	s_waitcnt lgkmcnt(0)
	s_barrier
	global_load_dwordx4 v[130:133], v[130:131], off
	v_lshl_add_u64 v[154:155], v[180:181], 0, v[164:165]
	global_load_dwordx4 v[134:137], v[134:135], off
	v_lshl_add_u64 v[158:159], v[180:181], 0, v[162:163]
	v_lshl_add_u64 v[138:139], v[180:181], 0, v[184:185]
	v_lshl_add_u64 v[142:143], v[180:181], 0, v[186:187]
	v_lshl_add_u64 v[146:147], v[180:181], 0, v[188:189]
	v_lshl_add_u64 v[150:151], v[180:181], 0, v[190:191]
	global_load_dwordx4 v[154:157], v[154:155], off
	ds_read_b128 v[238:241], v206
	global_load_dwordx4 v[158:161], v[158:159], off
	v_lshl_add_u64 v[210:211], v[196:197], 0, s[78:79]
	global_load_dwordx4 v[138:141], v[138:139], off
	v_lshl_add_u64 v[162:163], v[210:211], 0, v[162:163]
	global_load_dwordx4 v[142:145], v[142:143], off
	v_lshl_add_u64 v[164:165], v[210:211], 0, v[164:165]
	global_load_dwordx4 v[146:149], v[146:147], off
	v_lshl_add_u64 v[190:191], v[210:211], 0, v[190:191]
	global_load_dwordx4 v[150:153], v[150:151], off
	ds_read_b128 v[206:209], v208
	ds_read_b128 v[248:251], v202
	ds_read_b128 v[202:205], v204
	v_lshl_add_u64 v[188:189], v[210:211], 0, v[188:189]
	v_lshl_add_u64 v[186:187], v[210:211], 0, v[186:187]
	v_lshl_add_u64 v[184:185], v[210:211], 0, v[184:185]
	v_lshl_add_u64 v[178:179], v[210:211], 0, v[178:179]
	v_lshl_add_u64 v[172:173], v[210:211], 0, v[172:173]
	s_waitcnt vmcnt(7) lgkmcnt(3)
	v_pk_add_f32 v[130:131], v[130:131], v[238:239]
	v_pk_add_f32 v[132:133], v[132:133], v[240:241]
	ds_read_b128 v[196:199], v198
	ds_read_b128 v[238:241], v200
	s_waitcnt vmcnt(6) lgkmcnt(4)
	v_pk_add_f32 v[134:135], v[134:135], v[206:207]
	v_pk_add_f32 v[136:137], v[136:137], v[208:209]
	ds_read_b128 v[206:209], v192
	ds_read_b128 v[192:195], v194
	s_waitcnt vmcnt(5) lgkmcnt(4)
	v_pk_add_f32 v[154:155], v[154:155], v[202:203]
	v_pk_add_f32 v[156:157], v[156:157], v[204:205]
	s_waitcnt vmcnt(4)
	v_pk_add_f32 v[158:159], v[158:159], v[248:249]
	v_pk_add_f32 v[160:161], v[160:161], v[250:251]
	s_waitcnt vmcnt(3) lgkmcnt(0)
	v_pk_add_f32 v[138:139], v[138:139], v[192:193]
	v_pk_add_f32 v[140:141], v[140:141], v[194:195]
	s_waitcnt vmcnt(2)
	v_pk_add_f32 v[142:143], v[142:143], v[206:207]
	v_pk_add_f32 v[144:145], v[144:145], v[208:209]
	s_waitcnt vmcnt(1)
	v_pk_add_f32 v[146:147], v[146:147], v[238:239]
	v_pk_add_f32 v[148:149], v[148:149], v[240:241]
	s_waitcnt vmcnt(0)
	v_pk_add_f32 v[150:151], v[150:151], v[196:197]
	v_pk_add_f32 v[152:153], v[152:153], v[198:199]
	global_store_dwordx4 v[162:163], v[158:161], off sc1
	global_store_dwordx4 v[164:165], v[154:157], off sc1
	global_store_dwordx4 v[190:191], v[150:153], off sc1
	global_store_dwordx4 v[188:189], v[146:149], off sc1
	global_store_dwordx4 v[186:187], v[142:145], off sc1
	global_store_dwordx4 v[184:185], v[138:141], off sc1
	global_store_dwordx4 v[178:179], v[134:137], off sc1
	global_store_dwordx4 v[172:173], v[130:133], off sc1
	v_lshl_add_u64 v[154:155], v[180:181], 0, v[212:213]
	v_lshl_add_u64 v[158:159], v[180:181], 0, v[226:227]
	v_lshl_add_u64 v[130:131], v[180:181], 0, v[166:167]
	v_lshl_add_u64 v[134:135], v[180:181], 0, v[168:169]
	v_lshl_add_u64 v[138:139], v[180:181], 0, v[170:171]
	v_lshl_add_u64 v[142:143], v[180:181], 0, v[174:175]
	v_lshl_add_u64 v[146:147], v[180:181], 0, v[176:177]
	v_lshl_add_u64 v[150:151], v[180:181], 0, v[182:183]
	global_load_dwordx4 v[154:157], v[154:155], off
	v_lshl_add_u64 v[172:173], v[210:211], 0, v[226:227]
	global_load_dwordx4 v[158:161], v[158:159], off
	v_lshl_add_u64 v[208:209], v[210:211], 0, v[212:213]
	global_load_dwordx4 v[130:133], v[130:131], off
	v_lshl_add_u64 v[182:183], v[210:211], 0, v[182:183]
	global_load_dwordx4 v[134:137], v[134:135], off
	v_lshl_add_u64 v[176:177], v[210:211], 0, v[176:177]
	global_load_dwordx4 v[138:141], v[138:139], off
	v_lshl_add_u64 v[174:175], v[210:211], 0, v[174:175]
	global_load_dwordx4 v[142:145], v[142:143], off
	v_lshl_add_u64 v[170:171], v[210:211], 0, v[170:171]
	global_load_dwordx4 v[146:149], v[146:147], off
	v_lshl_add_u64 v[168:169], v[210:211], 0, v[168:169]
	global_load_dwordx4 v[150:153], v[150:151], off
	ds_read_b128 v[162:165], v230
	ds_read_b128 v[178:181], v228
	ds_read_b128 v[184:187], v224
	ds_read_b128 v[188:191], v222
	ds_read_b128 v[192:195], v220
	ds_read_b128 v[196:199], v218
	ds_read_b128 v[200:203], v216
	ds_read_b128 v[204:207], v214
	v_lshl_add_u64 v[166:167], v[210:211], 0, v[166:167]
	s_waitcnt vmcnt(7) lgkmcnt(6)
	v_pk_add_f32 v[154:155], v[154:155], v[178:179]
	v_pk_add_f32 v[156:157], v[156:157], v[180:181]
	s_waitcnt vmcnt(6)
	v_pk_add_f32 v[158:159], v[158:159], v[162:163]
	v_pk_add_f32 v[160:161], v[160:161], v[164:165]
	s_waitcnt vmcnt(5) lgkmcnt(0)
	v_pk_add_f32 v[130:131], v[130:131], v[204:205]
	v_pk_add_f32 v[132:133], v[132:133], v[206:207]
	s_waitcnt vmcnt(4)
	v_pk_add_f32 v[134:135], v[134:135], v[200:201]
	v_pk_add_f32 v[136:137], v[136:137], v[202:203]
	s_waitcnt vmcnt(3)
	v_pk_add_f32 v[138:139], v[138:139], v[196:197]
	v_pk_add_f32 v[140:141], v[140:141], v[198:199]
	s_waitcnt vmcnt(2)
	v_pk_add_f32 v[142:143], v[142:143], v[192:193]
	v_pk_add_f32 v[144:145], v[144:145], v[194:195]
	s_waitcnt vmcnt(1)
	v_pk_add_f32 v[146:147], v[146:147], v[188:189]
	v_pk_add_f32 v[148:149], v[148:149], v[190:191]
	s_waitcnt vmcnt(0)
	v_pk_add_f32 v[150:151], v[150:151], v[184:185]
	v_pk_add_f32 v[152:153], v[152:153], v[186:187]
	global_store_dwordx4 v[172:173], v[158:161], off sc1
	global_store_dwordx4 v[208:209], v[154:157], off sc1
	global_store_dwordx4 v[182:183], v[150:153], off sc1
	global_store_dwordx4 v[176:177], v[146:149], off sc1
	global_store_dwordx4 v[174:175], v[142:145], off sc1
	global_store_dwordx4 v[170:171], v[138:141], off sc1
	global_store_dwordx4 v[168:169], v[134:137], off sc1
	global_store_dwordx4 v[166:167], v[130:133], off sc1
	s_waitcnt lgkmcnt(0)
	s_barrier

; DI float bf2f(short b) { return __uint_as_float(((unsigned)(unsigned short)b) << 16); }
; DI bf16x8 pack8(const float* a) { u32x4 w = {cvtpk(a[0], a[1]), cvtpk(a[2], a[3]), cvtpk(a[4], a[5]), cvtpk(a[6], a[7])}; return *reinterpret_cast<bf16x8*>(&w); }
; DI float sigm(float x) { return __builtin_amdgcn_rcpf(1.f + __builtin_amdgcn_exp2f(-1.4426950408889634f * x)); }
; DI void gemm8_run(const GemmJob& ja, const GemmJob& jb, char* lds) {
;     ...
;           for (int it = 0; it < 4; ++it) { const int idx = (hb * 4 + it) * 512 + tid; const int r = idx >> 5, c16 = idx & 31; const size_t grow = (size_t)(brow + ai * 128 + r);
;             av[it] = *reinterpret_cast<const bf16x8*>(lds + r * 528 + c16 * 16);
;             gv[it] = ld8(J.gsrc + grow * INP + bcol + c16 * 8);
;             if (gb) ov[it] = ld8(J.C + grow * 1024 + bcol + c16 * 8); else ov[it] = av[it]; }
; #pragma unroll
;           for (int it = 0; it < 4; ++it) { const int idx = (hb * 4 + it) * 512 + tid; const int r = idx >> 5, c16 = idx & 31; const size_t grow = (size_t)(brow + ai * 128 + r);
;             const float4 b0 = *reinterpret_cast<const float4*>(J.bias + bcol + c16 * 8), b1 = *reinterpret_cast<const float4*>(J.bias + bcol + c16 * 8 + 4);
;             const float bb[8] = {b0.x, b0.y, b0.z, b0.w, b1.x, b1.y, b1.z, b1.w};
;             float o8[8];
; #pragma unroll
;             for (int j = 0; j < 8; ++j) { const float g = sigm(bf2f(gv[it][j]) + bb[j]); o8[j] = (gb ? bf2f(ov[it][j]) : 0.f) + bf2f(av[it][j]) * g; }
;             *reinterpret_cast<bf16x8*>(J.C + grow * 1024 + bcol + c16 * 8) = pack8(o8); } }
.LBB0_229:
	s_lshl_b64 s[78:79], s[12:13], 2
	v_lshlrev_b32_e32 v96, 3, v179
	s_add_u32 s78, s48, s78
	v_and_b32_e32 v96, 0xf8, v96
	s_addc_u32 s79, s49, s79
	v_lshlrev_b32_e32 v178, 2, v96
	global_load_dwordx4 v[194:197], v178, s[78:79]
	global_load_dwordx4 v[198:201], v178, s[78:79] offset:16
	s_waitcnt vmcnt(5)
	v_lshlrev_b32_e32 v182, 16, v174
	v_lshlrev_b32_e32 v183, 16, v175
	v_lshlrev_b32_e32 v96, 1, v96
	v_lshlrev_b32_e32 v203, 16, v170
	v_and_b32_e32 v214, 0xffff0000, v170
	v_and_b32_e32 v170, 0xffff0000, v174
	v_lshlrev_b32_e32 v174, 16, v171
	v_and_b32_e32 v216, 0xffff0000, v171
	v_and_b32_e32 v171, 0xffff0000, v175
	v_lshlrev_b32_e32 v175, 16, v172
	v_and_b32_e32 v172, 0xffff0000, v172
	v_lshlrev_b32_e32 v219, 16, v173
	v_and_b32_e32 v173, 0xffff0000, v173
	v_cndmask_b32_e64 v222, 0, v182, s[40:41]
	v_cndmask_b32_e64 v224, 0, v183, s[40:41]
	v_lshl_add_u64 v[182:183], s[80:81], 0, v[96:97]
	v_cndmask_b32_e64 v223, 0, v170, s[40:41]
	v_cndmask_b32_e64 v225, 0, v171, s[40:41]
	v_lshl_add_u64 v[170:171], v[182:183], 0, v[192:193]
	v_lshlrev_b32_e32 v217, 16, v176
	v_and_b32_e32 v176, 0xffff0000, v176
	v_lshlrev_b32_e32 v220, 16, v177
	v_and_b32_e32 v177, 0xffff0000, v177
	v_lshlrev_b32_e32 v204, 16, v166
	v_and_b32_e32 v166, 0xffff0000, v166
	v_lshlrev_b32_e32 v215, 16, v167
	v_and_b32_e32 v167, 0xffff0000, v167
	v_lshlrev_b32_e32 v218, 16, v168
	v_and_b32_e32 v168, 0xffff0000, v168
	v_lshlrev_b32_e32 v221, 16, v169
	v_and_b32_e32 v169, 0xffff0000, v169
	v_cndmask_b32_e64 v217, 0, v217, s[40:41]
	v_cndmask_b32_e64 v176, 0, v176, s[40:41]
	v_cndmask_b32_e64 v220, 0, v220, s[40:41]
	v_cndmask_b32_e64 v177, 0, v177, s[40:41]
	s_and_b64 vcc, exec, s[42:43]
	s_waitcnt vmcnt(1)
	v_add_f32_e32 v96, v194, v203
	v_add_f32_e32 v192, v195, v214
	v_add_f32_e32 v174, v196, v174
	v_add_f32_e32 v193, v197, v216
	s_waitcnt vmcnt(0)
	v_add_f32_e32 v175, v198, v175
	v_add_f32_e32 v172, v199, v172
	v_add_f32_e32 v194, v200, v219
	v_add_f32_e32 v173, v201, v173
	v_mul_f32_e32 v96, 0xbfb8aa3b, v96
	v_mul_f32_e32 v192, 0xbfb8aa3b, v192
	v_mul_f32_e32 v174, 0xbfb8aa3b, v174
	v_mul_f32_e32 v193, 0xbfb8aa3b, v193
	v_mul_f32_e32 v175, 0xbfb8aa3b, v175
	v_mul_f32_e32 v172, 0xbfb8aa3b, v172
	v_mul_f32_e32 v194, 0xbfb8aa3b, v194
	v_mul_f32_e32 v173, 0xbfb8aa3b, v173
	v_exp_f32_e32 v96, v96
	v_exp_f32_e32 v192, v192
	v_exp_f32_e32 v174, v174
	v_exp_f32_e32 v193, v193
	v_exp_f32_e32 v175, v175
	v_exp_f32_e32 v172, v172
	v_exp_f32_e32 v194, v194
	v_exp_f32_e32 v173, v173
	v_add_f32_e32 v96, 1.0, v96
	v_add_f32_e32 v192, 1.0, v192
	v_add_f32_e32 v174, 1.0, v174
	v_add_f32_e32 v193, 1.0, v193
	v_add_f32_e32 v175, 1.0, v175
	v_add_f32_e32 v172, 1.0, v172
	v_add_f32_e32 v194, 1.0, v194
	v_add_f32_e32 v173, 1.0, v173
	v_rcp_f32_e32 v96, v96
	v_rcp_f32_e32 v192, v192
	v_rcp_f32_e32 v174, v174
	v_rcp_f32_e32 v193, v193
	v_rcp_f32_e32 v175, v175
	v_rcp_f32_e32 v172, v172
	v_rcp_f32_e32 v194, v194
	v_rcp_f32_e32 v173, v173
	v_fmac_f32_e32 v222, v96, v204
	v_fmac_f32_e32 v223, v192, v166
	v_fmac_f32_e32 v224, v174, v215
	v_fmac_f32_e32 v225, v193, v167
	v_fmac_f32_e32 v217, v175, v218
	v_fmac_f32_e32 v176, v172, v168
	v_fmac_f32_e32 v220, v194, v221
	v_fmac_f32_e32 v177, v173, v169
	v_cvt_pk_bf16_f32 v166, v222, v223
	v_cvt_pk_bf16_f32 v167, v224, v225
	v_cvt_pk_bf16_f32 v168, v217, v176
	v_cvt_pk_bf16_f32 v169, v220, v177
	global_store_dwordx4 v[170:171], v[166:169], off sc1
	global_load_dwordx4 v[166:169], v178, s[78:79]
	s_nop 0
	global_load_dwordx4 v[170:173], v178, s[78:79] offset:16
	v_lshlrev_b32_e32 v96, 16, v158
	v_lshlrev_b32_e32 v174, 16, v162
	v_and_b32_e32 v176, 0xffff0000, v158
	v_and_b32_e32 v158, 0xffff0000, v162
	v_lshlrev_b32_e32 v162, 16, v159
	v_lshlrev_b32_e32 v177, 16, v163
	v_and_b32_e32 v193, 0xffff0000, v159
	v_and_b32_e32 v159, 0xffff0000, v163
	v_lshlrev_b32_e32 v163, 16, v160
	v_and_b32_e32 v160, 0xffff0000, v160
	v_lshlrev_b32_e32 v196, 16, v161
	v_and_b32_e32 v161, 0xffff0000, v161
	v_lshlrev_b32_e32 v194, 16, v164
	v_and_b32_e32 v164, 0xffff0000, v164
	v_lshlrev_b32_e32 v197, 16, v165
	v_and_b32_e32 v165, 0xffff0000, v165
	v_lshlrev_b32_e32 v175, 16, v154
	v_and_b32_e32 v154, 0xffff0000, v154
	v_lshlrev_b32_e32 v192, 16, v155
	v_and_b32_e32 v155, 0xffff0000, v155
	v_lshlrev_b32_e32 v195, 16, v156
	v_and_b32_e32 v156, 0xffff0000, v156
	v_lshlrev_b32_e32 v198, 16, v157
	v_and_b32_e32 v157, 0xffff0000, v157
	v_cndmask_b32_e64 v174, 0, v174, s[40:41]
	v_cndmask_b32_e64 v199, 0, v158, s[40:41]
	v_cndmask_b32_e64 v177, 0, v177, s[40:41]
	v_cndmask_b32_e64 v200, 0, v159, s[40:41]
	v_cndmask_b32_e64 v194, 0, v194, s[40:41]
	v_cndmask_b32_e64 v164, 0, v164, s[40:41]
	v_cndmask_b32_e64 v197, 0, v197, s[40:41]
	v_cndmask_b32_e64 v165, 0, v165, s[40:41]
	v_lshl_add_u64 v[158:159], v[182:183], 0, v[190:191]
	s_waitcnt vmcnt(1)
	v_add_f32_e32 v96, v166, v96
	v_add_f32_e32 v166, v167, v176
	v_add_f32_e32 v162, v168, v162
	v_add_f32_e32 v167, v169, v193
	s_waitcnt vmcnt(0)
; DI float bf2f(short b) { return __uint_as_float(((unsigned)(unsigned short)b) << 16); }
; DI bf16x8 pack8(const float* a) { u32x4 w = {cvtpk(a[0], a[1]), cvtpk(a[2], a[3]), cvtpk(a[4], a[5]), cvtpk(a[6], a[7])}; return *reinterpret_cast<bf16x8*>(&w); }
; DI float sigm(float x) { return __builtin_amdgcn_rcpf(1.f + __builtin_amdgcn_exp2f(-1.4426950408889634f * x)); }
; DI void gemm8_run(const GemmJob& ja, const GemmJob& jb, char* lds) {
;     ...
;           for (int it = 0; it < 4; ++it) { const int idx = (hb * 4 + it) * 512 + tid; const int r = idx >> 5, c16 = idx & 31; const size_t grow = (size_t)(brow + ai * 128 + r);
;             const float4 b0 = *reinterpret_cast<const float4*>(J.bias + bcol + c16 * 8), b1 = *reinterpret_cast<const float4*>(J.bias + bcol + c16 * 8 + 4);
;             const float bb[8] = {b0.x, b0.y, b0.z, b0.w, b1.x, b1.y, b1.z, b1.w};
;             float o8[8];
; #pragma unroll
;             for (int j = 0; j < 8; ++j) { const float g = sigm(bf2f(gv[it][j]) + bb[j]); o8[j] = (gb ? bf2f(ov[it][j]) : 0.f) + bf2f(av[it][j]) * g; }
;             *reinterpret_cast<bf16x8*>(J.C + grow * 1024 + bcol + c16 * 8) = pack8(o8); } }
	v_add_f32_e32 v163, v170, v163
	v_add_f32_e32 v160, v171, v160
	v_add_f32_e32 v168, v172, v196
	v_add_f32_e32 v161, v173, v161
	v_mul_f32_e32 v96, 0xbfb8aa3b, v96
	v_mul_f32_e32 v166, 0xbfb8aa3b, v166
	v_mul_f32_e32 v162, 0xbfb8aa3b, v162
	v_mul_f32_e32 v167, 0xbfb8aa3b, v167
	v_mul_f32_e32 v163, 0xbfb8aa3b, v163
	v_mul_f32_e32 v160, 0xbfb8aa3b, v160
	v_mul_f32_e32 v168, 0xbfb8aa3b, v168
	v_mul_f32_e32 v161, 0xbfb8aa3b, v161
	v_exp_f32_e32 v96, v96
	v_exp_f32_e32 v166, v166
	v_exp_f32_e32 v162, v162
	v_exp_f32_e32 v167, v167
	v_exp_f32_e32 v163, v163
	v_exp_f32_e32 v160, v160
	v_exp_f32_e32 v168, v168
	v_exp_f32_e32 v161, v161
	v_add_f32_e32 v96, 1.0, v96
	v_add_f32_e32 v166, 1.0, v166
	v_add_f32_e32 v162, 1.0, v162
	v_add_f32_e32 v167, 1.0, v167
	v_add_f32_e32 v163, 1.0, v163
	v_add_f32_e32 v160, 1.0, v160
	v_add_f32_e32 v168, 1.0, v168
	v_add_f32_e32 v161, 1.0, v161
	v_rcp_f32_e32 v96, v96
	v_rcp_f32_e32 v166, v166
	v_rcp_f32_e32 v162, v162
	v_rcp_f32_e32 v167, v167
	v_rcp_f32_e32 v163, v163
	v_rcp_f32_e32 v160, v160
	v_rcp_f32_e32 v168, v168
	v_rcp_f32_e32 v161, v161
	v_fmac_f32_e32 v174, v96, v175
	v_fmac_f32_e32 v199, v166, v154
	v_fmac_f32_e32 v177, v162, v192
	v_fmac_f32_e32 v200, v167, v155
	v_fmac_f32_e32 v194, v163, v195
	v_fmac_f32_e32 v164, v160, v156
	v_fmac_f32_e32 v197, v168, v198
	v_fmac_f32_e32 v165, v161, v157
	v_cvt_pk_bf16_f32 v154, v174, v199
	v_cvt_pk_bf16_f32 v155, v177, v200
	v_cvt_pk_bf16_f32 v156, v194, v164
	v_cvt_pk_bf16_f32 v157, v197, v165
	global_store_dwordx4 v[158:159], v[154:157], off sc1
	global_load_dwordx4 v[154:157], v178, s[78:79]
	s_nop 0
	global_load_dwordx4 v[158:161], v178, s[78:79] offset:16
	v_lshlrev_b32_e32 v96, 16, v146
	v_lshlrev_b32_e32 v162, 16, v150
	v_and_b32_e32 v164, 0xffff0000, v146
	v_and_b32_e32 v146, 0xffff0000, v150
	v_lshlrev_b32_e32 v150, 16, v147
	v_lshlrev_b32_e32 v165, 16, v151
	v_and_b32_e32 v167, 0xffff0000, v147
	v_and_b32_e32 v147, 0xffff0000, v151
	v_lshlrev_b32_e32 v151, 16, v148
	v_and_b32_e32 v148, 0xffff0000, v148
	v_lshlrev_b32_e32 v170, 16, v149
	v_and_b32_e32 v149, 0xffff0000, v149
	v_lshlrev_b32_e32 v168, 16, v152
	v_and_b32_e32 v152, 0xffff0000, v152
	v_lshlrev_b32_e32 v171, 16, v153
	v_and_b32_e32 v153, 0xffff0000, v153
	v_lshlrev_b32_e32 v163, 16, v142
	v_and_b32_e32 v142, 0xffff0000, v142
	v_lshlrev_b32_e32 v166, 16, v143
	v_and_b32_e32 v143, 0xffff0000, v143
	v_lshlrev_b32_e32 v169, 16, v144
	v_and_b32_e32 v144, 0xffff0000, v144
	v_lshlrev_b32_e32 v172, 16, v145
	v_and_b32_e32 v145, 0xffff0000, v145
	v_cndmask_b32_e64 v162, 0, v162, s[40:41]
	v_cndmask_b32_e64 v173, 0, v146, s[40:41]
	v_cndmask_b32_e64 v165, 0, v165, s[40:41]
	v_cndmask_b32_e64 v174, 0, v147, s[40:41]
	v_cndmask_b32_e64 v168, 0, v168, s[40:41]
	v_cndmask_b32_e64 v152, 0, v152, s[40:41]
	v_cndmask_b32_e64 v171, 0, v171, s[40:41]
	v_cndmask_b32_e64 v153, 0, v153, s[40:41]
	v_lshl_add_u64 v[146:147], v[182:183], 0, v[184:185]
	s_waitcnt vmcnt(1)
	v_add_f32_e32 v96, v154, v96
	v_add_f32_e32 v154, v155, v164
	v_add_f32_e32 v150, v156, v150
	v_add_f32_e32 v155, v157, v167
	s_waitcnt vmcnt(0)
; DI float bf2f(short b) { return __uint_as_float(((unsigned)(unsigned short)b) << 16); }
; DI bf16x8 pack8(const float* a) { u32x4 w = {cvtpk(a[0], a[1]), cvtpk(a[2], a[3]), cvtpk(a[4], a[5]), cvtpk(a[6], a[7])}; return *reinterpret_cast<bf16x8*>(&w); }
; DI float sigm(float x) { return __builtin_amdgcn_rcpf(1.f + __builtin_amdgcn_exp2f(-1.4426950408889634f * x)); }
; DI void gemm8_run(const GemmJob& ja, const GemmJob& jb, char* lds) {
;     ...
;           for (int it = 0; it < 4; ++it) { const int idx = (hb * 4 + it) * 512 + tid; const int r = idx >> 5, c16 = idx & 31; const size_t grow = (size_t)(brow + ai * 128 + r);
;             av[it] = *reinterpret_cast<const bf16x8*>(lds + r * 528 + c16 * 16);
;             gv[it] = ld8(J.gsrc + grow * INP + bcol + c16 * 8);
;             if (gb) ov[it] = ld8(J.C + grow * 1024 + bcol + c16 * 8); else ov[it] = av[it]; }
; #pragma unroll
;           for (int it = 0; it < 4; ++it) { const int idx = (hb * 4 + it) * 512 + tid; const int r = idx >> 5, c16 = idx & 31; const size_t grow = (size_t)(brow + ai * 128 + r);
;             const float4 b0 = *reinterpret_cast<const float4*>(J.bias + bcol + c16 * 8), b1 = *reinterpret_cast<const float4*>(J.bias + bcol + c16 * 8 + 4);
;             const float bb[8] = {b0.x, b0.y, b0.z, b0.w, b1.x, b1.y, b1.z, b1.w};
;             float o8[8];
; #pragma unroll
;             for (int j = 0; j < 8; ++j) { const float g = sigm(bf2f(gv[it][j]) + bb[j]); o8[j] = (gb ? bf2f(ov[it][j]) : 0.f) + bf2f(av[it][j]) * g; }
;             *reinterpret_cast<bf16x8*>(J.C + grow * 1024 + bcol + c16 * 8) = pack8(o8); } }
	v_add_f32_e32 v151, v158, v151
	v_add_f32_e32 v148, v159, v148
	v_add_f32_e32 v156, v160, v170
	v_add_f32_e32 v149, v161, v149
	v_mul_f32_e32 v96, 0xbfb8aa3b, v96
	v_mul_f32_e32 v154, 0xbfb8aa3b, v154
	v_mul_f32_e32 v150, 0xbfb8aa3b, v150
	v_mul_f32_e32 v155, 0xbfb8aa3b, v155
	v_mul_f32_e32 v151, 0xbfb8aa3b, v151
	v_mul_f32_e32 v148, 0xbfb8aa3b, v148
	v_mul_f32_e32 v156, 0xbfb8aa3b, v156
	v_mul_f32_e32 v149, 0xbfb8aa3b, v149
	v_exp_f32_e32 v96, v96
	v_exp_f32_e32 v154, v154
	v_exp_f32_e32 v150, v150
	v_exp_f32_e32 v155, v155
	v_exp_f32_e32 v151, v151
	v_exp_f32_e32 v148, v148
	v_exp_f32_e32 v156, v156
	v_exp_f32_e32 v149, v149
	v_add_f32_e32 v96, 1.0, v96
	v_add_f32_e32 v154, 1.0, v154
	v_add_f32_e32 v150, 1.0, v150
	v_add_f32_e32 v155, 1.0, v155
	v_add_f32_e32 v151, 1.0, v151
	v_add_f32_e32 v148, 1.0, v148
	v_add_f32_e32 v156, 1.0, v156
	v_add_f32_e32 v149, 1.0, v149
	v_rcp_f32_e32 v96, v96
	v_rcp_f32_e32 v154, v154
	v_rcp_f32_e32 v150, v150
	v_rcp_f32_e32 v155, v155
	v_rcp_f32_e32 v151, v151
	v_rcp_f32_e32 v148, v148
	v_rcp_f32_e32 v156, v156
	v_rcp_f32_e32 v149, v149
	v_fmac_f32_e32 v162, v96, v163
	v_fmac_f32_e32 v173, v154, v142
	v_fmac_f32_e32 v165, v150, v166
	v_fmac_f32_e32 v174, v155, v143
	v_fmac_f32_e32 v168, v151, v169
	v_fmac_f32_e32 v152, v148, v144
	v_fmac_f32_e32 v171, v156, v172
	v_fmac_f32_e32 v153, v149, v145
	v_cvt_pk_bf16_f32 v142, v162, v173
	v_cvt_pk_bf16_f32 v143, v165, v174
	v_cvt_pk_bf16_f32 v144, v168, v152
	v_cvt_pk_bf16_f32 v145, v171, v153
	global_store_dwordx4 v[146:147], v[142:145], off sc1
	global_load_dwordx4 v[142:145], v178, s[78:79]
	s_nop 0
	global_load_dwordx4 v[146:149], v178, s[78:79] offset:16
	v_lshlrev_b32_e32 v96, 16, v134
	v_lshlrev_b32_e32 v150, 16, v138
	v_and_b32_e32 v152, 0xffff0000, v134
	v_and_b32_e32 v134, 0xffff0000, v138
	v_lshlrev_b32_e32 v138, 16, v135
	v_and_b32_e32 v135, 0xffff0000, v135
	v_lshlrev_b32_e32 v155, 16, v136
	v_lshlrev_b32_e32 v156, 16, v140
	v_and_b32_e32 v158, 0xffff0000, v136
	v_and_b32_e32 v136, 0xffff0000, v140
	v_lshlrev_b32_e32 v140, 16, v137
	v_lshlrev_b32_e32 v159, 16, v141
	v_and_b32_e32 v161, 0xffff0000, v137
	v_and_b32_e32 v137, 0xffff0000, v141
	v_add_u32_e32 v141, 0x800, v179
	v_ashrrev_i32_e32 v203, 5, v141
	v_lshlrev_b32_e32 v153, 16, v139
	v_and_b32_e32 v139, 0xffff0000, v139
	v_lshlrev_b32_e32 v151, 16, v130
	v_and_b32_e32 v130, 0xffff0000, v130
	v_lshlrev_b32_e32 v154, 16, v131
	v_and_b32_e32 v131, 0xffff0000, v131
	v_cndmask_b32_e64 v150, 0, v150, s[40:41]
	v_cndmask_b32_e64 v162, 0, v134, s[40:41]
	v_cndmask_b32_e64 v153, 0, v153, s[40:41]
	v_cndmask_b32_e64 v139, 0, v139, s[40:41]
	v_lshlrev_b32_e32 v157, 16, v132
	v_and_b32_e32 v132, 0xffff0000, v132
	v_lshlrev_b32_e32 v160, 16, v133
	v_and_b32_e32 v133, 0xffff0000, v133
	v_cndmask_b32_e64 v156, 0, v156, s[40:41]
	v_cndmask_b32_e64 v163, 0, v136, s[40:41]
	v_cndmask_b32_e64 v159, 0, v159, s[40:41]
	v_cndmask_b32_e64 v164, 0, v137, s[40:41]
	v_add_u32_e32 v134, s96, v203
	v_lshl_add_u64 v[136:137], v[182:183], 0, v[180:181]
	s_waitcnt vmcnt(1)
	v_add_f32_e32 v96, v142, v96
	v_add_f32_e32 v141, v143, v152
	v_add_f32_e32 v138, v144, v138
	v_add_f32_e32 v135, v145, v135
	s_waitcnt vmcnt(0)
	v_add_f32_e32 v142, v146, v155
	v_add_f32_e32 v143, v147, v158
	v_add_f32_e32 v140, v148, v140
	v_add_f32_e32 v144, v149, v161
	v_mul_f32_e32 v96, 0xbfb8aa3b, v96
	v_mul_f32_e32 v141, 0xbfb8aa3b, v141
	v_mul_f32_e32 v138, 0xbfb8aa3b, v138
	v_mul_f32_e32 v135, 0xbfb8aa3b, v135
	v_mul_f32_e32 v142, 0xbfb8aa3b, v142
	v_mul_f32_e32 v143, 0xbfb8aa3b, v143
	v_mul_f32_e32 v140, 0xbfb8aa3b, v140
	v_mul_f32_e32 v144, 0xbfb8aa3b, v144
	v_exp_f32_e32 v96, v96
	v_exp_f32_e32 v141, v141
	v_exp_f32_e32 v138, v138
	v_exp_f32_e32 v135, v135
	v_exp_f32_e32 v142, v142
	v_exp_f32_e32 v143, v143
	v_exp_f32_e32 v140, v140
	v_exp_f32_e32 v144, v144
	v_add_f32_e32 v96, 1.0, v96
	v_add_f32_e32 v141, 1.0, v141
	v_add_f32_e32 v138, 1.0, v138
	v_add_f32_e32 v135, 1.0, v135
	v_add_f32_e32 v142, 1.0, v142
	v_add_f32_e32 v143, 1.0, v143
	v_add_f32_e32 v140, 1.0, v140
	v_add_f32_e32 v144, 1.0, v144
	v_rcp_f32_e32 v96, v96
	v_rcp_f32_e32 v141, v141
	v_rcp_f32_e32 v138, v138
	v_rcp_f32_e32 v135, v135
	v_rcp_f32_e32 v142, v142
	v_rcp_f32_e32 v143, v143
	v_rcp_f32_e32 v140, v140
	v_rcp_f32_e32 v144, v144
	v_fmac_f32_e32 v150, v96, v151
	v_fmac_f32_e32 v162, v141, v130
	v_fmac_f32_e32 v153, v138, v154
	v_fmac_f32_e32 v139, v135, v131
	v_cvt_pk_bf16_f32 v130, v150, v162
	v_cvt_pk_bf16_f32 v131, v153, v139
	v_fmac_f32_e32 v156, v142, v157
	v_fmac_f32_e32 v163, v143, v132
	v_fmac_f32_e32 v159, v140, v160
	v_fmac_f32_e32 v164, v144, v133
	v_cvt_pk_bf16_f32 v132, v156, v163
	v_cvt_pk_bf16_f32 v133, v159, v164
	global_store_dwordx4 v[136:137], v[130:133], off sc1
	v_mul_lo_u32 v96, v203, s11
	v_add_u32_e32 v204, v202, v96
	v_mad_i64_i32 v[130:131], s[80:81], v134, s33, v[186:187]
	global_load_dwordx4 v[174:177], v[130:131], off
	ds_read_b128 v[166:169], v204
	v_ashrrev_i32_e32 v135, 31, v134
	v_lshlrev_b64 v[196:197], 11, v[134:135]
	s_waitcnt lgkmcnt(0)
	v_mov_b64_e32 v[172:173], v[168:169]
	v_mov_b64_e32 v[170:171], v[166:167]
	s_cbranch_vccnz .LBB0_231
	v_lshl_add_u64 v[130:131], v[188:189], 0, v[196:197]
	global_load_dwordx4 v[170:173], v[130:131], off

; DI float bf2f(short b) { return __uint_as_float(((unsigned)(unsigned short)b) << 16); }
; DI bf16x8 pack8(const float* a) { u32x4 w = {cvtpk(a[0], a[1]), cvtpk(a[2], a[3]), cvtpk(a[4], a[5]), cvtpk(a[6], a[7])}; return *reinterpret_cast<bf16x8*>(&w); }
; DI float sigm(float x) { return __builtin_amdgcn_rcpf(1.f + __builtin_amdgcn_exp2f(-1.4426950408889634f * x)); }
; DI void gemm8_run(const GemmJob& ja, const GemmJob& jb, char* lds) {
;     ...
;           for (int it = 0; it < 4; ++it) { const int idx = (hb * 4 + it) * 512 + tid; const int r = idx >> 5, c16 = idx & 31; const size_t grow = (size_t)(brow + ai * 128 + r);
;             av[it] = *reinterpret_cast<const bf16x8*>(lds + r * 528 + c16 * 16);
;             gv[it] = ld8(J.gsrc + grow * INP + bcol + c16 * 8);
;             if (gb) ov[it] = ld8(J.C + grow * 1024 + bcol + c16 * 8); else ov[it] = av[it]; }
; #pragma unroll
;           for (int it = 0; it < 4; ++it) { const int idx = (hb * 4 + it) * 512 + tid; const int r = idx >> 5, c16 = idx & 31; const size_t grow = (size_t)(brow + ai * 128 + r);
;             const float4 b0 = *reinterpret_cast<const float4*>(J.bias + bcol + c16 * 8), b1 = *reinterpret_cast<const float4*>(J.bias + bcol + c16 * 8 + 4);
;             const float bb[8] = {b0.x, b0.y, b0.z, b0.w, b1.x, b1.y, b1.z, b1.w};
;             float o8[8];
; #pragma unroll
;             for (int j = 0; j < 8; ++j) { const float g = sigm(bf2f(gv[it][j]) + bb[j]); o8[j] = (gb ? bf2f(ov[it][j]) : 0.f) + bf2f(av[it][j]) * g; }
;             *reinterpret_cast<bf16x8*>(J.C + grow * 1024 + bcol + c16 * 8) = pack8(o8); } }
.LBB0_237:
	v_mov_b32_e32 v179, v97
	v_lshl_add_u64 v[184:185], s[78:79], 0, v[178:179]
	global_load_dwordx4 v[178:181], v[184:185], off offset:16
	global_load_dwordx4 v[214:217], v[184:185], off
	s_waitcnt vmcnt(5)
	v_lshlrev_b32_e32 v218, 16, v174
	v_and_b32_e32 v174, 0xffff0000, v174
	v_lshlrev_b32_e32 v219, 16, v166
	v_and_b32_e32 v166, 0xffff0000, v166
	s_and_b64 vcc, exec, s[42:43]
	s_waitcnt vmcnt(0)
	v_add_f32_e32 v174, v215, v174
	v_mul_f32_e32 v174, 0xbfb8aa3b, v174
	v_exp_f32_e32 v174, v174
	v_add_f32_e32 v214, v214, v218
	v_lshlrev_b32_e32 v218, 16, v170
	v_and_b32_e32 v170, 0xffff0000, v170
	v_add_f32_e32 v174, 1.0, v174
	v_rcp_f32_e32 v174, v174
	v_cndmask_b32_e64 v170, 0, v170, s[40:41]
	v_mul_f32_e32 v214, 0xbfb8aa3b, v214
	v_exp_f32_e32 v214, v214
	v_fmac_f32_e32 v170, v174, v166
	v_lshlrev_b32_e32 v166, 16, v175
	v_add_f32_e32 v166, v216, v166
	v_mul_f32_e32 v166, 0xbfb8aa3b, v166
	v_exp_f32_e32 v166, v166
	v_add_f32_e32 v214, 1.0, v214
	v_rcp_f32_e32 v214, v214
	v_cndmask_b32_e64 v218, 0, v218, s[40:41]
	v_add_f32_e32 v166, 1.0, v166
	v_rcp_f32_e32 v166, v166
	v_lshlrev_b32_e32 v174, 16, v171
	v_fmac_f32_e32 v218, v214, v219
	v_cndmask_b32_e64 v174, 0, v174, s[40:41]
	v_lshlrev_b32_e32 v214, 16, v167
	v_fmac_f32_e32 v174, v166, v214
	v_and_b32_e32 v166, 0xffff0000, v175
	v_add_f32_e32 v166, v217, v166
	v_mul_f32_e32 v166, 0xbfb8aa3b, v166
	v_exp_f32_e32 v166, v166
	v_and_b32_e32 v171, 0xffff0000, v171
	v_cndmask_b32_e64 v171, 0, v171, s[40:41]
	v_and_b32_e32 v167, 0xffff0000, v167
	v_add_f32_e32 v166, 1.0, v166
	v_rcp_f32_e32 v166, v166
	s_nop 0
	v_fmac_f32_e32 v171, v166, v167
	v_lshlrev_b32_e32 v166, 16, v176
	v_add_f32_e32 v166, v178, v166
	v_mul_f32_e32 v166, 0xbfb8aa3b, v166
	v_exp_f32_e32 v166, v166
	v_lshlrev_b32_e32 v167, 16, v172
	v_cndmask_b32_e64 v175, 0, v167, s[40:41]
	v_lshlrev_b32_e32 v167, 16, v168
	v_add_f32_e32 v166, 1.0, v166
	v_rcp_f32_e32 v166, v166
	s_nop 0
	v_fmac_f32_e32 v175, v166, v167
	v_and_b32_e32 v166, 0xffff0000, v176
	v_add_f32_e32 v166, v179, v166
	v_mul_f32_e32 v166, 0xbfb8aa3b, v166
	v_exp_f32_e32 v166, v166
	v_and_b32_e32 v167, 0xffff0000, v172
	v_cndmask_b32_e64 v172, 0, v167, s[40:41]
	v_and_b32_e32 v167, 0xffff0000, v168
	v_add_f32_e32 v166, 1.0, v166
	v_rcp_f32_e32 v166, v166
	s_nop 0
	v_fmac_f32_e32 v172, v166, v167
	v_lshlrev_b32_e32 v166, 16, v177
	v_add_f32_e32 v166, v180, v166
	v_mul_f32_e32 v166, 0xbfb8aa3b, v166
	v_exp_f32_e32 v166, v166
	v_lshlrev_b32_e32 v167, 16, v173
	v_cndmask_b32_e64 v176, 0, v167, s[40:41]
	v_lshlrev_b32_e32 v167, 16, v169
	v_add_f32_e32 v166, 1.0, v166
	v_rcp_f32_e32 v166, v166
	s_nop 0
	v_fmac_f32_e32 v176, v166, v167
	v_and_b32_e32 v166, 0xffff0000, v177
	v_add_f32_e32 v166, v181, v166
	v_mul_f32_e32 v166, 0xbfb8aa3b, v166
	v_exp_f32_e32 v166, v166
	v_and_b32_e32 v167, 0xffff0000, v173
	v_cndmask_b32_e64 v173, 0, v167, s[40:41]
	v_and_b32_e32 v167, 0xffff0000, v169
	v_add_f32_e32 v166, 1.0, v166
	v_rcp_f32_e32 v166, v166
	s_nop 0
	v_fmac_f32_e32 v173, v166, v167
	v_cvt_pk_bf16_f32 v166, v218, v170
	v_cvt_pk_bf16_f32 v167, v174, v171
	v_lshl_add_u64 v[170:171], v[182:183], 0, v[196:197]
	v_cvt_pk_bf16_f32 v168, v175, v172
	v_cvt_pk_bf16_f32 v169, v176, v173
	global_store_dwordx4 v[170:171], v[166:169], off sc1
	global_load_dwordx4 v[166:169], v[184:185], off offset:16
	s_nop 0
	global_load_dwordx4 v[170:173], v[184:185], off
	v_lshlrev_b32_e32 v174, 16, v162
	v_and_b32_e32 v162, 0xffff0000, v162
	v_lshlrev_b32_e32 v175, 16, v154
	v_and_b32_e32 v154, 0xffff0000, v154
	s_waitcnt vmcnt(0)
	v_add_f32_e32 v162, v171, v162
	v_mul_f32_e32 v162, 0xbfb8aa3b, v162
	v_exp_f32_e32 v162, v162
	v_add_f32_e32 v170, v170, v174
	v_lshlrev_b32_e32 v174, 16, v158
	v_and_b32_e32 v158, 0xffff0000, v158
	v_add_f32_e32 v162, 1.0, v162
	v_rcp_f32_e32 v162, v162
	v_cndmask_b32_e64 v158, 0, v158, s[40:41]
	v_mul_f32_e32 v170, 0xbfb8aa3b, v170
	v_exp_f32_e32 v170, v170
	v_fmac_f32_e32 v158, v162, v154
	v_lshlrev_b32_e32 v154, 16, v163
	v_add_f32_e32 v154, v172, v154
	v_mul_f32_e32 v154, 0xbfb8aa3b, v154
	v_exp_f32_e32 v154, v154
	v_add_f32_e32 v170, 1.0, v170
	v_rcp_f32_e32 v170, v170
	v_cndmask_b32_e64 v174, 0, v174, s[40:41]
	v_add_f32_e32 v154, 1.0, v154
	v_rcp_f32_e32 v154, v154
	v_lshlrev_b32_e32 v162, 16, v159
	v_fmac_f32_e32 v174, v170, v175
	v_cndmask_b32_e64 v162, 0, v162, s[40:41]
	v_lshlrev_b32_e32 v170, 16, v155
	v_fmac_f32_e32 v162, v154, v170
	v_and_b32_e32 v154, 0xffff0000, v163
	v_add_f32_e32 v154, v173, v154
	v_mul_f32_e32 v154, 0xbfb8aa3b, v154
	v_exp_f32_e32 v154, v154
	v_and_b32_e32 v159, 0xffff0000, v159
	v_cndmask_b32_e64 v159, 0, v159, s[40:41]
	v_and_b32_e32 v155, 0xffff0000, v155
	v_add_f32_e32 v154, 1.0, v154
	v_rcp_f32_e32 v154, v154
	s_nop 0
	v_fmac_f32_e32 v159, v154, v155
	v_lshlrev_b32_e32 v154, 16, v164
	v_add_f32_e32 v154, v166, v154
	v_mul_f32_e32 v154, 0xbfb8aa3b, v154
	v_exp_f32_e32 v154, v154
	v_lshlrev_b32_e32 v155, 16, v160
	v_cndmask_b32_e64 v163, 0, v155, s[40:41]
	v_lshlrev_b32_e32 v155, 16, v156
	v_add_f32_e32 v154, 1.0, v154
	v_rcp_f32_e32 v154, v154
	s_nop 0
	v_fmac_f32_e32 v163, v154, v155
	v_and_b32_e32 v154, 0xffff0000, v164
	v_add_f32_e32 v154, v167, v154
	v_mul_f32_e32 v154, 0xbfb8aa3b, v154
	v_exp_f32_e32 v154, v154
	v_and_b32_e32 v155, 0xffff0000, v160
	v_cndmask_b32_e64 v160, 0, v155, s[40:41]
	v_and_b32_e32 v155, 0xffff0000, v156
	v_add_f32_e32 v154, 1.0, v154
	v_rcp_f32_e32 v154, v154
	s_nop 0
	v_fmac_f32_e32 v160, v154, v155
	v_lshlrev_b32_e32 v154, 16, v165
	v_add_f32_e32 v154, v168, v154
	v_mul_f32_e32 v154, 0xbfb8aa3b, v154
	v_exp_f32_e32 v154, v154
	v_lshlrev_b32_e32 v155, 16, v161
	v_cndmask_b32_e64 v164, 0, v155, s[40:41]
	v_lshlrev_b32_e32 v155, 16, v157
	v_add_f32_e32 v154, 1.0, v154
	v_rcp_f32_e32 v154, v154
	s_nop 0
	v_fmac_f32_e32 v164, v154, v155
	v_and_b32_e32 v154, 0xffff0000, v165
	v_add_f32_e32 v154, v169, v154
	v_mul_f32_e32 v154, 0xbfb8aa3b, v154
	v_exp_f32_e32 v154, v154
	v_and_b32_e32 v155, 0xffff0000, v161
	v_cndmask_b32_e64 v161, 0, v155, s[40:41]
	v_and_b32_e32 v155, 0xffff0000, v157
	v_add_f32_e32 v154, 1.0, v154
	v_rcp_f32_e32 v154, v154
	s_nop 0
	v_fmac_f32_e32 v161, v154, v155
	v_cvt_pk_bf16_f32 v154, v174, v158
	v_cvt_pk_bf16_f32 v155, v162, v159
	v_lshl_add_u64 v[158:159], v[182:183], 0, v[194:195]
	v_cvt_pk_bf16_f32 v156, v163, v160
	v_cvt_pk_bf16_f32 v157, v164, v161
	global_store_dwordx4 v[158:159], v[154:157], off sc1
	global_load_dwordx4 v[154:157], v[184:185], off offset:16
	s_nop 0
	global_load_dwordx4 v[158:161], v[184:185], off
	v_lshlrev_b32_e32 v162, 16, v150
	v_and_b32_e32 v150, 0xffff0000, v150
	v_lshlrev_b32_e32 v163, 16, v142
	v_and_b32_e32 v142, 0xffff0000, v142
	s_waitcnt vmcnt(0)
; DI float bf2f(short b) { return __uint_as_float(((unsigned)(unsigned short)b) << 16); }
; DI bf16x8 pack8(const float* a) { u32x4 w = {cvtpk(a[0], a[1]), cvtpk(a[2], a[3]), cvtpk(a[4], a[5]), cvtpk(a[6], a[7])}; return *reinterpret_cast<bf16x8*>(&w); }
; DI float sigm(float x) { return __builtin_amdgcn_rcpf(1.f + __builtin_amdgcn_exp2f(-1.4426950408889634f * x)); }
; DI void gemm8_run(const GemmJob& ja, const GemmJob& jb, char* lds) {
;     ...
;           for (int it = 0; it < 4; ++it) { const int idx = (hb * 4 + it) * 512 + tid; const int r = idx >> 5, c16 = idx & 31; const size_t grow = (size_t)(brow + ai * 128 + r);
;             av[it] = *reinterpret_cast<const bf16x8*>(lds + r * 528 + c16 * 16);
;             gv[it] = ld8(J.gsrc + grow * INP + bcol + c16 * 8);
;             if (gb) ov[it] = ld8(J.C + grow * 1024 + bcol + c16 * 8); else ov[it] = av[it]; }
; #pragma unroll
;           for (int it = 0; it < 4; ++it) { const int idx = (hb * 4 + it) * 512 + tid; const int r = idx >> 5, c16 = idx & 31; const size_t grow = (size_t)(brow + ai * 128 + r);
;             const float4 b0 = *reinterpret_cast<const float4*>(J.bias + bcol + c16 * 8), b1 = *reinterpret_cast<const float4*>(J.bias + bcol + c16 * 8 + 4);
;             const float bb[8] = {b0.x, b0.y, b0.z, b0.w, b1.x, b1.y, b1.z, b1.w};
;             float o8[8];
; #pragma unroll
;             for (int j = 0; j < 8; ++j) { const float g = sigm(bf2f(gv[it][j]) + bb[j]); o8[j] = (gb ? bf2f(ov[it][j]) : 0.f) + bf2f(av[it][j]) * g; }
;             *reinterpret_cast<bf16x8*>(J.C + grow * 1024 + bcol + c16 * 8) = pack8(o8); } }
	v_add_f32_e32 v150, v159, v150
	v_mul_f32_e32 v150, 0xbfb8aa3b, v150
	v_exp_f32_e32 v150, v150
	v_add_f32_e32 v158, v158, v162
	v_lshlrev_b32_e32 v162, 16, v146
	v_and_b32_e32 v146, 0xffff0000, v146
	v_add_f32_e32 v150, 1.0, v150
	v_rcp_f32_e32 v150, v150
	v_cndmask_b32_e64 v146, 0, v146, s[40:41]
	v_mul_f32_e32 v158, 0xbfb8aa3b, v158
	v_exp_f32_e32 v158, v158
	v_fmac_f32_e32 v146, v150, v142
	v_lshlrev_b32_e32 v142, 16, v151
	v_add_f32_e32 v142, v160, v142
	v_mul_f32_e32 v142, 0xbfb8aa3b, v142
	v_exp_f32_e32 v142, v142
	v_add_f32_e32 v158, 1.0, v158
	v_rcp_f32_e32 v158, v158
	v_cndmask_b32_e64 v162, 0, v162, s[40:41]
	v_add_f32_e32 v142, 1.0, v142
	v_rcp_f32_e32 v142, v142
	v_lshlrev_b32_e32 v150, 16, v147
	v_fmac_f32_e32 v162, v158, v163
	v_cndmask_b32_e64 v150, 0, v150, s[40:41]
	v_lshlrev_b32_e32 v158, 16, v143
	v_fmac_f32_e32 v150, v142, v158
	v_and_b32_e32 v142, 0xffff0000, v151
	v_add_f32_e32 v142, v161, v142
	v_mul_f32_e32 v142, 0xbfb8aa3b, v142
	v_exp_f32_e32 v142, v142
	v_and_b32_e32 v147, 0xffff0000, v147
	v_cndmask_b32_e64 v147, 0, v147, s[40:41]
	v_and_b32_e32 v143, 0xffff0000, v143
	v_add_f32_e32 v142, 1.0, v142
	v_rcp_f32_e32 v142, v142
	s_nop 0
	v_fmac_f32_e32 v147, v142, v143
	v_lshlrev_b32_e32 v142, 16, v152
	v_add_f32_e32 v142, v154, v142
	v_mul_f32_e32 v142, 0xbfb8aa3b, v142
	v_exp_f32_e32 v142, v142
	v_lshlrev_b32_e32 v143, 16, v148
	v_cndmask_b32_e64 v151, 0, v143, s[40:41]
	v_lshlrev_b32_e32 v143, 16, v144
	v_add_f32_e32 v142, 1.0, v142
	v_rcp_f32_e32 v142, v142
	s_nop 0
	v_fmac_f32_e32 v151, v142, v143
	v_and_b32_e32 v142, 0xffff0000, v152
	v_add_f32_e32 v142, v155, v142
	v_mul_f32_e32 v142, 0xbfb8aa3b, v142
	v_exp_f32_e32 v142, v142
	v_and_b32_e32 v143, 0xffff0000, v148
	v_cndmask_b32_e64 v148, 0, v143, s[40:41]
	v_and_b32_e32 v143, 0xffff0000, v144
	v_add_f32_e32 v142, 1.0, v142
	v_rcp_f32_e32 v142, v142
	s_nop 0
	v_fmac_f32_e32 v148, v142, v143
	v_lshlrev_b32_e32 v142, 16, v153
	v_add_f32_e32 v142, v156, v142
	v_mul_f32_e32 v142, 0xbfb8aa3b, v142
	v_exp_f32_e32 v142, v142
	v_lshlrev_b32_e32 v143, 16, v149
	v_cndmask_b32_e64 v152, 0, v143, s[40:41]
	v_lshlrev_b32_e32 v143, 16, v145
	v_add_f32_e32 v142, 1.0, v142
	v_rcp_f32_e32 v142, v142
	s_nop 0
	v_fmac_f32_e32 v152, v142, v143
	v_and_b32_e32 v142, 0xffff0000, v153
	v_add_f32_e32 v142, v157, v142
	v_mul_f32_e32 v142, 0xbfb8aa3b, v142
	v_exp_f32_e32 v142, v142
	v_and_b32_e32 v143, 0xffff0000, v149
	v_cndmask_b32_e64 v149, 0, v143, s[40:41]
	v_and_b32_e32 v143, 0xffff0000, v145
	v_add_f32_e32 v142, 1.0, v142
	v_rcp_f32_e32 v142, v142
	s_nop 0
	v_fmac_f32_e32 v149, v142, v143
	v_cvt_pk_bf16_f32 v142, v162, v146
	v_cvt_pk_bf16_f32 v143, v150, v147
	v_lshl_add_u64 v[146:147], v[182:183], 0, v[192:193]
	v_cvt_pk_bf16_f32 v144, v151, v148
	v_cvt_pk_bf16_f32 v145, v152, v149
	global_store_dwordx4 v[146:147], v[142:145], off sc1
	global_load_dwordx4 v[142:145], v[184:185], off offset:16
	s_nop 0
	global_load_dwordx4 v[146:149], v[184:185], off
	v_lshlrev_b32_e32 v150, 16, v138
	v_and_b32_e32 v138, 0xffff0000, v138
	v_lshlrev_b32_e32 v151, 16, v130
	v_and_b32_e32 v130, 0xffff0000, v130
	s_waitcnt vmcnt(0)
	v_add_f32_e32 v138, v147, v138
	v_mul_f32_e32 v138, 0xbfb8aa3b, v138
	v_exp_f32_e32 v138, v138
	v_add_f32_e32 v146, v146, v150
	v_lshlrev_b32_e32 v150, 16, v134
	v_and_b32_e32 v134, 0xffff0000, v134
	v_add_f32_e32 v138, 1.0, v138
	v_rcp_f32_e32 v138, v138
	v_cndmask_b32_e64 v134, 0, v134, s[40:41]
	v_mul_f32_e32 v146, 0xbfb8aa3b, v146
	v_exp_f32_e32 v146, v146
	v_fmac_f32_e32 v134, v138, v130
	v_lshlrev_b32_e32 v130, 16, v139
	v_add_f32_e32 v130, v148, v130
	v_mul_f32_e32 v130, 0xbfb8aa3b, v130
	v_exp_f32_e32 v130, v130
	v_add_f32_e32 v146, 1.0, v146
	v_rcp_f32_e32 v146, v146
	v_cndmask_b32_e64 v150, 0, v150, s[40:41]
	v_add_f32_e32 v130, 1.0, v130
	v_rcp_f32_e32 v130, v130
	v_lshlrev_b32_e32 v138, 16, v135
	v_fmac_f32_e32 v150, v146, v151
	v_cndmask_b32_e64 v138, 0, v138, s[40:41]
	v_lshlrev_b32_e32 v146, 16, v131
	v_fmac_f32_e32 v138, v130, v146
	v_and_b32_e32 v130, 0xffff0000, v139
	v_add_f32_e32 v130, v149, v130
	v_mul_f32_e32 v130, 0xbfb8aa3b, v130
	v_exp_f32_e32 v130, v130
	v_and_b32_e32 v135, 0xffff0000, v135
	v_cndmask_b32_e64 v135, 0, v135, s[40:41]
	v_and_b32_e32 v131, 0xffff0000, v131
	v_add_f32_e32 v130, 1.0, v130
	v_rcp_f32_e32 v130, v130
	s_nop 0
	v_fmac_f32_e32 v135, v130, v131
	v_lshlrev_b32_e32 v130, 16, v140
	v_add_f32_e32 v130, v142, v130
	v_mul_f32_e32 v130, 0xbfb8aa3b, v130
	v_exp_f32_e32 v130, v130
	v_lshlrev_b32_e32 v131, 16, v136
	v_cndmask_b32_e64 v139, 0, v131, s[40:41]
	v_lshlrev_b32_e32 v131, 16, v132
	v_add_f32_e32 v130, 1.0, v130
	v_rcp_f32_e32 v130, v130
	s_nop 0
	v_fmac_f32_e32 v139, v130, v131
	v_and_b32_e32 v130, 0xffff0000, v140
	v_add_f32_e32 v130, v143, v130
	v_mul_f32_e32 v130, 0xbfb8aa3b, v130
	v_exp_f32_e32 v130, v130
	v_and_b32_e32 v131, 0xffff0000, v136
	v_cndmask_b32_e64 v136, 0, v131, s[40:41]
	v_and_b32_e32 v131, 0xffff0000, v132
	v_add_f32_e32 v130, 1.0, v130
	v_rcp_f32_e32 v130, v130
	s_nop 0
	v_fmac_f32_e32 v136, v130, v131
	v_lshlrev_b32_e32 v130, 16, v141
	v_add_f32_e32 v130, v144, v130
	v_mul_f32_e32 v130, 0xbfb8aa3b, v130
	v_exp_f32_e32 v130, v130
	v_lshlrev_b32_e32 v131, 16, v137
	v_cndmask_b32_e64 v140, 0, v131, s[40:41]
	v_lshlrev_b32_e32 v131, 16, v133
	v_add_f32_e32 v130, 1.0, v130
	v_rcp_f32_e32 v130, v130
	s_nop 0
	v_fmac_f32_e32 v140, v130, v131
	v_and_b32_e32 v130, 0xffff0000, v141
	v_add_f32_e32 v130, v145, v130
	v_mul_f32_e32 v130, 0xbfb8aa3b, v130
	v_exp_f32_e32 v130, v130
	v_and_b32_e32 v131, 0xffff0000, v137
	v_cndmask_b32_e64 v137, 0, v131, s[40:41]
	v_and_b32_e32 v131, 0xffff0000, v133
	v_add_f32_e32 v130, 1.0, v130
	v_rcp_f32_e32 v130, v130
	s_nop 0
	v_fmac_f32_e32 v137, v130, v131
	v_cvt_pk_bf16_f32 v130, v150, v134
	v_cvt_pk_bf16_f32 v131, v138, v135
	v_lshl_add_u64 v[134:135], v[182:183], 0, v[190:191]
	v_cvt_pk_bf16_f32 v132, v139, v136
	v_cvt_pk_bf16_f32 v133, v140, v137
	global_store_dwordx4 v[134:135], v[130:133], off sc1
	s_waitcnt lgkmcnt(0)
	s_barrier
; DI uint2 pack4(float a, float b, float c, float d) { return make_uint2(cvtpk(a, b), cvtpk(c, d)); }
; #define WAIT_L(n) asm volatile("s_waitcnt lgkmcnt(" #n ")":::"memory")
; #define BAR __builtin_amdgcn_s_barrier()
; #define WAIT_L(n) asm volatile("s_waitcnt lgkmcnt(" #n ")":::"memory")
; #define BAR __builtin_amdgcn_s_barrier()
; DI void gemm8_run(const GemmJob& ja, const GemmJob& jb, char* lds) {
;     ...
;       for (int ai = 0; ai < 2; ++ai) {
; #pragma unroll
;         for (int bj = 0; bj < 2; ++bj) {
; #pragma unroll
;           for (int m = 0; m < 4; ++m) {
; #pragma unroll
;             for (int n = 0; n < 2; ++n)
;               *reinterpret_cast<uint2*>(lds + (wr * 64 + m * 16 + fr) * 528 + (bj * 128 + wc * 32 + n * 16 + fq * 4) * 2) =
;                 pack4(acc[ai][bj][m][n][0], acc[ai][bj][m][n][1], acc[ai][bj][m][n][2], acc[ai][bj][m][n][3]); } }
;         WAIT_L(0); BAR;
	s_nop 0
	v_cvt_pk_bf16_f32 v130, v60, v61
	v_cvt_pk_bf16_f32 v131, v62, v63
	ds_write_b64 v205, v[130:131]
	v_cvt_pk_bf16_f32 v130, v56, v57
	v_cvt_pk_bf16_f32 v131, v58, v59
	ds_write_b64 v205, v[130:131] offset:32
	v_cvt_pk_bf16_f32 v130, v52, v53
	v_cvt_pk_bf16_f32 v131, v54, v55
	ds_write_b64 v205, v[130:131] offset:8448
	v_cvt_pk_bf16_f32 v130, v48, v49
	v_cvt_pk_bf16_f32 v131, v50, v51
	ds_write_b64 v205, v[130:131] offset:8480
	v_cvt_pk_bf16_f32 v130, v44, v45
	v_cvt_pk_bf16_f32 v131, v46, v47
	ds_write_b64 v205, v[130:131] offset:16896
	v_cvt_pk_bf16_f32 v130, v40, v41
	v_cvt_pk_bf16_f32 v131, v42, v43
	ds_write_b64 v205, v[130:131] offset:16928
	v_cvt_pk_bf16_f32 v130, v36, v37
	v_cvt_pk_bf16_f32 v131, v38, v39
	ds_write_b64 v205, v[130:131] offset:25344
	v_cvt_pk_bf16_f32 v130, v32, v33
	v_cvt_pk_bf16_f32 v131, v34, v35
	ds_write_b64 v205, v[130:131] offset:25376
	v_cvt_pk_bf16_f32 v130, v28, v29
	v_cvt_pk_bf16_f32 v131, v30, v31
	ds_write_b64 v205, v[130:131] offset:256
	v_cvt_pk_bf16_f32 v130, v24, v25
	v_cvt_pk_bf16_f32 v131, v26, v27
	ds_write_b64 v205, v[130:131] offset:288
	v_cvt_pk_bf16_f32 v130, v20, v21
	v_cvt_pk_bf16_f32 v131, v22, v23
	ds_write_b64 v205, v[130:131] offset:8704
	v_cvt_pk_bf16_f32 v130, v16, v17
	v_cvt_pk_bf16_f32 v131, v18, v19
	ds_write_b64 v205, v[130:131] offset:8736
	v_cvt_pk_bf16_f32 v130, v12, v13
	v_cvt_pk_bf16_f32 v131, v14, v15
	ds_write_b64 v205, v[130:131] offset:17152
	v_cvt_pk_bf16_f32 v130, v8, v9
	v_cvt_pk_bf16_f32 v131, v10, v11
	ds_write_b64 v205, v[130:131] offset:17184
	v_cvt_pk_bf16_f32 v130, v4, v5
	v_cvt_pk_bf16_f32 v131, v6, v7
	ds_write_b64 v205, v[130:131] offset:25600
	v_cvt_pk_bf16_f32 v130, v0, v1
	v_cvt_pk_bf16_f32 v131, v2, v3
	ds_write_b64 v205, v[130:131] offset:25632
	v_add_u32_e32 v130, s95, v207
	v_mad_i64_i32 v[132:133], s[78:79], v130, s33, v[186:187]
	s_waitcnt lgkmcnt(0)
	s_barrier
	global_load_dwordx4 v[174:177], v[132:133], off
	ds_read_b128 v[166:169], v212
	v_ashrrev_i32_e32 v131, 31, v130
	v_lshlrev_b64 v[196:197], 11, v[130:131]
	s_waitcnt lgkmcnt(0)
	v_mov_b64_e32 v[172:173], v[168:169]
	v_mov_b64_e32 v[170:171], v[166:167]
	s_cbranch_vccnz .LBB0_239
	v_lshl_add_u64 v[130:131], v[188:189], 0, v[196:197]
	global_load_dwordx4 v[170:173], v[130:131], off

; DI float bf2f(short b) { return __uint_as_float(((unsigned)(unsigned short)b) << 16); }
; DI bf16x8 pack8(const float* a) { u32x4 w = {cvtpk(a[0], a[1]), cvtpk(a[2], a[3]), cvtpk(a[4], a[5]), cvtpk(a[6], a[7])}; return *reinterpret_cast<bf16x8*>(&w); }
; DI float sigm(float x) { return __builtin_amdgcn_rcpf(1.f + __builtin_amdgcn_exp2f(-1.4426950408889634f * x)); }
; DI void gemm8_run(const GemmJob& ja, const GemmJob& jb, char* lds) {
;     ...
;           for (int it = 0; it < 4; ++it) { const int idx = (hb * 4 + it) * 512 + tid; const int r = idx >> 5, c16 = idx & 31; const size_t grow = (size_t)(brow + ai * 128 + r);
;             av[it] = *reinterpret_cast<const bf16x8*>(lds + r * 528 + c16 * 16);
;             gv[it] = ld8(J.gsrc + grow * INP + bcol + c16 * 8);
;             if (gb) ov[it] = ld8(J.C + grow * 1024 + bcol + c16 * 8); else ov[it] = av[it]; }
; #pragma unroll
;           for (int it = 0; it < 4; ++it) { const int idx = (hb * 4 + it) * 512 + tid; const int r = idx >> 5, c16 = idx & 31; const size_t grow = (size_t)(brow + ai * 128 + r);
;             const float4 b0 = *reinterpret_cast<const float4*>(J.bias + bcol + c16 * 8), b1 = *reinterpret_cast<const float4*>(J.bias + bcol + c16 * 8 + 4);
;             const float bb[8] = {b0.x, b0.y, b0.z, b0.w, b1.x, b1.y, b1.z, b1.w};
;             float o8[8];
; #pragma unroll
;             for (int j = 0; j < 8; ++j) { const float g = sigm(bf2f(gv[it][j]) + bb[j]); o8[j] = (gb ? bf2f(ov[it][j]) : 0.f) + bf2f(av[it][j]) * g; }
;             *reinterpret_cast<bf16x8*>(J.C + grow * 1024 + bcol + c16 * 8) = pack8(o8); } }
.LBB0_245:
	s_nop 0
	global_load_dwordx4 v[178:181], v[184:185], off offset:16
	global_load_dwordx4 v[206:209], v[184:185], off
	s_waitcnt vmcnt(5)
	v_lshlrev_b32_e32 v205, 16, v174
	v_and_b32_e32 v174, 0xffff0000, v174
	v_lshlrev_b32_e32 v210, 16, v166
	v_and_b32_e32 v166, 0xffff0000, v166
	s_and_b64 vcc, exec, s[42:43]
	s_waitcnt vmcnt(0)
	v_add_f32_e32 v174, v207, v174
	v_mul_f32_e32 v174, 0xbfb8aa3b, v174
	v_exp_f32_e32 v174, v174
	v_add_f32_e32 v205, v206, v205
	v_lshlrev_b32_e32 v206, 16, v170
	v_and_b32_e32 v170, 0xffff0000, v170
	v_add_f32_e32 v174, 1.0, v174
	v_rcp_f32_e32 v174, v174
	v_cndmask_b32_e64 v170, 0, v170, s[40:41]
	v_mul_f32_e32 v205, 0xbfb8aa3b, v205
	v_exp_f32_e32 v205, v205
	v_fmac_f32_e32 v170, v174, v166
	v_lshlrev_b32_e32 v166, 16, v175
	v_add_f32_e32 v166, v208, v166
	v_mul_f32_e32 v166, 0xbfb8aa3b, v166
	v_exp_f32_e32 v166, v166
	v_add_f32_e32 v205, 1.0, v205
	v_rcp_f32_e32 v205, v205
	v_cndmask_b32_e64 v206, 0, v206, s[40:41]
	v_add_f32_e32 v166, 1.0, v166
	v_rcp_f32_e32 v166, v166
	v_lshlrev_b32_e32 v174, 16, v171
	v_fmac_f32_e32 v206, v205, v210
	v_cndmask_b32_e64 v174, 0, v174, s[40:41]
	v_lshlrev_b32_e32 v205, 16, v167
	v_fmac_f32_e32 v174, v166, v205
	v_and_b32_e32 v166, 0xffff0000, v175
	v_add_f32_e32 v166, v209, v166
	v_mul_f32_e32 v166, 0xbfb8aa3b, v166
	v_exp_f32_e32 v166, v166
	v_and_b32_e32 v171, 0xffff0000, v171
	v_cndmask_b32_e64 v171, 0, v171, s[40:41]
	v_and_b32_e32 v167, 0xffff0000, v167
	v_add_f32_e32 v166, 1.0, v166
	v_rcp_f32_e32 v166, v166
	s_nop 0
	v_fmac_f32_e32 v171, v166, v167
	v_lshlrev_b32_e32 v166, 16, v176
	v_add_f32_e32 v166, v178, v166
	v_mul_f32_e32 v166, 0xbfb8aa3b, v166
	v_exp_f32_e32 v166, v166
	v_lshlrev_b32_e32 v167, 16, v172
	v_cndmask_b32_e64 v175, 0, v167, s[40:41]
	v_lshlrev_b32_e32 v167, 16, v168
	v_add_f32_e32 v166, 1.0, v166
	v_rcp_f32_e32 v166, v166
	s_nop 0
	v_fmac_f32_e32 v175, v166, v167
	v_and_b32_e32 v166, 0xffff0000, v176
	v_add_f32_e32 v166, v179, v166
	v_mul_f32_e32 v166, 0xbfb8aa3b, v166
	v_exp_f32_e32 v166, v166
	v_and_b32_e32 v167, 0xffff0000, v172
	v_cndmask_b32_e64 v172, 0, v167, s[40:41]
	v_and_b32_e32 v167, 0xffff0000, v168
	v_add_f32_e32 v166, 1.0, v166
	v_rcp_f32_e32 v166, v166
	s_nop 0
	v_fmac_f32_e32 v172, v166, v167
	v_lshlrev_b32_e32 v166, 16, v177
	v_add_f32_e32 v166, v180, v166
	v_mul_f32_e32 v166, 0xbfb8aa3b, v166
	v_exp_f32_e32 v166, v166
	v_lshlrev_b32_e32 v167, 16, v173
	v_cndmask_b32_e64 v176, 0, v167, s[40:41]
	v_lshlrev_b32_e32 v167, 16, v169
	v_add_f32_e32 v166, 1.0, v166
	v_rcp_f32_e32 v166, v166
	s_nop 0
	v_fmac_f32_e32 v176, v166, v167
	v_and_b32_e32 v166, 0xffff0000, v177
	v_add_f32_e32 v166, v181, v166
	v_mul_f32_e32 v166, 0xbfb8aa3b, v166
	v_exp_f32_e32 v166, v166
	v_and_b32_e32 v167, 0xffff0000, v173
	v_cndmask_b32_e64 v173, 0, v167, s[40:41]
	v_and_b32_e32 v167, 0xffff0000, v169
	v_add_f32_e32 v166, 1.0, v166
	v_rcp_f32_e32 v166, v166
	s_nop 0
	v_fmac_f32_e32 v173, v166, v167
	v_cvt_pk_bf16_f32 v166, v206, v170
	v_cvt_pk_bf16_f32 v167, v174, v171
	v_lshl_add_u64 v[170:171], v[182:183], 0, v[196:197]
	v_cvt_pk_bf16_f32 v168, v175, v172
	v_cvt_pk_bf16_f32 v169, v176, v173
	global_store_dwordx4 v[170:171], v[166:169], off sc1
	global_load_dwordx4 v[166:169], v[184:185], off offset:16
	s_nop 0
	global_load_dwordx4 v[170:173], v[184:185], off
	v_lshlrev_b32_e32 v174, 16, v162
	v_and_b32_e32 v162, 0xffff0000, v162
	v_lshlrev_b32_e32 v175, 16, v154
	v_and_b32_e32 v154, 0xffff0000, v154
	s_waitcnt vmcnt(0)
	v_add_f32_e32 v162, v171, v162
	v_mul_f32_e32 v162, 0xbfb8aa3b, v162
	v_exp_f32_e32 v162, v162
	v_add_f32_e32 v170, v170, v174
	v_lshlrev_b32_e32 v174, 16, v158
	v_and_b32_e32 v158, 0xffff0000, v158
	v_add_f32_e32 v162, 1.0, v162
	v_rcp_f32_e32 v162, v162
	v_cndmask_b32_e64 v158, 0, v158, s[40:41]
	v_mul_f32_e32 v170, 0xbfb8aa3b, v170
	v_exp_f32_e32 v170, v170
	v_fmac_f32_e32 v158, v162, v154
	v_lshlrev_b32_e32 v154, 16, v163
	v_add_f32_e32 v154, v172, v154
	v_mul_f32_e32 v154, 0xbfb8aa3b, v154
	v_exp_f32_e32 v154, v154
	v_add_f32_e32 v170, 1.0, v170
	v_rcp_f32_e32 v170, v170
	v_cndmask_b32_e64 v174, 0, v174, s[40:41]
	v_add_f32_e32 v154, 1.0, v154
	v_rcp_f32_e32 v154, v154
	v_lshlrev_b32_e32 v162, 16, v159
	v_fmac_f32_e32 v174, v170, v175
	v_cndmask_b32_e64 v162, 0, v162, s[40:41]
	v_lshlrev_b32_e32 v170, 16, v155
	v_fmac_f32_e32 v162, v154, v170
	v_and_b32_e32 v154, 0xffff0000, v163
	v_add_f32_e32 v154, v173, v154
	v_mul_f32_e32 v154, 0xbfb8aa3b, v154
	v_exp_f32_e32 v154, v154
	v_and_b32_e32 v159, 0xffff0000, v159
	v_cndmask_b32_e64 v159, 0, v159, s[40:41]
	v_and_b32_e32 v155, 0xffff0000, v155
	v_add_f32_e32 v154, 1.0, v154
	v_rcp_f32_e32 v154, v154
	s_nop 0
	v_fmac_f32_e32 v159, v154, v155
	v_lshlrev_b32_e32 v154, 16, v164
	v_add_f32_e32 v154, v166, v154
	v_mul_f32_e32 v154, 0xbfb8aa3b, v154
	v_exp_f32_e32 v154, v154
	v_lshlrev_b32_e32 v155, 16, v160
	v_cndmask_b32_e64 v163, 0, v155, s[40:41]
	v_lshlrev_b32_e32 v155, 16, v156
	v_add_f32_e32 v154, 1.0, v154
	v_rcp_f32_e32 v154, v154
	s_nop 0
	v_fmac_f32_e32 v163, v154, v155
	v_and_b32_e32 v154, 0xffff0000, v164
	v_add_f32_e32 v154, v167, v154
	v_mul_f32_e32 v154, 0xbfb8aa3b, v154
	v_exp_f32_e32 v154, v154
	v_and_b32_e32 v155, 0xffff0000, v160
	v_cndmask_b32_e64 v160, 0, v155, s[40:41]
	v_and_b32_e32 v155, 0xffff0000, v156
	v_add_f32_e32 v154, 1.0, v154
	v_rcp_f32_e32 v154, v154
	s_nop 0
	v_fmac_f32_e32 v160, v154, v155
	v_lshlrev_b32_e32 v154, 16, v165
	v_add_f32_e32 v154, v168, v154
	v_mul_f32_e32 v154, 0xbfb8aa3b, v154
	v_exp_f32_e32 v154, v154
	v_lshlrev_b32_e32 v155, 16, v161
	v_cndmask_b32_e64 v164, 0, v155, s[40:41]
	v_lshlrev_b32_e32 v155, 16, v157
	v_add_f32_e32 v154, 1.0, v154
	v_rcp_f32_e32 v154, v154
	s_nop 0
	v_fmac_f32_e32 v164, v154, v155
	v_and_b32_e32 v154, 0xffff0000, v165
	v_add_f32_e32 v154, v169, v154
	v_mul_f32_e32 v154, 0xbfb8aa3b, v154
	v_exp_f32_e32 v154, v154
	v_and_b32_e32 v155, 0xffff0000, v161
	v_cndmask_b32_e64 v161, 0, v155, s[40:41]
	v_and_b32_e32 v155, 0xffff0000, v157
	v_add_f32_e32 v154, 1.0, v154
	v_rcp_f32_e32 v154, v154
	s_nop 0
	v_fmac_f32_e32 v161, v154, v155
	v_cvt_pk_bf16_f32 v154, v174, v158
	v_cvt_pk_bf16_f32 v155, v162, v159
	v_lshl_add_u64 v[158:159], v[182:183], 0, v[194:195]
	v_cvt_pk_bf16_f32 v156, v163, v160
	v_cvt_pk_bf16_f32 v157, v164, v161
	global_store_dwordx4 v[158:159], v[154:157], off sc1
	global_load_dwordx4 v[154:157], v[184:185], off offset:16
	s_nop 0
	global_load_dwordx4 v[158:161], v[184:185], off
	v_lshlrev_b32_e32 v162, 16, v150
	v_and_b32_e32 v150, 0xffff0000, v150
	v_lshlrev_b32_e32 v163, 16, v142
	v_and_b32_e32 v142, 0xffff0000, v142
	s_waitcnt vmcnt(0)
; DI float bf2f(short b) { return __uint_as_float(((unsigned)(unsigned short)b) << 16); }
; DI bf16x8 pack8(const float* a) { u32x4 w = {cvtpk(a[0], a[1]), cvtpk(a[2], a[3]), cvtpk(a[4], a[5]), cvtpk(a[6], a[7])}; return *reinterpret_cast<bf16x8*>(&w); }
; DI float sigm(float x) { return __builtin_amdgcn_rcpf(1.f + __builtin_amdgcn_exp2f(-1.4426950408889634f * x)); }
; DI void gemm8_run(const GemmJob& ja, const GemmJob& jb, char* lds) {
;     ...
;           for (int it = 0; it < 4; ++it) { const int idx = (hb * 4 + it) * 512 + tid; const int r = idx >> 5, c16 = idx & 31; const size_t grow = (size_t)(brow + ai * 128 + r);
;             av[it] = *reinterpret_cast<const bf16x8*>(lds + r * 528 + c16 * 16);
;             gv[it] = ld8(J.gsrc + grow * INP + bcol + c16 * 8);
;             if (gb) ov[it] = ld8(J.C + grow * 1024 + bcol + c16 * 8); else ov[it] = av[it]; }
; #pragma unroll
;           for (int it = 0; it < 4; ++it) { const int idx = (hb * 4 + it) * 512 + tid; const int r = idx >> 5, c16 = idx & 31; const size_t grow = (size_t)(brow + ai * 128 + r);
;             const float4 b0 = *reinterpret_cast<const float4*>(J.bias + bcol + c16 * 8), b1 = *reinterpret_cast<const float4*>(J.bias + bcol + c16 * 8 + 4);
;             const float bb[8] = {b0.x, b0.y, b0.z, b0.w, b1.x, b1.y, b1.z, b1.w};
;             float o8[8];
; #pragma unroll
;             for (int j = 0; j < 8; ++j) { const float g = sigm(bf2f(gv[it][j]) + bb[j]); o8[j] = (gb ? bf2f(ov[it][j]) : 0.f) + bf2f(av[it][j]) * g; }
;             *reinterpret_cast<bf16x8*>(J.C + grow * 1024 + bcol + c16 * 8) = pack8(o8); } }
	v_add_f32_e32 v150, v159, v150
	v_mul_f32_e32 v150, 0xbfb8aa3b, v150
	v_exp_f32_e32 v150, v150
	v_add_f32_e32 v158, v158, v162
	v_lshlrev_b32_e32 v162, 16, v146
	v_and_b32_e32 v146, 0xffff0000, v146
	v_add_f32_e32 v150, 1.0, v150
	v_rcp_f32_e32 v150, v150
	v_cndmask_b32_e64 v146, 0, v146, s[40:41]
	v_mul_f32_e32 v158, 0xbfb8aa3b, v158
	v_exp_f32_e32 v158, v158
	v_fmac_f32_e32 v146, v150, v142
	v_lshlrev_b32_e32 v142, 16, v151
	v_add_f32_e32 v142, v160, v142
	v_mul_f32_e32 v142, 0xbfb8aa3b, v142
	v_exp_f32_e32 v142, v142
	v_add_f32_e32 v158, 1.0, v158
	v_rcp_f32_e32 v158, v158
	v_cndmask_b32_e64 v162, 0, v162, s[40:41]
	v_add_f32_e32 v142, 1.0, v142
	v_rcp_f32_e32 v142, v142
	v_lshlrev_b32_e32 v150, 16, v147
	v_fmac_f32_e32 v162, v158, v163
	v_cndmask_b32_e64 v150, 0, v150, s[40:41]
	v_lshlrev_b32_e32 v158, 16, v143
	v_fmac_f32_e32 v150, v142, v158
	v_and_b32_e32 v142, 0xffff0000, v151
	v_add_f32_e32 v142, v161, v142
	v_mul_f32_e32 v142, 0xbfb8aa3b, v142
	v_exp_f32_e32 v142, v142
	v_and_b32_e32 v147, 0xffff0000, v147
	v_cndmask_b32_e64 v147, 0, v147, s[40:41]
	v_and_b32_e32 v143, 0xffff0000, v143
	v_add_f32_e32 v142, 1.0, v142
	v_rcp_f32_e32 v142, v142
	s_nop 0
	v_fmac_f32_e32 v147, v142, v143
	v_lshlrev_b32_e32 v142, 16, v152
	v_add_f32_e32 v142, v154, v142
	v_mul_f32_e32 v142, 0xbfb8aa3b, v142
	v_exp_f32_e32 v142, v142
	v_lshlrev_b32_e32 v143, 16, v148
	v_cndmask_b32_e64 v151, 0, v143, s[40:41]
	v_lshlrev_b32_e32 v143, 16, v144
	v_add_f32_e32 v142, 1.0, v142
	v_rcp_f32_e32 v142, v142
	s_nop 0
	v_fmac_f32_e32 v151, v142, v143
	v_and_b32_e32 v142, 0xffff0000, v152
	v_add_f32_e32 v142, v155, v142
	v_mul_f32_e32 v142, 0xbfb8aa3b, v142
	v_exp_f32_e32 v142, v142
	v_and_b32_e32 v143, 0xffff0000, v148
	v_cndmask_b32_e64 v148, 0, v143, s[40:41]
	v_and_b32_e32 v143, 0xffff0000, v144
	v_add_f32_e32 v142, 1.0, v142
	v_rcp_f32_e32 v142, v142
	s_nop 0
	v_fmac_f32_e32 v148, v142, v143
	v_lshlrev_b32_e32 v142, 16, v153
	v_add_f32_e32 v142, v156, v142
	v_mul_f32_e32 v142, 0xbfb8aa3b, v142
	v_exp_f32_e32 v142, v142
	v_lshlrev_b32_e32 v143, 16, v149
	v_cndmask_b32_e64 v152, 0, v143, s[40:41]
	v_lshlrev_b32_e32 v143, 16, v145
	v_add_f32_e32 v142, 1.0, v142
	v_rcp_f32_e32 v142, v142
	s_nop 0
	v_fmac_f32_e32 v152, v142, v143
	v_and_b32_e32 v142, 0xffff0000, v153
	v_add_f32_e32 v142, v157, v142
	v_mul_f32_e32 v142, 0xbfb8aa3b, v142
	v_exp_f32_e32 v142, v142
	v_and_b32_e32 v143, 0xffff0000, v149
	v_cndmask_b32_e64 v149, 0, v143, s[40:41]
	v_and_b32_e32 v143, 0xffff0000, v145
	v_add_f32_e32 v142, 1.0, v142
	v_rcp_f32_e32 v142, v142
	s_nop 0
	v_fmac_f32_e32 v149, v142, v143
	v_cvt_pk_bf16_f32 v142, v162, v146
	v_cvt_pk_bf16_f32 v143, v150, v147
	v_lshl_add_u64 v[146:147], v[182:183], 0, v[192:193]
	v_cvt_pk_bf16_f32 v144, v151, v148
	v_cvt_pk_bf16_f32 v145, v152, v149
	global_store_dwordx4 v[146:147], v[142:145], off sc1
	global_load_dwordx4 v[142:145], v[184:185], off offset:16
	s_nop 0
	global_load_dwordx4 v[146:149], v[184:185], off
	v_lshlrev_b32_e32 v150, 16, v138
	v_and_b32_e32 v138, 0xffff0000, v138
	v_lshlrev_b32_e32 v151, 16, v130
	v_and_b32_e32 v130, 0xffff0000, v130
	s_waitcnt vmcnt(0)
	v_add_f32_e32 v138, v147, v138
	v_mul_f32_e32 v138, 0xbfb8aa3b, v138
	v_exp_f32_e32 v138, v138
	v_add_f32_e32 v146, v146, v150
	v_lshlrev_b32_e32 v150, 16, v134
	v_and_b32_e32 v134, 0xffff0000, v134
	v_add_f32_e32 v138, 1.0, v138
	v_rcp_f32_e32 v138, v138
	v_cndmask_b32_e64 v134, 0, v134, s[40:41]
	v_mul_f32_e32 v146, 0xbfb8aa3b, v146
	v_exp_f32_e32 v146, v146
	v_fmac_f32_e32 v134, v138, v130
	v_lshlrev_b32_e32 v130, 16, v139
	v_add_f32_e32 v130, v148, v130
	v_mul_f32_e32 v130, 0xbfb8aa3b, v130
	v_exp_f32_e32 v130, v130
	v_add_f32_e32 v146, 1.0, v146
	v_rcp_f32_e32 v146, v146
	v_cndmask_b32_e64 v150, 0, v150, s[40:41]
	v_add_f32_e32 v130, 1.0, v130
	v_rcp_f32_e32 v130, v130
	v_lshlrev_b32_e32 v138, 16, v135
	v_fmac_f32_e32 v150, v146, v151
	v_cndmask_b32_e64 v138, 0, v138, s[40:41]
	v_lshlrev_b32_e32 v146, 16, v131
	v_fmac_f32_e32 v138, v130, v146
	v_and_b32_e32 v130, 0xffff0000, v139
	v_add_f32_e32 v130, v149, v130
	v_mul_f32_e32 v130, 0xbfb8aa3b, v130
	v_exp_f32_e32 v130, v130
	v_and_b32_e32 v135, 0xffff0000, v135
	v_cndmask_b32_e64 v135, 0, v135, s[40:41]
	v_and_b32_e32 v131, 0xffff0000, v131
	v_add_f32_e32 v130, 1.0, v130
	v_rcp_f32_e32 v130, v130
	s_nop 0
	v_fmac_f32_e32 v135, v130, v131
	v_lshlrev_b32_e32 v130, 16, v140
	v_add_f32_e32 v130, v142, v130
	v_mul_f32_e32 v130, 0xbfb8aa3b, v130
	v_exp_f32_e32 v130, v130
	v_lshlrev_b32_e32 v131, 16, v136
	v_cndmask_b32_e64 v139, 0, v131, s[40:41]
	v_lshlrev_b32_e32 v131, 16, v132
	v_add_f32_e32 v130, 1.0, v130
	v_rcp_f32_e32 v130, v130
	s_nop 0
	v_fmac_f32_e32 v139, v130, v131
	v_and_b32_e32 v130, 0xffff0000, v140
	v_add_f32_e32 v130, v143, v130
	v_mul_f32_e32 v130, 0xbfb8aa3b, v130
	v_exp_f32_e32 v130, v130
	v_and_b32_e32 v131, 0xffff0000, v136
	v_cndmask_b32_e64 v136, 0, v131, s[40:41]
	v_and_b32_e32 v131, 0xffff0000, v132
	v_add_f32_e32 v130, 1.0, v130
	v_rcp_f32_e32 v130, v130
	s_nop 0
	v_fmac_f32_e32 v136, v130, v131
	v_lshlrev_b32_e32 v130, 16, v141
	v_add_f32_e32 v130, v144, v130
	v_mul_f32_e32 v130, 0xbfb8aa3b, v130
	v_exp_f32_e32 v130, v130
	v_lshlrev_b32_e32 v131, 16, v137
	v_cndmask_b32_e64 v140, 0, v131, s[40:41]
	v_lshlrev_b32_e32 v131, 16, v133
	v_add_f32_e32 v130, 1.0, v130
	v_rcp_f32_e32 v130, v130
	s_nop 0
	v_fmac_f32_e32 v140, v130, v131
	v_and_b32_e32 v130, 0xffff0000, v141
	v_add_f32_e32 v130, v145, v130
	v_mul_f32_e32 v130, 0xbfb8aa3b, v130
	v_exp_f32_e32 v130, v130
	v_and_b32_e32 v131, 0xffff0000, v137
	v_cndmask_b32_e64 v137, 0, v131, s[40:41]
	v_and_b32_e32 v131, 0xffff0000, v133
	v_add_f32_e32 v130, 1.0, v130
	v_rcp_f32_e32 v130, v130
	s_nop 0
	v_fmac_f32_e32 v137, v130, v131
	v_cvt_pk_bf16_f32 v130, v150, v134
	v_cvt_pk_bf16_f32 v131, v138, v135
	v_lshl_add_u64 v[134:135], v[182:183], 0, v[190:191]
	v_cvt_pk_bf16_f32 v132, v139, v136
	v_cvt_pk_bf16_f32 v133, v140, v137
	global_store_dwordx4 v[134:135], v[130:133], off sc1
	ds_read_b128 v[166:169], v204
	s_waitcnt lgkmcnt(0)
	v_mov_b64_e32 v[172:173], v[168:169]
	v_add_u32_e32 v130, s95, v203
	v_mad_i64_i32 v[132:133], s[78:79], v130, s33, v[186:187]
	global_load_dwordx4 v[174:177], v[132:133], off
	v_ashrrev_i32_e32 v131, 31, v130
	v_lshlrev_b64 v[194:195], 11, v[130:131]
	v_mov_b64_e32 v[170:171], v[166:167]
	s_cbranch_vccnz .LBB0_247
	v_lshl_add_u64 v[130:131], v[188:189], 0, v[194:195]
	global_load_dwordx4 v[170:173], v[130:131], off

; DI float bf2f(short b) { return __uint_as_float(((unsigned)(unsigned short)b) << 16); }
; DI bf16x8 pack8(const float* a) { u32x4 w = {cvtpk(a[0], a[1]), cvtpk(a[2], a[3]), cvtpk(a[4], a[5]), cvtpk(a[6], a[7])}; return *reinterpret_cast<bf16x8*>(&w); }
; DI float sigm(float x) { return __builtin_amdgcn_rcpf(1.f + __builtin_amdgcn_exp2f(-1.4426950408889634f * x)); }
; DI void gemm8_run(const GemmJob& ja, const GemmJob& jb, char* lds) {
;     ...
;           for (int it = 0; it < 4; ++it) { const int idx = (hb * 4 + it) * 512 + tid; const int r = idx >> 5, c16 = idx & 31; const size_t grow = (size_t)(brow + ai * 128 + r);
;             av[it] = *reinterpret_cast<const bf16x8*>(lds + r * 528 + c16 * 16);
;             gv[it] = ld8(J.gsrc + grow * INP + bcol + c16 * 8);
;             if (gb) ov[it] = ld8(J.C + grow * 1024 + bcol + c16 * 8); else ov[it] = av[it]; }
; #pragma unroll
;           for (int it = 0; it < 4; ++it) { const int idx = (hb * 4 + it) * 512 + tid; const int r = idx >> 5, c16 = idx & 31; const size_t grow = (size_t)(brow + ai * 128 + r);
;             const float4 b0 = *reinterpret_cast<const float4*>(J.bias + bcol + c16 * 8), b1 = *reinterpret_cast<const float4*>(J.bias + bcol + c16 * 8 + 4);
;             const float bb[8] = {b0.x, b0.y, b0.z, b0.w, b1.x, b1.y, b1.z, b1.w};
;             float o8[8];
; #pragma unroll
;             for (int j = 0; j < 8; ++j) { const float g = sigm(bf2f(gv[it][j]) + bb[j]); o8[j] = (gb ? bf2f(ov[it][j]) : 0.f) + bf2f(av[it][j]) * g; }
;             *reinterpret_cast<bf16x8*>(J.C + grow * 1024 + bcol + c16 * 8) = pack8(o8); } }
.LBB0_253:
	s_nop 0
	global_load_dwordx4 v[178:181], v[184:185], off offset:16
	global_load_dwordx4 v[196:199], v[184:185], off
	s_waitcnt vmcnt(5)
	v_lshlrev_b32_e32 v96, 16, v174
	v_lshlrev_b32_e32 v188, 16, v170
	v_cndmask_b32_e64 v188, 0, v188, s[40:41]
	v_lshlrev_b32_e32 v189, 16, v166
	v_and_b32_e32 v170, 0xffff0000, v170
	v_cndmask_b32_e64 v170, 0, v170, s[40:41]
	v_and_b32_e32 v166, 0xffff0000, v166
	s_waitcnt vmcnt(0)
	v_add_f32_e32 v96, v196, v96
	v_mul_f32_e32 v96, 0xbfb8aa3b, v96
	v_exp_f32_e32 v96, v96
	s_nop 0
	v_add_f32_e32 v96, 1.0, v96
	v_rcp_f32_e32 v96, v96
	s_nop 0
	v_fmac_f32_e32 v188, v96, v189
	v_and_b32_e32 v96, 0xffff0000, v174
	v_add_f32_e32 v96, v197, v96
	v_mul_f32_e32 v96, 0xbfb8aa3b, v96
	v_exp_f32_e32 v96, v96
	s_nop 0
	v_add_f32_e32 v96, 1.0, v96
	v_rcp_f32_e32 v96, v96
	s_nop 0
	v_fmac_f32_e32 v170, v96, v166
	v_lshlrev_b32_e32 v96, 16, v175
	v_add_f32_e32 v96, v198, v96
	v_mul_f32_e32 v96, 0xbfb8aa3b, v96
	v_exp_f32_e32 v96, v96
	v_lshlrev_b32_e32 v166, 16, v171
	v_cndmask_b32_e64 v174, 0, v166, s[40:41]
	v_lshlrev_b32_e32 v166, 16, v167
	v_add_f32_e32 v96, 1.0, v96
	v_rcp_f32_e32 v96, v96
	s_nop 0
	v_fmac_f32_e32 v174, v96, v166
	v_and_b32_e32 v96, 0xffff0000, v175
	v_add_f32_e32 v96, v199, v96
	v_mul_f32_e32 v96, 0xbfb8aa3b, v96
	v_exp_f32_e32 v96, v96
	v_and_b32_e32 v166, 0xffff0000, v171
	v_cndmask_b32_e64 v171, 0, v166, s[40:41]
	v_and_b32_e32 v166, 0xffff0000, v167
	v_add_f32_e32 v96, 1.0, v96
	v_rcp_f32_e32 v96, v96
	s_nop 0
	v_fmac_f32_e32 v171, v96, v166
	v_lshlrev_b32_e32 v96, 16, v176
	v_add_f32_e32 v96, v178, v96
	v_mul_f32_e32 v96, 0xbfb8aa3b, v96
	v_exp_f32_e32 v96, v96
	v_lshlrev_b32_e32 v166, 16, v172
	v_cndmask_b32_e64 v175, 0, v166, s[40:41]
	v_lshlrev_b32_e32 v166, 16, v168
	v_add_f32_e32 v96, 1.0, v96
	v_rcp_f32_e32 v96, v96
	s_nop 0
	v_fmac_f32_e32 v175, v96, v166
	v_and_b32_e32 v96, 0xffff0000, v176
	v_add_f32_e32 v96, v179, v96
	v_mul_f32_e32 v96, 0xbfb8aa3b, v96
	v_exp_f32_e32 v96, v96
	v_and_b32_e32 v166, 0xffff0000, v172
	v_cndmask_b32_e64 v172, 0, v166, s[40:41]
	v_and_b32_e32 v166, 0xffff0000, v168
	v_add_f32_e32 v96, 1.0, v96
	v_rcp_f32_e32 v96, v96
	s_nop 0
	v_fmac_f32_e32 v172, v96, v166
	v_lshlrev_b32_e32 v96, 16, v177
	v_add_f32_e32 v96, v180, v96
	v_mul_f32_e32 v96, 0xbfb8aa3b, v96
	v_exp_f32_e32 v96, v96
	v_lshlrev_b32_e32 v166, 16, v173
	v_cndmask_b32_e64 v176, 0, v166, s[40:41]
	v_lshlrev_b32_e32 v166, 16, v169
	v_add_f32_e32 v96, 1.0, v96
	v_rcp_f32_e32 v96, v96
	s_nop 0
	v_fmac_f32_e32 v176, v96, v166
	v_and_b32_e32 v96, 0xffff0000, v177
	v_add_f32_e32 v96, v181, v96
	v_mul_f32_e32 v96, 0xbfb8aa3b, v96
	v_exp_f32_e32 v96, v96
	v_and_b32_e32 v166, 0xffff0000, v173
	v_cndmask_b32_e64 v173, 0, v166, s[40:41]
	v_and_b32_e32 v166, 0xffff0000, v169
	v_add_f32_e32 v96, 1.0, v96
	v_rcp_f32_e32 v96, v96
	s_nop 0
	v_fmac_f32_e32 v173, v96, v166
	v_cvt_pk_bf16_f32 v166, v188, v170
	v_cvt_pk_bf16_f32 v167, v174, v171
	v_lshl_add_u64 v[170:171], v[182:183], 0, v[194:195]
	v_cvt_pk_bf16_f32 v168, v175, v172
	v_cvt_pk_bf16_f32 v169, v176, v173
	global_store_dwordx4 v[170:171], v[166:169], off sc1
	global_load_dwordx4 v[166:169], v[184:185], off offset:16
	s_nop 0
	global_load_dwordx4 v[170:173], v[184:185], off
	v_lshlrev_b32_e32 v96, 16, v162
	v_lshlrev_b32_e32 v174, 16, v154
	v_and_b32_e32 v154, 0xffff0000, v154
	s_waitcnt vmcnt(0)
	v_add_f32_e32 v96, v170, v96
	v_mul_f32_e32 v96, 0xbfb8aa3b, v96
	v_exp_f32_e32 v96, v96
	v_lshlrev_b32_e32 v170, 16, v158
	v_cndmask_b32_e64 v170, 0, v170, s[40:41]
	v_and_b32_e32 v158, 0xffff0000, v158
	v_add_f32_e32 v96, 1.0, v96
	v_rcp_f32_e32 v96, v96
	v_cndmask_b32_e64 v158, 0, v158, s[40:41]
	v_fmac_f32_e32 v170, v96, v174
	v_and_b32_e32 v96, 0xffff0000, v162
	v_add_f32_e32 v96, v171, v96
	v_mul_f32_e32 v96, 0xbfb8aa3b, v96
	v_exp_f32_e32 v96, v96
	s_nop 0
	v_add_f32_e32 v96, 1.0, v96
	v_rcp_f32_e32 v96, v96
	s_nop 0
	v_fmac_f32_e32 v158, v96, v154
	v_lshlrev_b32_e32 v96, 16, v163
	v_add_f32_e32 v96, v172, v96
	v_mul_f32_e32 v96, 0xbfb8aa3b, v96
	v_exp_f32_e32 v96, v96
	v_lshlrev_b32_e32 v154, 16, v159
	v_cndmask_b32_e64 v162, 0, v154, s[40:41]
	v_lshlrev_b32_e32 v154, 16, v155
	v_add_f32_e32 v96, 1.0, v96
	v_rcp_f32_e32 v96, v96
	s_nop 0
	v_fmac_f32_e32 v162, v96, v154
	v_and_b32_e32 v96, 0xffff0000, v163
	v_add_f32_e32 v96, v173, v96
	v_mul_f32_e32 v96, 0xbfb8aa3b, v96
	v_exp_f32_e32 v96, v96
	v_and_b32_e32 v154, 0xffff0000, v159
	v_cndmask_b32_e64 v159, 0, v154, s[40:41]
	v_and_b32_e32 v154, 0xffff0000, v155
	v_add_f32_e32 v96, 1.0, v96
	v_rcp_f32_e32 v96, v96
	s_nop 0
	v_fmac_f32_e32 v159, v96, v154
	v_lshlrev_b32_e32 v96, 16, v164
	v_add_f32_e32 v96, v166, v96
	v_mul_f32_e32 v96, 0xbfb8aa3b, v96
	v_exp_f32_e32 v96, v96
	v_lshlrev_b32_e32 v154, 16, v160
	v_cndmask_b32_e64 v163, 0, v154, s[40:41]
	v_lshlrev_b32_e32 v154, 16, v156
	v_add_f32_e32 v96, 1.0, v96
	v_rcp_f32_e32 v96, v96
	s_nop 0
	v_fmac_f32_e32 v163, v96, v154
	v_and_b32_e32 v96, 0xffff0000, v164
	v_add_f32_e32 v96, v167, v96
	v_mul_f32_e32 v96, 0xbfb8aa3b, v96
	v_exp_f32_e32 v96, v96
	v_and_b32_e32 v154, 0xffff0000, v160
	v_cndmask_b32_e64 v160, 0, v154, s[40:41]
	v_and_b32_e32 v154, 0xffff0000, v156
	v_add_f32_e32 v96, 1.0, v96
	v_rcp_f32_e32 v96, v96
	s_nop 0
	v_fmac_f32_e32 v160, v96, v154
	v_lshlrev_b32_e32 v96, 16, v165
	v_add_f32_e32 v96, v168, v96
	v_mul_f32_e32 v96, 0xbfb8aa3b, v96
	v_exp_f32_e32 v96, v96
	v_lshlrev_b32_e32 v154, 16, v161
	v_cndmask_b32_e64 v164, 0, v154, s[40:41]
	v_lshlrev_b32_e32 v154, 16, v157
	v_add_f32_e32 v96, 1.0, v96
	v_rcp_f32_e32 v96, v96
	s_nop 0
	v_fmac_f32_e32 v164, v96, v154
	v_and_b32_e32 v96, 0xffff0000, v165
	v_add_f32_e32 v96, v169, v96
	v_mul_f32_e32 v96, 0xbfb8aa3b, v96
	v_exp_f32_e32 v96, v96
	v_and_b32_e32 v154, 0xffff0000, v161
	v_cndmask_b32_e64 v161, 0, v154, s[40:41]
	v_and_b32_e32 v154, 0xffff0000, v157
	v_add_f32_e32 v96, 1.0, v96
	v_rcp_f32_e32 v96, v96
	s_nop 0
	v_fmac_f32_e32 v161, v96, v154
	v_cvt_pk_bf16_f32 v154, v170, v158
	v_cvt_pk_bf16_f32 v155, v162, v159
	v_lshl_add_u64 v[158:159], v[182:183], 0, v[192:193]
	v_cvt_pk_bf16_f32 v156, v163, v160
	v_cvt_pk_bf16_f32 v157, v164, v161
	global_store_dwordx4 v[158:159], v[154:157], off sc1
	global_load_dwordx4 v[154:157], v[184:185], off offset:16
	s_nop 0
	global_load_dwordx4 v[158:161], v[184:185], off
	v_lshlrev_b32_e32 v96, 16, v150
	v_lshlrev_b32_e32 v162, 16, v142
	v_and_b32_e32 v142, 0xffff0000, v142
	s_waitcnt vmcnt(0)
; DI float bf2f(short b) { return __uint_as_float(((unsigned)(unsigned short)b) << 16); }
; DI bf16x8 pack8(const float* a) { u32x4 w = {cvtpk(a[0], a[1]), cvtpk(a[2], a[3]), cvtpk(a[4], a[5]), cvtpk(a[6], a[7])}; return *reinterpret_cast<bf16x8*>(&w); }
; DI float sigm(float x) { return __builtin_amdgcn_rcpf(1.f + __builtin_amdgcn_exp2f(-1.4426950408889634f * x)); }
; DI void gemm8_run(const GemmJob& ja, const GemmJob& jb, char* lds) {
;     ...
;           for (int it = 0; it < 4; ++it) { const int idx = (hb * 4 + it) * 512 + tid; const int r = idx >> 5, c16 = idx & 31; const size_t grow = (size_t)(brow + ai * 128 + r);
;             av[it] = *reinterpret_cast<const bf16x8*>(lds + r * 528 + c16 * 16);
;             gv[it] = ld8(J.gsrc + grow * INP + bcol + c16 * 8);
;             if (gb) ov[it] = ld8(J.C + grow * 1024 + bcol + c16 * 8); else ov[it] = av[it]; }
; #pragma unroll
;           for (int it = 0; it < 4; ++it) { const int idx = (hb * 4 + it) * 512 + tid; const int r = idx >> 5, c16 = idx & 31; const size_t grow = (size_t)(brow + ai * 128 + r);
;             const float4 b0 = *reinterpret_cast<const float4*>(J.bias + bcol + c16 * 8), b1 = *reinterpret_cast<const float4*>(J.bias + bcol + c16 * 8 + 4);
;             const float bb[8] = {b0.x, b0.y, b0.z, b0.w, b1.x, b1.y, b1.z, b1.w};
;             float o8[8];
; #pragma unroll
;             for (int j = 0; j < 8; ++j) { const float g = sigm(bf2f(gv[it][j]) + bb[j]); o8[j] = (gb ? bf2f(ov[it][j]) : 0.f) + bf2f(av[it][j]) * g; }
;             *reinterpret_cast<bf16x8*>(J.C + grow * 1024 + bcol + c16 * 8) = pack8(o8); } }
	v_add_f32_e32 v96, v158, v96
	v_mul_f32_e32 v96, 0xbfb8aa3b, v96
	v_exp_f32_e32 v96, v96
	v_lshlrev_b32_e32 v158, 16, v146
	v_cndmask_b32_e64 v158, 0, v158, s[40:41]
	v_and_b32_e32 v146, 0xffff0000, v146
	v_add_f32_e32 v96, 1.0, v96
	v_rcp_f32_e32 v96, v96
	v_cndmask_b32_e64 v146, 0, v146, s[40:41]
	v_fmac_f32_e32 v158, v96, v162
	v_and_b32_e32 v96, 0xffff0000, v150
	v_add_f32_e32 v96, v159, v96
	v_mul_f32_e32 v96, 0xbfb8aa3b, v96
	v_exp_f32_e32 v96, v96
	s_nop 0
	v_add_f32_e32 v96, 1.0, v96
	v_rcp_f32_e32 v96, v96
	s_nop 0
	v_fmac_f32_e32 v146, v96, v142
	v_lshlrev_b32_e32 v96, 16, v151
	v_add_f32_e32 v96, v160, v96
	v_mul_f32_e32 v96, 0xbfb8aa3b, v96
	v_exp_f32_e32 v96, v96
	v_lshlrev_b32_e32 v142, 16, v147
	v_cndmask_b32_e64 v150, 0, v142, s[40:41]
	v_lshlrev_b32_e32 v142, 16, v143
	v_add_f32_e32 v96, 1.0, v96
	v_rcp_f32_e32 v96, v96
	s_nop 0
	v_fmac_f32_e32 v150, v96, v142
	v_and_b32_e32 v96, 0xffff0000, v151
	v_add_f32_e32 v96, v161, v96
	v_mul_f32_e32 v96, 0xbfb8aa3b, v96
	v_exp_f32_e32 v96, v96
	v_and_b32_e32 v142, 0xffff0000, v147
	v_cndmask_b32_e64 v147, 0, v142, s[40:41]
	v_and_b32_e32 v142, 0xffff0000, v143
	v_add_f32_e32 v96, 1.0, v96
	v_rcp_f32_e32 v96, v96
	s_nop 0
	v_fmac_f32_e32 v147, v96, v142
	v_lshlrev_b32_e32 v96, 16, v152
	v_add_f32_e32 v96, v154, v96
	v_mul_f32_e32 v96, 0xbfb8aa3b, v96
	v_exp_f32_e32 v96, v96
	v_lshlrev_b32_e32 v142, 16, v148
	v_cndmask_b32_e64 v151, 0, v142, s[40:41]
	v_lshlrev_b32_e32 v142, 16, v144
	v_add_f32_e32 v96, 1.0, v96
	v_rcp_f32_e32 v96, v96
	s_nop 0
	v_fmac_f32_e32 v151, v96, v142
	v_and_b32_e32 v96, 0xffff0000, v152
	v_add_f32_e32 v96, v155, v96
	v_mul_f32_e32 v96, 0xbfb8aa3b, v96
	v_exp_f32_e32 v96, v96
	v_and_b32_e32 v142, 0xffff0000, v148
	v_cndmask_b32_e64 v148, 0, v142, s[40:41]
	v_and_b32_e32 v142, 0xffff0000, v144
	v_add_f32_e32 v96, 1.0, v96
	v_rcp_f32_e32 v96, v96
	s_nop 0
	v_fmac_f32_e32 v148, v96, v142
	v_lshlrev_b32_e32 v96, 16, v153
	v_add_f32_e32 v96, v156, v96
	v_mul_f32_e32 v96, 0xbfb8aa3b, v96
	v_exp_f32_e32 v96, v96
	v_lshlrev_b32_e32 v142, 16, v149
	v_cndmask_b32_e64 v152, 0, v142, s[40:41]
	v_lshlrev_b32_e32 v142, 16, v145
	v_add_f32_e32 v96, 1.0, v96
	v_rcp_f32_e32 v96, v96
	s_nop 0
	v_fmac_f32_e32 v152, v96, v142
	v_and_b32_e32 v96, 0xffff0000, v153
	v_add_f32_e32 v96, v157, v96
	v_mul_f32_e32 v96, 0xbfb8aa3b, v96
	v_exp_f32_e32 v96, v96
	v_and_b32_e32 v142, 0xffff0000, v149
	v_cndmask_b32_e64 v149, 0, v142, s[40:41]
	v_and_b32_e32 v142, 0xffff0000, v145
	v_add_f32_e32 v96, 1.0, v96
	v_rcp_f32_e32 v96, v96
	s_nop 0
	v_fmac_f32_e32 v149, v96, v142
	v_cvt_pk_bf16_f32 v142, v158, v146
	v_cvt_pk_bf16_f32 v143, v150, v147
	v_lshl_add_u64 v[146:147], v[182:183], 0, v[190:191]
	v_cvt_pk_bf16_f32 v144, v151, v148
	v_cvt_pk_bf16_f32 v145, v152, v149
	global_store_dwordx4 v[146:147], v[142:145], off sc1
	global_load_dwordx4 v[142:145], v[184:185], off offset:16
	s_nop 0
	global_load_dwordx4 v[146:149], v[184:185], off
	v_lshlrev_b32_e32 v96, 16, v138
	v_lshlrev_b32_e32 v150, 16, v130
	v_and_b32_e32 v130, 0xffff0000, v130
	s_waitcnt vmcnt(0)
	v_add_f32_e32 v96, v146, v96
	v_mul_f32_e32 v96, 0xbfb8aa3b, v96
	v_exp_f32_e32 v96, v96
	v_lshlrev_b32_e32 v146, 16, v134
	v_cndmask_b32_e64 v146, 0, v146, s[40:41]
	v_and_b32_e32 v134, 0xffff0000, v134
	v_add_f32_e32 v96, 1.0, v96
	v_rcp_f32_e32 v96, v96
	v_cndmask_b32_e64 v134, 0, v134, s[40:41]
	v_fmac_f32_e32 v146, v96, v150
	v_and_b32_e32 v96, 0xffff0000, v138
	v_add_f32_e32 v96, v147, v96
	v_mul_f32_e32 v96, 0xbfb8aa3b, v96
	v_exp_f32_e32 v96, v96
	s_nop 0
	v_add_f32_e32 v96, 1.0, v96
	v_rcp_f32_e32 v96, v96
	s_nop 0
	v_fmac_f32_e32 v134, v96, v130
	v_lshlrev_b32_e32 v96, 16, v139
	v_add_f32_e32 v96, v148, v96
	v_mul_f32_e32 v96, 0xbfb8aa3b, v96
	v_exp_f32_e32 v96, v96
	v_lshlrev_b32_e32 v130, 16, v135
	v_cndmask_b32_e64 v138, 0, v130, s[40:41]
	v_lshlrev_b32_e32 v130, 16, v131
	v_add_f32_e32 v96, 1.0, v96
	v_rcp_f32_e32 v96, v96
	s_nop 0
	v_fmac_f32_e32 v138, v96, v130
	v_and_b32_e32 v96, 0xffff0000, v139
	v_add_f32_e32 v96, v149, v96
	v_mul_f32_e32 v96, 0xbfb8aa3b, v96
	v_exp_f32_e32 v96, v96
	v_and_b32_e32 v130, 0xffff0000, v135
	v_cndmask_b32_e64 v135, 0, v130, s[40:41]
	v_and_b32_e32 v130, 0xffff0000, v131
	v_add_f32_e32 v96, 1.0, v96
	v_rcp_f32_e32 v96, v96
	s_nop 0
	v_fmac_f32_e32 v135, v96, v130
	v_lshlrev_b32_e32 v96, 16, v140
	v_add_f32_e32 v96, v142, v96
	v_mul_f32_e32 v96, 0xbfb8aa3b, v96
	v_exp_f32_e32 v96, v96
	v_lshlrev_b32_e32 v130, 16, v136
	v_cndmask_b32_e64 v139, 0, v130, s[40:41]
	v_lshlrev_b32_e32 v130, 16, v132
	v_add_f32_e32 v96, 1.0, v96
	v_rcp_f32_e32 v96, v96
	s_nop 0
	v_fmac_f32_e32 v139, v96, v130
	v_and_b32_e32 v96, 0xffff0000, v140
	v_add_f32_e32 v96, v143, v96
	v_mul_f32_e32 v96, 0xbfb8aa3b, v96
	v_exp_f32_e32 v96, v96
	v_and_b32_e32 v130, 0xffff0000, v136
	v_cndmask_b32_e64 v136, 0, v130, s[40:41]
	v_and_b32_e32 v130, 0xffff0000, v132
	v_add_f32_e32 v96, 1.0, v96
	v_rcp_f32_e32 v96, v96
	s_nop 0
	v_fmac_f32_e32 v136, v96, v130
	v_lshlrev_b32_e32 v96, 16, v141
	v_add_f32_e32 v96, v144, v96
	v_mul_f32_e32 v96, 0xbfb8aa3b, v96
	v_exp_f32_e32 v96, v96
	v_lshlrev_b32_e32 v130, 16, v137
	v_cndmask_b32_e64 v140, 0, v130, s[40:41]
	v_lshlrev_b32_e32 v130, 16, v133
	v_add_f32_e32 v96, 1.0, v96
	v_rcp_f32_e32 v96, v96
	s_nop 0
	v_fmac_f32_e32 v140, v96, v130
	v_and_b32_e32 v96, 0xffff0000, v141
	v_add_f32_e32 v96, v145, v96
	v_mul_f32_e32 v96, 0xbfb8aa3b, v96
	v_exp_f32_e32 v96, v96
	v_and_b32_e32 v130, 0xffff0000, v137
	v_cndmask_b32_e64 v137, 0, v130, s[40:41]
	v_and_b32_e32 v130, 0xffff0000, v133
	v_add_f32_e32 v96, 1.0, v96
	v_rcp_f32_e32 v96, v96
	s_nop 0
	v_fmac_f32_e32 v137, v96, v130
	v_cvt_pk_bf16_f32 v130, v146, v134
	v_cvt_pk_bf16_f32 v131, v138, v135
	v_lshl_add_u64 v[134:135], v[182:183], 0, v[186:187]
	v_cvt_pk_bf16_f32 v132, v139, v136
	v_cvt_pk_bf16_f32 v133, v140, v137
	global_store_dwordx4 v[134:135], v[130:133], off sc1
	s_waitcnt lgkmcnt(0)
	s_barrier
	s_branch .LBB0_191

; DI uint2 pack4(float a, float b, float c, float d) { return make_uint2(cvtpk(a, b), cvtpk(c, d)); }
; #define WAIT_L(n) asm volatile("s_waitcnt lgkmcnt(" #n ")":::"memory")
; #define BAR __builtin_amdgcn_s_barrier()
; #define WAIT_L(n) asm volatile("s_waitcnt lgkmcnt(" #n ")":::"memory")
; #define BAR __builtin_amdgcn_s_barrier()
; DI void gemm8_run(const GemmJob& ja, const GemmJob& jb, char* lds) {
;     ...
;               float v0 = acc[ai][bj][m][n][0], v1 = acc[ai][bj][m][n][1], v2 = acc[ai][bj][m][n][2], v3 = acc[ai][bj][m][n][3];
;               if (r2) { v0 = fmaxf(v0, 0.f); v1 = fmaxf(v1, 0.f); v2 = fmaxf(v2, 0.f); v3 = fmaxf(v3, 0.f); v0 *= v0; v1 *= v1; v2 *= v2; v3 *= v3; }
;               *reinterpret_cast<uint2*>(cst + (wr * 64 + m * 16 + fr) * 528 + (bj * 128 + wc * 32 + n * 16 + fq * 4) * 2) = pack4(v0, v1, v2, v3); } } }
;         WAIT_L(0); BAR;
;         u16* Cb = J.C + (size_t)(brow + ai * 128) * J.ldc + bcol;
; #pragma unroll
;         for (int it = 0; it < 8; ++it) { const int idx = it * 512 + tid; const int r = idx >> 5, c16 = idx & 31;
;           *reinterpret_cast<bf16x8*>(Cb + (size_t)r * J.ldc + c16 * 8) = *reinterpret_cast<const bf16x8*>(cst + r * 528 + c16 * 16); }
;         WAIT_L(0); BAR;
.LBB0_286:
	s_lshl_b64 s[12:13], s[12:13], 1
	s_add_u32 s12, s7, s12
	s_addc_u32 s13, s6, s13
	v_lshlrev_b32_e32 v68, 4, v130
	v_and_b32_e32 v96, 0x1f0, v68
	v_ashrrev_i32_e32 v70, 5, v130
	s_and_b64 s[6:7], s[8:9], exec
	v_cvt_pk_bf16_f32 v64, v64, v65
	v_add_u32_e32 v88, s97, v96
	v_mul_lo_u32 v71, v70, s11
	s_cselect_b32 s6, s52, s58
	v_cvt_pk_bf16_f32 v65, v66, v67
	ds_write_b64 v126, v[64:65] offset:25632
	v_mov_b32_e32 v64, s96
	v_lshl_add_u64 v[68:69], s[12:13], 0, v[96:97]
	v_mul_hi_u32_u24_e32 v65, s6, v64
	v_mul_u32_u24_e32 v64, s6, v64
	v_add_u32_e32 v89, v88, v71
	s_waitcnt lgkmcnt(0)
	s_barrier
	v_lshl_add_u64 v[94:95], v[64:65], 1, v[68:69]
	ds_read_b128 v[64:67], v89
	s_cselect_b32 s2, s53, s59
	v_ashrrev_i32_e32 v71, 31, v70
	v_mul_lo_u32 v71, s6, v71
	v_mul_lo_u32 v72, s2, v70
	v_mad_u64_u32 v[78:79], s[8:9], s6, v70, 0
	v_add3_u32 v79, v79, v71, v72
	v_lshl_add_u64 v[70:71], v[78:79], 1, v[94:95]
	s_waitcnt lgkmcnt(0)
	global_store_dwordx4 v[70:71], v[64:67], off sc1
	s_and_b64 vcc, exec, s[40:41]
	s_nop 0
	v_add_u32_e32 v64, 0x200, v130
	v_ashrrev_i32_e32 v70, 5, v64
	v_mul_lo_u32 v64, v70, s11
	v_add_u32_e32 v87, v88, v64
	ds_read_b128 v[64:67], v87
	v_ashrrev_i32_e32 v71, 31, v70
	v_mul_lo_u32 v71, s6, v71
	v_mul_lo_u32 v72, s2, v70
	v_mad_u64_u32 v[80:81], s[8:9], s6, v70, 0
	v_add3_u32 v81, v81, v71, v72
	v_lshl_add_u64 v[70:71], v[80:81], 1, v[94:95]
	s_waitcnt lgkmcnt(0)
	global_store_dwordx4 v[70:71], v[64:67], off sc1
	s_nop 1
	v_add_u32_e32 v64, 0x400, v130
	v_ashrrev_i32_e32 v70, 5, v64
	v_mul_lo_u32 v64, v70, s11
	v_add_u32_e32 v85, v88, v64
	ds_read_b128 v[64:67], v85
	v_ashrrev_i32_e32 v71, 31, v70
	v_mul_lo_u32 v71, s6, v71
	v_mul_lo_u32 v74, s2, v70
	v_mad_u64_u32 v[72:73], s[8:9], s6, v70, 0
	v_add3_u32 v73, v73, v71, v74
	v_lshl_add_u64 v[70:71], v[72:73], 1, v[94:95]
	s_waitcnt lgkmcnt(0)
	global_store_dwordx4 v[70:71], v[64:67], off sc1
	s_nop 1
	v_add_u32_e32 v64, 0x600, v130
	v_ashrrev_i32_e32 v70, 5, v64
	v_mul_lo_u32 v64, v70, s11
	v_add_u32_e32 v83, v88, v64
	ds_read_b128 v[64:67], v83
	v_ashrrev_i32_e32 v71, 31, v70
	v_mul_lo_u32 v71, s6, v71
	v_mul_lo_u32 v74, s2, v70
	v_mad_u64_u32 v[76:77], s[8:9], s6, v70, 0
	v_add3_u32 v77, v77, v71, v74
	v_lshl_add_u64 v[70:71], v[76:77], 1, v[94:95]
	s_waitcnt lgkmcnt(0)
	global_store_dwordx4 v[70:71], v[64:67], off sc1
	s_nop 1
	v_add_u32_e32 v64, 0x800, v130
	v_ashrrev_i32_e32 v64, 5, v64
	v_mul_lo_u32 v65, v64, s11
	v_add_u32_e32 v82, v88, v65
	ds_read_b128 v[90:93], v82
	v_ashrrev_i32_e32 v65, 31, v64
	v_mul_lo_u32 v66, s6, v65
	v_mul_lo_u32 v67, s2, v64
	v_mad_u64_u32 v[64:65], s[8:9], s6, v64, 0
	v_add3_u32 v65, v65, v66, v67
	v_lshl_add_u64 v[66:67], v[64:65], 1, v[94:95]
	s_waitcnt lgkmcnt(0)
	global_store_dwordx4 v[66:67], v[90:93], off sc1
	v_add_u32_e32 v66, 0xa00, v130
	v_ashrrev_i32_e32 v66, 5, v66
	v_mul_lo_u32 v67, v66, s11
	v_add_u32_e32 v84, v88, v67
	ds_read_b128 v[90:93], v84
	v_ashrrev_i32_e32 v67, 31, v66
	v_mul_lo_u32 v67, s6, v67
	v_mul_lo_u32 v70, s2, v66
	v_mad_u64_u32 v[74:75], s[8:9], s6, v66, 0
	v_add3_u32 v75, v75, v67, v70
	v_lshl_add_u64 v[66:67], v[74:75], 1, v[94:95]
	s_waitcnt lgkmcnt(0)
	global_store_dwordx4 v[66:67], v[90:93], off sc1
	v_add_u32_e32 v66, 0xc00, v130
	v_ashrrev_i32_e32 v66, 5, v66
	v_mul_lo_u32 v67, v66, s11
	v_add_u32_e32 v86, v88, v67
	ds_read_b128 v[90:93], v86
	v_ashrrev_i32_e32 v67, 31, v66
	v_mul_lo_u32 v67, s6, v67
	v_mul_lo_u32 v96, s2, v66
	v_mad_u64_u32 v[70:71], s[8:9], s6, v66, 0
	v_add3_u32 v71, v71, v67, v96
	v_lshl_add_u64 v[66:67], v[70:71], 1, v[94:95]
	s_waitcnt lgkmcnt(0)
	global_store_dwordx4 v[66:67], v[90:93], off sc1
	v_add_u32_e32 v66, 0xe00, v130
	v_ashrrev_i32_e32 v66, 5, v66
	v_mul_lo_u32 v67, v66, s11
	v_add_u32_e32 v88, v88, v67
	ds_read_b128 v[90:93], v88
	v_ashrrev_i32_e32 v67, 31, v66
	v_mul_lo_u32 v96, s6, v67
	v_mul_lo_u32 v98, s2, v66
	v_mad_u64_u32 v[66:67], s[8:9], s6, v66, 0
	v_add3_u32 v67, v67, v96, v98
	v_lshl_add_u64 v[94:95], v[66:67], 1, v[94:95]
	s_waitcnt lgkmcnt(0)
	global_store_dwordx4 v[94:95], v[90:93], off sc1
	s_waitcnt lgkmcnt(0)
	s_barrier
	s_cbranch_vccnz .LBB0_288
	v_max_f32_e32 v60, v60, v60
	v_max_f32_e32 v61, v61, v61
	v_max_f32_e32 v62, v62, v62
	v_max_f32_e32 v63, v63, v63
	v_max_f32_e32 v60, 0, v60
	v_max_f32_e32 v61, 0, v61
	v_max_f32_e32 v62, 0, v62
	v_max_f32_e32 v63, 0, v63
	v_pk_mul_f32 v[60:61], v[60:61], v[60:61]
	v_pk_mul_f32 v[62:63], v[62:63], v[62:63]

; DI bf16x8 pack8(const float* a) { u32x4 w = {cvtpk(a[0], a[1]), cvtpk(a[2], a[3]), cvtpk(a[4], a[5]), cvtpk(a[6], a[7])}; return *reinterpret_cast<bf16x8*>(&w); }
; DI int tid_() { int t = threadIdx.x; asm volatile("" : "+v"(t)); return t; }
; DI int bid_() { int b = blockIdx.x; asm volatile("" : "+s"(b)); return b; }
; DI void cvt_weight_T(const float* src, u16* dst, int K, int Nsrc, int Npad, float* tile) {
;   const int tid = tid_(), tk = K >> 6, tn = Npad >> 6;
;   for (int t = bid_(); t < tk * tn; t += gridDim.x) {
;     const int k0 = (t % tk) * 64, n0 = (t / tk) * 64;
;     __syncthreads();
;     { const int r = tid >> 4, c4 = (tid & 15) * 4;
; #pragma unroll
;       for (int i = 0; i < 2; ++i) { const int k = r + 32 * i; float4 v = make_float4(0.f, 0.f, 0.f, 0.f);
;         if (n0 < Nsrc) v = *reinterpret_cast<const float4*>(src + (size_t)(k0 + k) * Nsrc + n0 + c4);
;         float* tp = tile + k * 65 + c4; tp[0] = v.x; tp[1] = v.y; tp[2] = v.z; tp[3] = v.w; } }
;     __syncthreads();
;     { const int n = tid >> 3, k8 = (tid & 7) * 8; float a[8];
; #pragma unroll
;       for (int j = 0; j < 8; ++j) a[j] = tile[(k8 + j) * 65 + n];
;       *reinterpret_cast<bf16x8*>(dst + (size_t)(n0 + n) * K + k0 + k8) = pack8(a); }
;   }
.LBB0_323:
	s_waitcnt vmcnt(1)
	ds_write2_b32 v12, v0, v1 offset1:1
	ds_write2_b32 v12, v2, v3 offset0:2 offset1:3
	v_add_u32_e32 v0, 0x2080, v12
	s_waitcnt vmcnt(0)
	ds_write2_b32 v0, v4, v5 offset1:1
	v_add_u32_e32 v0, 0x2088, v12
	ds_write2_b32 v0, v6, v7 offset1:1
	s_waitcnt lgkmcnt(0)
	s_barrier
	ds_read2_b32 v[0:1], v13 offset1:65
	ds_read2_b32 v[2:3], v13 offset0:130 offset1:195
	v_add_u32_e32 v6, 0x400, v13
	ds_read2_b32 v[4:5], v6 offset0:4 offset1:69
	ds_read2_b32 v[6:7], v6 offset0:134 offset1:199
	s_waitcnt lgkmcnt(3)
	v_cvt_pk_bf16_f32 v0, v0, v1
	s_waitcnt lgkmcnt(2)
	v_cvt_pk_bf16_f32 v1, v2, v3
	s_waitcnt lgkmcnt(1)
	v_cvt_pk_bf16_f32 v2, v4, v5
	v_add_u32_e32 v4, s38, v11
	v_ashrrev_i32_e32 v5, 31, v4
	v_lshlrev_b64 v[4:5], 11, v[4:5]
	v_lshl_add_u64 v[4:5], s[12:13], 0, v[4:5]
	s_ashr_i32 s37, s36, 31
	v_lshl_add_u64 v[4:5], s[36:37], 1, v[4:5]
	v_lshl_add_u64 v[4:5], v[4:5], 0, v[96:97]
	s_waitcnt lgkmcnt(0)
	v_cvt_pk_bf16_f32 v3, v6, v7
	global_store_dwordx4 v[4:5], v[0:3], off sc1
	s_load_dword s2, s[34:35], 0x10
	s_waitcnt lgkmcnt(0)
	s_lshr_b32 s2, s2, 16
	s_cmp_lg_u32 s2, 0
	s_cselect_b64 s[36:37], -1, 0
	s_cmp_lg_u64 s[36:37], 0
	s_addc_u32 s6, s6, s30
	s_cmpk_lt_i32 s6, 0x7c0
	s_cbranch_scc0 .LBB0_326

; DI bf16x8 pack8(const float* a) { u32x4 w = {cvtpk(a[0], a[1]), cvtpk(a[2], a[3]), cvtpk(a[4], a[5]), cvtpk(a[6], a[7])}; return *reinterpret_cast<bf16x8*>(&w); }
; DI int tid_() { int t = threadIdx.x; asm volatile("" : "+v"(t)); return t; }
; DI int bid_() { int b = blockIdx.x; asm volatile("" : "+s"(b)); return b; }
; DI void cvt_weight_T(const float* src, u16* dst, int K, int Nsrc, int Npad, float* tile) {
;   const int tid = tid_(), tk = K >> 6, tn = Npad >> 6;
;   for (int t = bid_(); t < tk * tn; t += gridDim.x) {
;     const int k0 = (t % tk) * 64, n0 = (t / tk) * 64;
;     __syncthreads();
;     { const int r = tid >> 4, c4 = (tid & 15) * 4;
; #pragma unroll
;       for (int i = 0; i < 2; ++i) { const int k = r + 32 * i; float4 v = make_float4(0.f, 0.f, 0.f, 0.f);
;         if (n0 < Nsrc) v = *reinterpret_cast<const float4*>(src + (size_t)(k0 + k) * Nsrc + n0 + c4);
;         float* tp = tile + k * 65 + c4; tp[0] = v.x; tp[1] = v.y; tp[2] = v.z; tp[3] = v.w; } }
;     __syncthreads();
;     { const int n = tid >> 3, k8 = (tid & 7) * 8; float a[8];
; #pragma unroll
;       for (int j = 0; j < 8; ++j) a[j] = tile[(k8 + j) * 65 + n];
;       *reinterpret_cast<bf16x8*>(dst + (size_t)(n0 + n) * K + k0 + k8) = pack8(a); }
;   }
.LBB0_328:
	s_mul_hi_i32 s2, s6, 0x2aaaaaab
	s_lshr_b32 s7, s2, 31
	s_add_i32 s2, s2, s7
	s_mul_i32 s7, s2, 6
	s_lshl_b32 s38, s2, 6
	s_sub_i32 s2, s6, s7
	s_ashr_i32 s39, s38, 31
	s_lshl_b32 s40, s2, 6
	v_lshl_add_u64 v[10:11], s[38:39], 2, v[0:1]
	v_add_u32_e32 v8, s40, v2
	v_mad_i64_i32 v[6:7], s[42:43], v8, s1, v[10:11]
	s_barrier
	v_add_u32_e32 v12, 32, v8
	global_load_dwordx4 v[6:9], v[6:7], off
	v_mad_i64_i32 v[10:11], s[42:43], v12, s1, v[10:11]
	global_load_dwordx4 v[10:13], v[10:11], off
	v_add_u32_e32 v16, 0x2080, v4
	v_add_u32_e32 v17, 0x2088, v4
	v_add_u32_e32 v18, 0x400, v5
	v_mov_b64_e32 v[14:15], s[36:37]
	v_add_u32_e32 v19, s38, v3
	s_movk_i32 s2, 0x300
	v_mad_i64_i32 v[14:15], s[38:39], v19, s2, v[14:15]
	s_ashr_i32 s41, s40, 31
	v_lshl_add_u64 v[14:15], s[40:41], 1, v[14:15]
	v_lshl_add_u64 v[14:15], v[14:15], 0, v[96:97]
	s_waitcnt vmcnt(1)
	ds_write2_b32 v4, v6, v7 offset1:1
	ds_write2_b32 v4, v8, v9 offset0:2 offset1:3
	s_waitcnt vmcnt(0)
	ds_write2_b32 v16, v10, v11 offset1:1
	ds_write2_b32 v17, v12, v13 offset1:1
	s_waitcnt lgkmcnt(0)
	s_barrier
	ds_read2_b32 v[6:7], v5 offset1:65
	ds_read2_b32 v[8:9], v5 offset0:130 offset1:195
	ds_read2_b32 v[10:11], v18 offset0:4 offset1:69
	ds_read2_b32 v[12:13], v18 offset0:134 offset1:199
	s_waitcnt lgkmcnt(3)
	v_cvt_pk_bf16_f32 v6, v6, v7
	s_waitcnt lgkmcnt(2)
	v_cvt_pk_bf16_f32 v7, v8, v9
	s_waitcnt lgkmcnt(1)
	v_cvt_pk_bf16_f32 v8, v10, v11
	s_waitcnt lgkmcnt(0)
	v_cvt_pk_bf16_f32 v9, v12, v13
	global_store_dwordx4 v[14:15], v[6:9], off sc1
	s_load_dword s2, s[34:35], 0x10
	s_waitcnt lgkmcnt(0)
	s_lshr_b32 s2, s2, 16
	s_cmp_lg_u32 s2, 0
	s_cselect_b64 s[38:39], -1, 0
	s_cmp_lg_u64 s[38:39], 0
	s_addc_u32 s6, s6, s30
	s_cmpk_lt_i32 s6, 0x90
	s_cbranch_scc1 .LBB0_328

; DI bf16x8 pack8(const float* a) { u32x4 w = {cvtpk(a[0], a[1]), cvtpk(a[2], a[3]), cvtpk(a[4], a[5]), cvtpk(a[6], a[7])}; return *reinterpret_cast<bf16x8*>(&w); }
; DI int tid_() { int t = threadIdx.x; asm volatile("" : "+v"(t)); return t; }
; DI int bid_() { int b = blockIdx.x; asm volatile("" : "+s"(b)); return b; }
; DI void cvt_weight_T(const float* src, u16* dst, int K, int Nsrc, int Npad, float* tile) {
;   const int tid = tid_(), tk = K >> 6, tn = Npad >> 6;
;   for (int t = bid_(); t < tk * tn; t += gridDim.x) {
;     const int k0 = (t % tk) * 64, n0 = (t / tk) * 64;
;     __syncthreads();
;     { const int r = tid >> 4, c4 = (tid & 15) * 4;
; #pragma unroll
;       for (int i = 0; i < 2; ++i) { const int k = r + 32 * i; float4 v = make_float4(0.f, 0.f, 0.f, 0.f);
;         if (n0 < Nsrc) v = *reinterpret_cast<const float4*>(src + (size_t)(k0 + k) * Nsrc + n0 + c4);
;         float* tp = tile + k * 65 + c4; tp[0] = v.x; tp[1] = v.y; tp[2] = v.z; tp[3] = v.w; } }
;     __syncthreads();
;     { const int n = tid >> 3, k8 = (tid & 7) * 8; float a[8];
; #pragma unroll
;       for (int j = 0; j < 8; ++j) a[j] = tile[(k8 + j) * 65 + n];
;       *reinterpret_cast<bf16x8*>(dst + (size_t)(n0 + n) * K + k0 + k8) = pack8(a); }
;   }
.LBB0_331:
	s_ashr_i32 s2, s6, 31
	s_lshr_b32 s2, s2, 30
	s_add_i32 s2, s6, s2
	s_and_b32 s7, s2, 0x3fffffc
	s_sub_i32 s7, s6, s7
	s_lshl_b32 s2, s2, 4
	s_lshl_b32 s40, s7, 6
	s_and_b32 s38, s2, 0xffffffc0
	v_add_u32_e32 v6, s40, v2
	s_ashr_i32 s39, s38, 31
	v_ashrrev_i32_e32 v7, 31, v6
	v_lshl_add_u64 v[10:11], s[38:39], 2, v[0:1]
	v_add_u32_e32 v8, 32, v6
	v_lshlrev_b64 v[6:7], 13, v[6:7]
	v_ashrrev_i32_e32 v9, 31, v8
	v_lshl_add_u64 v[6:7], v[10:11], 0, v[6:7]
	s_barrier
	v_lshlrev_b64 v[12:13], 13, v[8:9]
	global_load_dwordx4 v[6:9], v[6:7], off
	v_lshl_add_u64 v[10:11], v[10:11], 0, v[12:13]
	global_load_dwordx4 v[10:13], v[10:11], off
	v_add_u32_e32 v14, s38, v3
	v_add_u32_e32 v16, 0x2080, v4
	v_add_u32_e32 v17, 0x2088, v4
	v_add_u32_e32 v18, 0x400, v5
	v_ashrrev_i32_e32 v15, 31, v14
	v_lshlrev_b64 v[14:15], 9, v[14:15]
	s_ashr_i32 s41, s40, 31
	v_lshl_add_u64 v[14:15], s[36:37], 0, v[14:15]
	v_lshl_add_u64 v[14:15], s[40:41], 1, v[14:15]
	v_lshl_add_u64 v[14:15], v[14:15], 0, v[96:97]
	s_waitcnt vmcnt(1)
	ds_write2_b32 v4, v6, v7 offset1:1
	ds_write2_b32 v4, v8, v9 offset0:2 offset1:3
	s_waitcnt vmcnt(0)
	ds_write2_b32 v16, v10, v11 offset1:1
	ds_write2_b32 v17, v12, v13 offset1:1
	s_waitcnt lgkmcnt(0)
	s_barrier
	ds_read2_b32 v[6:7], v5 offset1:65
	ds_read2_b32 v[8:9], v5 offset0:130 offset1:195
	ds_read2_b32 v[10:11], v18 offset0:4 offset1:69
	ds_read2_b32 v[12:13], v18 offset0:134 offset1:199
	s_waitcnt lgkmcnt(3)
	v_cvt_pk_bf16_f32 v6, v6, v7
	s_waitcnt lgkmcnt(2)
	v_cvt_pk_bf16_f32 v7, v8, v9
	s_waitcnt lgkmcnt(1)
	v_cvt_pk_bf16_f32 v8, v10, v11
	s_waitcnt lgkmcnt(0)
	v_cvt_pk_bf16_f32 v9, v12, v13
	global_store_dwordx4 v[14:15], v[6:9], off sc1
	s_load_dword s2, s[34:35], 0x10
	s_waitcnt lgkmcnt(0)
	s_lshr_b32 s2, s2, 16
	s_cmp_lg_u32 s2, 0
	s_cselect_b64 s[38:39], -1, 0
	s_cmp_lg_u64 s[38:39], 0
	s_addc_u32 s6, s6, s30
	s_cmpk_lt_i32 s6, 0x80
	s_cbranch_scc1 .LBB0_331

; DI bf16x8 pack8(const float* a) { u32x4 w = {cvtpk(a[0], a[1]), cvtpk(a[2], a[3]), cvtpk(a[4], a[5]), cvtpk(a[6], a[7])}; return *reinterpret_cast<bf16x8*>(&w); }
; DI int tid_() { int t = threadIdx.x; asm volatile("" : "+v"(t)); return t; }
; DI int bid_() { int b = blockIdx.x; asm volatile("" : "+s"(b)); return b; }
; DI void cvt_weight_T(const float* src, u16* dst, int K, int Nsrc, int Npad, float* tile) {
;   const int tid = tid_(), tk = K >> 6, tn = Npad >> 6;
;   for (int t = bid_(); t < tk * tn; t += gridDim.x) {
;     const int k0 = (t % tk) * 64, n0 = (t / tk) * 64;
;     __syncthreads();
;     { const int r = tid >> 4, c4 = (tid & 15) * 4;
; #pragma unroll
;       for (int i = 0; i < 2; ++i) { const int k = r + 32 * i; float4 v = make_float4(0.f, 0.f, 0.f, 0.f);
;         if (n0 < Nsrc) v = *reinterpret_cast<const float4*>(src + (size_t)(k0 + k) * Nsrc + n0 + c4);
;         float* tp = tile + k * 65 + c4; tp[0] = v.x; tp[1] = v.y; tp[2] = v.z; tp[3] = v.w; } }
;     __syncthreads();
;     { const int n = tid >> 3, k8 = (tid & 7) * 8; float a[8];
; #pragma unroll
;       for (int j = 0; j < 8; ++j) a[j] = tile[(k8 + j) * 65 + n];
;       *reinterpret_cast<bf16x8*>(dst + (size_t)(n0 + n) * K + k0 + k8) = pack8(a); }
;   }
.LBB0_334:
	s_ashr_i32 s2, s6, 31
	s_lshr_b32 s2, s2, 28
	s_add_i32 s2, s6, s2
	s_and_b32 s7, s2, 0x3fffff0
	s_sub_i32 s7, s6, s7
	s_lshl_b32 s2, s2, 2
	s_lshl_b32 s42, s7, 6
	s_and_b32 s40, s2, 0xffffffc0
	v_add_u32_e32 v6, s42, v2
	s_ashr_i32 s41, s40, 31
	v_ashrrev_i32_e32 v7, 31, v6
	v_lshl_add_u64 v[10:11], s[40:41], 2, v[0:1]
	v_add_u32_e32 v8, 32, v6
	v_lshlrev_b64 v[6:7], 12, v[6:7]
	v_ashrrev_i32_e32 v9, 31, v8
	v_lshl_add_u64 v[6:7], v[10:11], 0, v[6:7]
	s_barrier
	v_lshlrev_b64 v[12:13], 12, v[8:9]
	global_load_dwordx4 v[6:9], v[6:7], off
	v_lshl_add_u64 v[10:11], v[10:11], 0, v[12:13]
	global_load_dwordx4 v[10:13], v[10:11], off
	v_add_u32_e32 v14, s40, v3
	v_add_u32_e32 v16, 0x2080, v4
	v_add_u32_e32 v17, 0x2088, v4
	v_add_u32_e32 v18, 0x400, v5
	v_ashrrev_i32_e32 v15, 31, v14
	v_lshlrev_b64 v[14:15], 11, v[14:15]
	s_ashr_i32 s43, s42, 31
	v_lshl_add_u64 v[14:15], s[38:39], 0, v[14:15]
	v_lshl_add_u64 v[14:15], s[42:43], 1, v[14:15]
	v_lshl_add_u64 v[14:15], v[14:15], 0, v[96:97]
	s_waitcnt vmcnt(1)
	ds_write2_b32 v4, v6, v7 offset1:1
	ds_write2_b32 v4, v8, v9 offset0:2 offset1:3
	s_waitcnt vmcnt(0)
	ds_write2_b32 v16, v10, v11 offset1:1
	ds_write2_b32 v17, v12, v13 offset1:1
	s_waitcnt lgkmcnt(0)
	s_barrier
	ds_read2_b32 v[6:7], v5 offset1:65
	ds_read2_b32 v[8:9], v5 offset0:130 offset1:195
	ds_read2_b32 v[10:11], v18 offset0:4 offset1:69
	ds_read2_b32 v[12:13], v18 offset0:134 offset1:199
	s_waitcnt lgkmcnt(3)
	v_cvt_pk_bf16_f32 v6, v6, v7
	s_waitcnt lgkmcnt(2)
	v_cvt_pk_bf16_f32 v7, v8, v9
	s_waitcnt lgkmcnt(1)
	v_cvt_pk_bf16_f32 v8, v10, v11
	s_waitcnt lgkmcnt(0)
	v_cvt_pk_bf16_f32 v9, v12, v13
	global_store_dwordx4 v[14:15], v[6:9], off sc1
	s_load_dword s2, s[34:35], 0x10
	s_waitcnt lgkmcnt(0)
	s_lshr_b32 s2, s2, 16
	s_cmp_lg_u32 s2, 0
	s_cselect_b64 s[40:41], -1, 0
	s_cmp_lg_u64 s[40:41], 0
	s_addc_u32 s6, s6, s30
	s_cmpk_lt_i32 s6, 0x100
	s_cbranch_scc1 .LBB0_334

; DI bf16x8 pack8(const float* a) { u32x4 w = {cvtpk(a[0], a[1]), cvtpk(a[2], a[3]), cvtpk(a[4], a[5]), cvtpk(a[6], a[7])}; return *reinterpret_cast<bf16x8*>(&w); }
; DI int tid_() { int t = threadIdx.x; asm volatile("" : "+v"(t)); return t; }
; DI int bid_() { int b = blockIdx.x; asm volatile("" : "+s"(b)); return b; }
; DI void cvt_weight_T(const float* src, u16* dst, int K, int Nsrc, int Npad, float* tile) {
;   const int tid = tid_(), tk = K >> 6, tn = Npad >> 6;
;   for (int t = bid_(); t < tk * tn; t += gridDim.x) {
;     const int k0 = (t % tk) * 64, n0 = (t / tk) * 64;
;     __syncthreads();
;     { const int r = tid >> 4, c4 = (tid & 15) * 4;
; #pragma unroll
;       for (int i = 0; i < 2; ++i) { const int k = r + 32 * i; float4 v = make_float4(0.f, 0.f, 0.f, 0.f);
;         if (n0 < Nsrc) v = *reinterpret_cast<const float4*>(src + (size_t)(k0 + k) * Nsrc + n0 + c4);
;         float* tp = tile + k * 65 + c4; tp[0] = v.x; tp[1] = v.y; tp[2] = v.z; tp[3] = v.w; } }
;     __syncthreads();
;     { const int n = tid >> 3, k8 = (tid & 7) * 8; float a[8];
; #pragma unroll
;       for (int j = 0; j < 8; ++j) a[j] = tile[(k8 + j) * 65 + n];
;       *reinterpret_cast<bf16x8*>(dst + (size_t)(n0 + n) * K + k0 + k8) = pack8(a); }
;   }
.LBB0_340:
	s_ashr_i32 s2, s6, 31
	s_lshr_b32 s2, s2, 28
	s_add_i32 s2, s6, s2
	s_and_b32 s7, s2, 0x3fffff0
	s_sub_i32 s7, s6, s7
	s_lshl_b32 s2, s2, 2
	s_lshl_b32 s40, s7, 6
	s_and_b32 s36, s2, 0xffffffc0
	v_add_u32_e32 v6, s40, v2
	s_ashr_i32 s37, s36, 31
	v_ashrrev_i32_e32 v7, 31, v6
	v_lshl_add_u64 v[10:11], s[36:37], 2, v[0:1]
	v_add_u32_e32 v8, 32, v6
	v_lshlrev_b64 v[6:7], 12, v[6:7]
	v_ashrrev_i32_e32 v9, 31, v8
	v_lshl_add_u64 v[6:7], v[10:11], 0, v[6:7]
	s_barrier
	v_lshlrev_b64 v[12:13], 12, v[8:9]
	global_load_dwordx4 v[6:9], v[6:7], off
	v_lshl_add_u64 v[10:11], v[10:11], 0, v[12:13]
	global_load_dwordx4 v[10:13], v[10:11], off
	v_add_u32_e32 v14, s36, v3
	v_add_u32_e32 v16, 0x2080, v4
	v_add_u32_e32 v17, 0x2088, v4
	v_add_u32_e32 v18, 0x400, v5
	v_ashrrev_i32_e32 v15, 31, v14
	v_lshlrev_b64 v[14:15], 11, v[14:15]
	s_ashr_i32 s41, s40, 31
	v_lshl_add_u64 v[14:15], s[38:39], 0, v[14:15]
	v_lshl_add_u64 v[14:15], s[40:41], 1, v[14:15]
	v_lshl_add_u64 v[14:15], v[14:15], 0, v[96:97]
	s_waitcnt vmcnt(1)
	ds_write2_b32 v4, v6, v7 offset1:1
	ds_write2_b32 v4, v8, v9 offset0:2 offset1:3
	s_waitcnt vmcnt(0)
	ds_write2_b32 v16, v10, v11 offset1:1
	ds_write2_b32 v17, v12, v13 offset1:1
	s_waitcnt lgkmcnt(0)
	s_barrier
	ds_read2_b32 v[6:7], v5 offset1:65
	ds_read2_b32 v[8:9], v5 offset0:130 offset1:195
	ds_read2_b32 v[10:11], v18 offset0:4 offset1:69
	ds_read2_b32 v[12:13], v18 offset0:134 offset1:199
	s_waitcnt lgkmcnt(3)
	v_cvt_pk_bf16_f32 v6, v6, v7
	s_waitcnt lgkmcnt(2)
	v_cvt_pk_bf16_f32 v7, v8, v9
	s_waitcnt lgkmcnt(1)
	v_cvt_pk_bf16_f32 v8, v10, v11
	s_waitcnt lgkmcnt(0)
	v_cvt_pk_bf16_f32 v9, v12, v13
	global_store_dwordx4 v[14:15], v[6:9], off sc1
	s_load_dword s2, s[34:35], 0x10
	s_waitcnt lgkmcnt(0)
	s_lshr_b32 s2, s2, 16
	s_cmp_lg_u32 s2, 0
	s_cselect_b64 s[36:37], -1, 0
	s_cmp_lg_u64 s[36:37], 0
	s_addc_u32 s6, s6, s30
	s_cmpk_lt_i32 s6, 0x100
	s_cbranch_scc1 .LBB0_340

; DI bf16x8 pack8(const float* a) { u32x4 w = {cvtpk(a[0], a[1]), cvtpk(a[2], a[3]), cvtpk(a[4], a[5]), cvtpk(a[6], a[7])}; return *reinterpret_cast<bf16x8*>(&w); }
; DI int tid_() { int t = threadIdx.x; asm volatile("" : "+v"(t)); return t; }
; DI int bid_() { int b = blockIdx.x; asm volatile("" : "+s"(b)); return b; }
; DI void cvt_weight_T(const float* src, u16* dst, int K, int Nsrc, int Npad, float* tile) {
;   const int tid = tid_(), tk = K >> 6, tn = Npad >> 6;
;   for (int t = bid_(); t < tk * tn; t += gridDim.x) {
;     const int k0 = (t % tk) * 64, n0 = (t / tk) * 64;
;     __syncthreads();
;     { const int r = tid >> 4, c4 = (tid & 15) * 4;
; #pragma unroll
;       for (int i = 0; i < 2; ++i) { const int k = r + 32 * i; float4 v = make_float4(0.f, 0.f, 0.f, 0.f);
;         if (n0 < Nsrc) v = *reinterpret_cast<const float4*>(src + (size_t)(k0 + k) * Nsrc + n0 + c4);
;         float* tp = tile + k * 65 + c4; tp[0] = v.x; tp[1] = v.y; tp[2] = v.z; tp[3] = v.w; } }
;     __syncthreads();
;     { const int n = tid >> 3, k8 = (tid & 7) * 8; float a[8];
; #pragma unroll
;       for (int j = 0; j < 8; ++j) a[j] = tile[(k8 + j) * 65 + n];
;       *reinterpret_cast<bf16x8*>(dst + (size_t)(n0 + n) * K + k0 + k8) = pack8(a); }
;   }
.LBB0_343:
	s_ashr_i32 s2, s6, 31
	s_lshr_b32 s2, s2, 28
	s_add_i32 s2, s6, s2
	s_and_b32 s7, s2, 0x3fffff0
	s_sub_i32 s7, s6, s7
	s_lshl_b32 s2, s2, 2
	s_lshl_b32 s40, s7, 6
	s_and_b32 s38, s2, 0xffffffc0
	v_add_u32_e32 v6, s40, v2
	s_ashr_i32 s39, s38, 31
	v_ashrrev_i32_e32 v7, 31, v6
	v_lshl_add_u64 v[10:11], s[38:39], 2, v[0:1]
	v_add_u32_e32 v8, 32, v6
	v_lshlrev_b64 v[6:7], 14, v[6:7]
	v_ashrrev_i32_e32 v9, 31, v8
	v_lshl_add_u64 v[6:7], v[10:11], 0, v[6:7]
	s_barrier
	v_lshlrev_b64 v[12:13], 14, v[8:9]
	global_load_dwordx4 v[6:9], v[6:7], off
	v_lshl_add_u64 v[10:11], v[10:11], 0, v[12:13]
	global_load_dwordx4 v[10:13], v[10:11], off
	v_add_u32_e32 v14, s38, v3
	v_add_u32_e32 v16, 0x2080, v4
	v_add_u32_e32 v17, 0x2088, v4
	v_add_u32_e32 v18, 0x400, v5
	v_ashrrev_i32_e32 v15, 31, v14
	v_lshlrev_b64 v[14:15], 11, v[14:15]
	s_ashr_i32 s41, s40, 31
	v_lshl_add_u64 v[14:15], s[36:37], 0, v[14:15]
	v_lshl_add_u64 v[14:15], s[40:41], 1, v[14:15]
	v_lshl_add_u64 v[14:15], v[14:15], 0, v[96:97]
	s_waitcnt vmcnt(1)
	ds_write2_b32 v4, v6, v7 offset1:1
	ds_write2_b32 v4, v8, v9 offset0:2 offset1:3
	s_waitcnt vmcnt(0)
	ds_write2_b32 v16, v10, v11 offset1:1
	ds_write2_b32 v17, v12, v13 offset1:1
	s_waitcnt lgkmcnt(0)
	s_barrier
	ds_read2_b32 v[6:7], v5 offset1:65
	ds_read2_b32 v[8:9], v5 offset0:130 offset1:195
	ds_read2_b32 v[10:11], v18 offset0:4 offset1:69
	ds_read2_b32 v[12:13], v18 offset0:134 offset1:199
	s_waitcnt lgkmcnt(3)
	v_cvt_pk_bf16_f32 v6, v6, v7
	s_waitcnt lgkmcnt(2)
	v_cvt_pk_bf16_f32 v7, v8, v9
	s_waitcnt lgkmcnt(1)
	v_cvt_pk_bf16_f32 v8, v10, v11
	s_waitcnt lgkmcnt(0)
	v_cvt_pk_bf16_f32 v9, v12, v13
	global_store_dwordx4 v[14:15], v[6:9], off sc1
	s_load_dword s2, s[34:35], 0x10
	s_waitcnt lgkmcnt(0)
	s_lshr_b32 s2, s2, 16
	s_cmp_lg_u32 s2, 0
	s_cselect_b64 s[38:39], -1, 0
	s_cmp_lg_u64 s[38:39], 0
	s_addc_u32 s6, s6, s30
	s_cmpk_lt_i32 s6, 0x400
	s_cbranch_scc1 .LBB0_343

; DI bf16x8 pack8(const float* a) { u32x4 w = {cvtpk(a[0], a[1]), cvtpk(a[2], a[3]), cvtpk(a[4], a[5]), cvtpk(a[6], a[7])}; return *reinterpret_cast<bf16x8*>(&w); }
; DI int tid_() { int t = threadIdx.x; asm volatile("" : "+v"(t)); return t; }
; DI int bid_() { int b = blockIdx.x; asm volatile("" : "+s"(b)); return b; }
; DI void cvt_weight_T(const float* src, u16* dst, int K, int Nsrc, int Npad, float* tile) {
;   const int tid = tid_(), tk = K >> 6, tn = Npad >> 6;
;   for (int t = bid_(); t < tk * tn; t += gridDim.x) {
;     const int k0 = (t % tk) * 64, n0 = (t / tk) * 64;
;     __syncthreads();
;     { const int r = tid >> 4, c4 = (tid & 15) * 4;
; #pragma unroll
;       for (int i = 0; i < 2; ++i) { const int k = r + 32 * i; float4 v = make_float4(0.f, 0.f, 0.f, 0.f);
;         if (n0 < Nsrc) v = *reinterpret_cast<const float4*>(src + (size_t)(k0 + k) * Nsrc + n0 + c4);
;         float* tp = tile + k * 65 + c4; tp[0] = v.x; tp[1] = v.y; tp[2] = v.z; tp[3] = v.w; } }
;     __syncthreads();
;     { const int n = tid >> 3, k8 = (tid & 7) * 8; float a[8];
; #pragma unroll
;       for (int j = 0; j < 8; ++j) a[j] = tile[(k8 + j) * 65 + n];
;       *reinterpret_cast<bf16x8*>(dst + (size_t)(n0 + n) * K + k0 + k8) = pack8(a); }
;   }
.LBB0_346:
	s_ashr_i32 s2, s6, 31
	s_lshr_b32 s2, s2, 26
	s_add_i32 s2, s6, s2
	s_and_b32 s14, s2, 0xffffffc0
	s_sub_i32 s2, s6, s14
	s_lshl_b32 s36, s2, 6
	v_add_u32_e32 v6, s36, v2
	s_ashr_i32 s15, s14, 31
	v_ashrrev_i32_e32 v7, 31, v6
	v_lshl_add_u64 v[10:11], s[14:15], 2, v[0:1]
	v_add_u32_e32 v8, 32, v6
	v_lshlrev_b64 v[6:7], 12, v[6:7]
	v_ashrrev_i32_e32 v9, 31, v8
	v_lshl_add_u64 v[6:7], v[10:11], 0, v[6:7]
	s_barrier
	v_lshlrev_b64 v[12:13], 12, v[8:9]
	global_load_dwordx4 v[6:9], v[6:7], off
	v_lshl_add_u64 v[10:11], v[10:11], 0, v[12:13]
	global_load_dwordx4 v[10:13], v[10:11], off
	v_add_u32_e32 v14, s14, v3
	v_add_u32_e32 v16, 0x2080, v4
	v_add_u32_e32 v17, 0x2088, v4
	v_add_u32_e32 v18, 0x400, v5
	v_ashrrev_i32_e32 v15, 31, v14
	v_lshlrev_b64 v[14:15], 13, v[14:15]
	s_ashr_i32 s37, s36, 31
	v_lshl_add_u64 v[14:15], s[12:13], 0, v[14:15]
	v_lshl_add_u64 v[14:15], s[36:37], 1, v[14:15]
	v_lshl_add_u64 v[14:15], v[14:15], 0, v[96:97]
	s_waitcnt vmcnt(1)
	ds_write2_b32 v4, v6, v7 offset1:1
	ds_write2_b32 v4, v8, v9 offset0:2 offset1:3
	s_waitcnt vmcnt(0)
	ds_write2_b32 v16, v10, v11 offset1:1
	ds_write2_b32 v17, v12, v13 offset1:1
	s_waitcnt lgkmcnt(0)
	s_barrier
	ds_read2_b32 v[6:7], v5 offset1:65
	ds_read2_b32 v[8:9], v5 offset0:130 offset1:195
	ds_read2_b32 v[10:11], v18 offset0:4 offset1:69
	ds_read2_b32 v[12:13], v18 offset0:134 offset1:199
	s_waitcnt lgkmcnt(3)
	v_cvt_pk_bf16_f32 v6, v6, v7
	s_waitcnt lgkmcnt(2)
	v_cvt_pk_bf16_f32 v7, v8, v9
	s_waitcnt lgkmcnt(1)
	v_cvt_pk_bf16_f32 v8, v10, v11
	s_waitcnt lgkmcnt(0)
	v_cvt_pk_bf16_f32 v9, v12, v13
	global_store_dwordx4 v[14:15], v[6:9], off sc1
	s_load_dword s2, s[34:35], 0x10
	s_waitcnt lgkmcnt(0)
	s_lshr_b32 s2, s2, 16
	s_cmp_lg_u32 s2, 0
	s_cselect_b64 s[14:15], -1, 0
	s_cmp_lg_u64 s[14:15], 0
	s_addc_u32 s6, s6, s30
	s_cmpk_lt_i32 s6, 0x400
	s_cbranch_scc1 .LBB0_346
	s_branch .LBB0_320

; DI int tid_() { int t = threadIdx.x; asm volatile("" : "+v"(t)); return t; }
; DI int bid_() { int b = blockIdx.x; asm volatile("" : "+s"(b)); return b; }
; DI void phase_weights(const Params& p, char* lds) {
;     ...
;   float* rope = (float*)(p.ws + WS_ROPE);
;   for (int i = bid_() * 512 + tid_(); i < 16384 * 32; i += gridDim.x * 512) {
;     const int pos = i >> 5, j = i & 31;
;     const float inv = 1.0f / powf(10000.0f, (float)(2 * j) / 64.0f);
;     const float ang = (float)pos * inv;
;     rope[pos * 64 + j] = cosf(ang); rope[pos * 64 + 32 + j] = sinf(ang);
;   }
.LBB0_349:
	s_or_b64 exec, exec, s[14:15]
	v_mul_f32_e32 v7, v11, v11
	v_fmamk_f32 v8, v7, 0xb94c1982, v252
	v_fmaak_f32 v8, v7, v8, 0xbe2aaa9d
	v_mul_f32_e32 v8, v7, v8
	v_fmac_f32_e32 v11, v11, v8
	v_fmamk_f32 v8, v7, 0x37d75334, v238
	v_fmaak_f32 v8, v7, v8, 0x3d2aabf7
	v_fmaak_f32 v8, v7, v8, 0xbf000004
	v_fma_f32 v7, v7, v8, 1.0
	v_and_b32_e32 v8, 1, v10
	v_cmp_eq_u32_e64 s[36:37], 0, v8
	v_lshlrev_b32_e32 v8, 30, v10
	v_and_b32_e32 v8, 0x80000000, v8
	v_xor_b32_e32 v5, v6, v5
	v_cndmask_b32_e64 v7, v7, v11, s[36:37]
	v_xor_b32_e32 v5, v5, v8
	v_xor_b32_e32 v5, v5, v7
	v_add_u32_e32 v2, s6, v2
	s_mov_b32 s2, 0x7ffff
	v_cndmask_b32_e32 v5, v240, v5, vcc
	v_cmp_lt_i32_e32 vcc, s2, v2
	s_or_b64 s[12:13], vcc, s[12:13]
	global_store_dword v[0:1], v5, off offset:128 sc1
	s_andn2_b64 exec, exec, s[12:13]
	s_cbranch_execz .LBB0_358

; DI int tid_() { int t = threadIdx.x; asm volatile("" : "+v"(t)); return t; }
; DI int bid_() { int b = blockIdx.x; asm volatile("" : "+s"(b)); return b; }
; DI void phase_weights(const Params& p, char* lds) {
;     ...
;   float* rope = (float*)(p.ws + WS_ROPE);
;   for (int i = bid_() * 512 + tid_(); i < 16384 * 32; i += gridDim.x * 512) {
;     const int pos = i >> 5, j = i & 31;
;     const float inv = 1.0f / powf(10000.0f, (float)(2 * j) / 64.0f);
;     const float ang = (float)pos * inv;
;     rope[pos * 64 + j] = cosf(ang); rope[pos * 64 + 32 + j] = sinf(ang);
;   }
.LBB0_352:
	s_or_saveexec_b64 s[36:37], s[42:43]
	s_mov_b32 s2, 0x3f22f983
	v_mul_f32_e64 v9, |v5|, s2
	v_rndne_f32_e32 v9, v9
	s_xor_b64 exec, exec, s[36:37]
	v_cvt_i32_f32_e32 v1, v9
	s_mov_b32 s2, 0xbfc90fda
	v_fma_f32 v10, v9, s2, |v5|
	v_fmac_f32_e32 v10, 0xb3a22168, v9
	v_fmac_f32_e32 v10, 0xa7c234c4, v9
	s_or_b64 exec, exec, s[36:37]
	v_mul_f32_e32 v11, v10, v10
	v_fmamk_f32 v12, v11, 0xb94c1982, v252
	v_fmaak_f32 v12, v11, v12, 0xbe2aaa9d
	v_mul_f32_e32 v12, v11, v12
	v_fmac_f32_e32 v10, v10, v12
	v_fmamk_f32 v12, v11, 0x37d75334, v238
	v_fmaak_f32 v12, v11, v12, 0x3d2aabf7
	v_fmaak_f32 v12, v11, v12, 0xbf000004
	v_fma_f32 v11, v11, v12, 1.0
	v_and_b32_e32 v12, 1, v1
	v_cmp_eq_u32_e32 vcc, 0, v12
	v_lshlrev_b32_e32 v1, 30, v1
	s_brev_b32 s2, 1
	v_cndmask_b32_e64 v10, -v10, v11, vcc
	v_bitop3_b32 v1, v1, v10, s2 bitop3:0x6c
	s_movk_i32 s2, 0x1f8
	v_cmp_class_f32_e64 vcc, v5, s2
	v_lshl_or_b32 v0, v0, 6, v3
	s_nop 0
	v_cndmask_b32_e32 v10, v240, v1, vcc
	v_ashrrev_i32_e32 v1, 31, v0
	v_lshl_add_u64 v[0:1], v[0:1], 2, s[76:77]
	global_store_dword v[0:1], v10, off sc1
	s_and_saveexec_b64 s[36:37], s[14:15]
	s_xor_b64 s[14:15], exec, s[36:37]
	s_cbranch_execz .LBB0_356
	v_cmp_lt_u32_e64 s[36:37], 63, v8
	s_mov_b32 s2, 0xfe5163ab
	s_nop 0
	v_cndmask_b32_e64 v9, 0, v242, s[36:37]
	v_add_u32_e32 v8, v9, v8
	v_cmp_lt_u32_e64 s[38:39], 31, v8
	s_nop 1
	v_cndmask_b32_e64 v9, 0, v239, s[38:39]
	v_add_u32_e32 v8, v9, v8
	v_cmp_lt_u32_e64 s[40:41], 31, v8
	s_nop 1
	v_cndmask_b32_e64 v9, 0, v239, s[40:41]
	v_add_u32_e32 v22, v9, v8
	v_mad_u64_u32 v[8:9], s[42:43], v7, s2, 0
	v_mov_b32_e32 v96, v9
	s_mov_b32 s2, 0x3c439041
	v_mad_u64_u32 v[10:11], s[42:43], v7, s2, v[96:97]
	v_mov_b32_e32 v96, v11
	s_mov_b32 s2, 0xdb629599
	v_mad_u64_u32 v[12:13], s[42:43], v7, s2, v[96:97]
	v_mov_b32_e32 v96, v13
	s_mov_b32 s2, 0xf534ddc0
	v_mad_u64_u32 v[14:15], s[42:43], v7, s2, v[96:97]
	v_mov_b32_e32 v96, v15
	s_mov_b32 s2, 0xfc2757d1
	v_mad_u64_u32 v[16:17], s[42:43], v7, s2, v[96:97]
	v_mov_b32_e32 v96, v17
	s_mov_b32 s2, 0x4e441529
	v_mad_u64_u32 v[18:19], s[42:43], v7, s2, v[96:97]
	v_mov_b32_e32 v96, v19
	s_mov_b32 s2, 0xa2f9836e
	v_mad_u64_u32 v[20:21], s[42:43], v7, s2, v[96:97]
	v_cndmask_b32_e64 v9, v18, v14, s[36:37]
	v_cndmask_b32_e64 v7, v20, v16, s[36:37]
	v_cndmask_b32_e64 v13, v21, v18, s[36:37]
	v_cndmask_b32_e64 v11, v7, v9, s[38:39]
	v_cndmask_b32_e64 v7, v13, v7, s[38:39]
	v_cndmask_b32_e64 v13, v16, v12, s[36:37]
	v_cndmask_b32_e64 v9, v9, v13, s[38:39]
	v_cndmask_b32_e64 v10, v14, v10, s[36:37]
	v_cndmask_b32_e64 v7, v7, v11, s[40:41]
	v_cndmask_b32_e64 v11, v11, v9, s[40:41]
	v_sub_u32_e32 v15, 32, v22
	v_cndmask_b32_e64 v13, v13, v10, s[38:39]
	v_alignbit_b32 v16, v7, v11, v15
	v_cmp_eq_u32_e64 s[42:43], 0, v22
	v_cndmask_b32_e64 v9, v9, v13, s[40:41]
	v_cndmask_b32_e64 v8, v12, v8, s[36:37]
	v_cndmask_b32_e64 v7, v16, v7, s[42:43]
	v_alignbit_b32 v14, v11, v9, v15
	v_cndmask_b32_e64 v8, v10, v8, s[38:39]
	v_cndmask_b32_e64 v11, v14, v11, s[42:43]
	v_bfe_u32 v17, v7, 29, 1
	v_cndmask_b32_e64 v8, v13, v8, s[40:41]
	v_alignbit_b32 v14, v7, v11, 30
	v_sub_u32_e32 v18, 0, v17
	v_alignbit_b32 v10, v9, v8, v15
	v_xor_b32_e32 v14, v14, v18
	v_cndmask_b32_e64 v9, v10, v9, s[42:43]
	v_alignbit_b32 v10, v11, v9, 30
	v_ffbh_u32_e32 v11, v14
	v_min_u32_e32 v11, 32, v11
	v_alignbit_b32 v8, v9, v8, 30
	v_xor_b32_e32 v10, v10, v18
	v_sub_u32_e32 v12, 31, v11
	v_xor_b32_e32 v8, v8, v18
	v_alignbit_b32 v13, v14, v10, v12
	v_alignbit_b32 v8, v10, v8, v12
	v_alignbit_b32 v9, v13, v8, 9
	v_ffbh_u32_e32 v10, v9
	v_min_u32_e32 v10, 32, v10
	v_lshrrev_b32_e32 v16, 29, v7
	v_not_b32_e32 v12, v10
	v_alignbit_b32 v8, v9, v8, v12
	v_lshlrev_b32_e32 v9, 31, v16
	v_or_b32_e32 v12, 0x33000000, v9
	v_add_lshl_u32 v10, v10, v11, 23
	v_lshrrev_b32_e32 v8, 9, v8
	v_sub_u32_e32 v10, v12, v10
	v_or_b32_e32 v9, 0.5, v9
	v_lshlrev_b32_e32 v11, 23, v11
	v_or_b32_e32 v8, v10, v8
	v_lshrrev_b32_e32 v10, 9, v13
	v_sub_u32_e32 v9, v9, v11
	v_or_b32_e32 v9, v10, v9
	v_mul_f32_e32 v10, 0x3fc90fda, v9
	s_mov_b32 s2, 0x3fc90fda
	v_fma_f32 v11, v9, s2, -v10
	v_fmac_f32_e32 v11, 0x33a22168, v9
	v_fmac_f32_e32 v11, 0x3fc90fda, v8
	v_lshrrev_b32_e32 v7, 30, v7
	v_add_f32_e32 v11, v10, v11
	v_add_u32_e32 v10, v17, v7
